# RG-LRU scan: (hf+hb)*gelu(y) written out chunk by chunk inside the second half of the scan (old 16-pass flush removed)
# speedup vs baseline: 1.0430x; 1.0065x over previous
.LBB0_598:
	s_lshl_b32 s4, s84, 5
	s_and_b32 s68, s4, 32
	s_bfe_u32 s70, s84, 0x40001
	s_or_b32 s34, s68, s3
	s_lshl_b32 s67, s70, 6
	v_or_b32_e32 v164, s34, v3
	v_or_b32_e32 v4, s67, v164
	v_lshlrev_b32_e32 v128, 2, v4
	v_lshl_add_u64 v[134:135], s[90:91], 0, v[128:129]
	v_add_co_u32_e32 v4, vcc, s53, v134
	s_ashr_i32 s69, s84, 5
	s_nop 0
	v_addc_co_u32_e32 v5, vcc, 0, v135, vcc
	v_add_co_u32_e32 v6, vcc, s55, v134
	s_lshl_b32 s4, s69, 4
	s_nop 0
	v_addc_co_u32_e32 v7, vcc, 0, v135, vcc
	global_load_dword v8, v[4:5], off offset:576
	global_load_dword v9, v[6:7], off offset:576
	v_add_co_u32_e32 v4, vcc, s56, v134
	s_or_b32 s4, s4, s70
	s_nop 0
	v_addc_co_u32_e32 v5, vcc, 0, v135, vcc
	v_add_co_u32_e32 v6, vcc, s57, v134
	s_mul_i32 s28, s4, 0x804
	s_nop 0
	v_addc_co_u32_e32 v7, vcc, 0, v135, vcc
	global_load_dword v10, v[4:5], off offset:576
	s_nop 0
	global_load_dword v6, v[6:7], off offset:576
	v_add_co_u32_e32 v4, vcc, 0xd000, v134
	s_ashr_i32 s29, s28, 31
	s_nop 0
	v_addc_co_u32_e32 v5, vcc, 0, v135, vcc
	global_load_dword v133, v[4:5], off offset:576
	s_lshl_b64 s[28:29], s[28:29], 7
	s_add_u32 s50, s42, s28
	s_addc_u32 s51, s43, s29
	s_bitcmp1_b32 s84, 0
	s_cselect_b64 s[28:29], -1, 0
	s_mov_b64 s[26:27], -1
	s_lshl_b32 s71, s70, 10
	s_and_b64 vcc, exec, s[28:29]
	s_waitcnt vmcnt(4)
	v_bfe_u32 v4, v8, 16, 1
	v_add3_u32 v184, v8, v4, s54
	s_waitcnt vmcnt(3)
	v_bfe_u32 v5, v9, 16, 1
	v_add3_u32 v185, v9, v5, s54
	s_waitcnt vmcnt(2)
	v_bfe_u32 v4, v10, 16, 1
	v_add3_u32 v195, v10, v4, s54
	s_waitcnt vmcnt(1)
	v_bfe_u32 v4, v6, 16, 1
	v_add3_u32 v197, v6, v4, s54
	s_waitcnt vmcnt(0)
	s_cmpk_gt_u32 s85, 0xff
	s_cbranch_scc1 .Lrec2_bwd
	v_and_b32_e32 v252, 15, v157
	v_lshrrev_b32_e32 v253, 4, v157
	s_bfe_u32 s5, s85, 0x10006
	s_bfe_u32 s6, s85, 0x10007
	s_and_b32 s8, s84, 1
	v_readlane_b32 s26, v254, 13
	v_readlane_b32 s27, v254, 14
	s_nop 3
	s_lshl_b32 s9, s70, 2
	s_lshl_b32 s52, s9, 15
	s_add_u32 s26, s26, 0x100000
	s_addc_u32 s27, s27, 0
	s_add_u32 s26, s26, s52
	s_addc_u32 s27, s27, 0
	v_add_u32_e32 v8, s34, v252
	v_lshlrev_b32_e32 v9, 7, v8
	v_lshl_add_u32 v9, v253, 4, v9
	s_lshl_b32 s64, s8, 6
	s_xor_b32 s71, s64, 64
	v_add_u32_e32 v10, s64, v9
	v_add_u32_e32 v255, s71, v9
	s_add_u32 s38, s26, 0x0
	s_addc_u32 s39, s27, 0
	global_load_dwordx4 v[20:23], v10, s[38:39]
	global_load_dwordx4 v[24:27], v255, s[38:39]
	s_add_u32 s38, s26, 0x2000
	s_addc_u32 s39, s27, 0
	global_load_dwordx4 v[28:31], v10, s[38:39]
	global_load_dwordx4 v[32:35], v255, s[38:39]
	s_add_u32 s38, s26, 0x4000
	s_addc_u32 s39, s27, 0
	global_load_dwordx4 v[36:39], v10, s[38:39]
	global_load_dwordx4 v[40:43], v255, s[38:39]
	s_add_u32 s38, s26, 0x6000
	s_addc_u32 s39, s27, 0
	global_load_dwordx4 v[44:47], v10, s[38:39]
	global_load_dwordx4 v[48:51], v255, s[38:39]
	s_add_u32 s38, s26, 0x8000
	s_addc_u32 s39, s27, 0
	global_load_dwordx4 v[52:55], v10, s[38:39]
	global_load_dwordx4 v[56:59], v255, s[38:39]
	s_add_u32 s38, s26, 0xa000
	s_addc_u32 s39, s27, 0
	global_load_dwordx4 v[60:63], v10, s[38:39]
	global_load_dwordx4 v[64:67], v255, s[38:39]
	s_add_u32 s38, s26, 0xc000
	s_addc_u32 s39, s27, 0
	global_load_dwordx4 v[68:71], v10, s[38:39]
	global_load_dwordx4 v[72:75], v255, s[38:39]
	s_add_u32 s38, s26, 0xe000
	s_addc_u32 s39, s27, 0
	global_load_dwordx4 v[76:79], v10, s[38:39]
	global_load_dwordx4 v[80:83], v255, s[38:39]
	s_lshl_b32 s52, s9, 8
	s_add_i32 s52, s52, 0x15240
	v_lshlrev_b32_e32 v8, 2, v8
	v_add_u32_e32 v9, s52, v8
	global_load_dword v128, v9, s[90:91]
	global_load_dword v178, v9, s[90:91] offset:256
	s_lshl_b32 s52, s70, 8
	s_add_i32 s52, s52, 0x12240
	v_add_u32_e32 v9, s52, v8
	global_load_dword v179, v9, s[90:91]
	v_lshlrev_b32_e32 v198, 3, v253
	v_sub_u32_e32 v198, v252, v198
	v_lshl_add_u32 v198, s6, 4, v198
	v_cmp_gt_u32_e32 vcc, 8, v198
	v_and_b32_e32 v199, 1, v198
	v_lshlrev_b32_e32 v199, 4, v199
	v_lshrrev_b32_e32 v200, 1, v198
	s_nop 1
	v_cndmask_b32_e32 v200, 7, v200, vcc
	v_cmp_eq_u32_e64 s[58:59], 0, v200
	v_cmp_eq_u32_e64 s[60:61], 1, v200
	v_cmp_eq_u32_e64 s[98:99], 2, v200
	v_cmp_eq_u32_e64 s[100:101], 3, v200
	s_nop 1
	v_lshrrev_b32_e32 v201, 16, v184
	v_lshlrev_b32_e32 v201, v199, v201
	v_cndmask_b32_e64 v84, 0, v201, s[58:59]
	v_cndmask_b32_e64 v85, 0, v201, s[60:61]
	v_cndmask_b32_e64 v86, 0, v201, s[98:99]
	v_cndmask_b32_e64 v87, 0, v201, s[100:101]
	v_lshrrev_b32_e32 v201, 16, v185
	v_lshlrev_b32_e32 v201, v199, v201
	v_cndmask_b32_e64 v88, 0, v201, s[58:59]
	v_cndmask_b32_e64 v89, 0, v201, s[60:61]
	v_cndmask_b32_e64 v90, 0, v201, s[98:99]
	v_cndmask_b32_e64 v91, 0, v201, s[100:101]
	v_lshrrev_b32_e32 v201, 16, v195
	v_lshlrev_b32_e32 v201, v199, v201
	v_cndmask_b32_e64 v92, 0, v201, s[58:59]
	v_cndmask_b32_e64 v93, 0, v201, s[60:61]
	v_cndmask_b32_e64 v94, 0, v201, s[98:99]
	v_cndmask_b32_e64 v95, 0, v201, s[100:101]
	v_lshrrev_b32_e32 v201, 16, v197
	v_lshlrev_b32_e32 v201, v199, v201
	v_cndmask_b32_e64 v96, 0, v201, s[58:59]
	v_cndmask_b32_e64 v97, 0, v201, s[60:61]
	v_cndmask_b32_e64 v98, 0, v201, s[98:99]
	v_cndmask_b32_e64 v99, 0, v201, s[100:101]
	v_mov_b32_e32 v184, 1.0
	v_mov_b32_e32 v185, 1.0
	v_lshrrev_b32_e32 v8, 2, v252
	v_and_b32_e32 v9, 3, v252
	v_lshl_add_u32 v8, v8, 3, v9
	v_lshl_add_u32 v8, s5, 5, v8
	v_mul_u32_u24_e32 v8, 0x90, v8
	v_lshl_add_u32 v8, v253, 4, v8
	v_add_u32_e32 v8, 0x20900, v8
	v_add_u32_e32 v130, s64, v8
	v_add_u32_e32 v131, s71, v8
	v_and_b32_e32 v8, 0xff, v156
	v_lshrrev_b32_e32 v9, 3, v8
	v_mul_u32_u24_e32 v9, 0x90, v9
	v_and_b32_e32 v10, 7, v8
	v_lshl_add_u32 v9, v10, 4, v9
	v_add_u32_e32 v134, 0x20900, v9
	v_lshlrev_b32_e32 v154, 4, v8
	v_add_u32_e32 v155, 0x1000, v154
	v_min_u32_e32 v9, 23, v8
	v_add_u32_e32 v9, 0x200, v9
	v_lshlrev_b32_e32 v159, 4, v9
	v_lshrrev_b32_e32 v10, 3, v9
	v_mul_u32_u24_e32 v10, 0x90, v10
	v_and_b32_e32 v9, 7, v9
	v_lshl_add_u32 v10, v9, 4, v10
	v_add_u32_e32 v135, 0x20900, v10
	s_lshl_b32 s52, s6, 8
	s_add_i32 s52, s52, 0x20100
	v_lshl_add_u32 v183, v252, 3, s52
	s_lshl_b32 s52, s5, 7
	v_add_u32_e32 v182, s52, v183
	s_lshl_b32 s52, s5, 11
	s_lshl_b32 s9, s6, 5
	s_add_i32 s52, s52, s9
	s_add_i32 s52, s52, 0x100
	v_lshlrev_b32_e32 v8, 9, v253
	v_lshl_add_u32 v8, v252, 1, v8
	v_add_u32_e32 v184, s52, v8
	v_lshlrev_b32_e32 v185, 2, v252
	s_mul_i32 s52, s69, 0x600000
	s_add_u32 s60, s30, s52
	s_addc_u32 s61, s31, 0
	s_add_i32 s52, s68, s67
	s_lshl_b32 s52, s52, 1
	s_addk_i32 s52, 0x400
	s_add_u32 s60, s60, s52
	s_addc_u32 s61, s61, 0
	v_and_b32_e32 v8, 0xff, v156
	v_lshlrev_b32_e32 v195, 4, v8
	v_add_u32_e32 v195, 0x100, v195
	v_lshrrev_b32_e32 v9, 2, v8
	v_mul_u32_u24_e32 v9, 0xc00, v9
	v_and_b32_e32 v8, 3, v8
	v_lshl_add_u32 v255, v8, 4, v9
	v_cmp_eq_u32_e64 s[10:11], 0, v253
	v_cmp_lt_u32_e64 s[16:17], 0, v253
	v_cmp_lt_u32_e64 s[20:21], 1, v253
	v_cmp_lt_u32_e64 s[22:23], 2, v253
	s_cmp_lg_u32 s5, 0
	s_cselect_b64 s[24:25], -1, 0
	v_mov_b32_e32 v180, 0
	s_add_u32 s26, s50, 0x0
	s_addc_u32 s27, s51, 0
	global_load_dwordx4 v[230:233], v154, s[26:27]
	global_load_dwordx4 v[234:237], v155, s[26:27]
	global_load_dwordx4 v[238:241], v159, s[26:27]
	s_add_u32 s26, s50, 0x2000
	s_addc_u32 s27, s51, 0
	global_load_dwordx4 v[146:149], v154, s[26:27]
	global_load_dwordx4 v[150:153], v155, s[26:27]
	global_load_dwordx4 v[160:163], v159, s[26:27]
	s_waitcnt vmcnt(0)
	v_mov_b32_e32 v12, v128
	v_mov_b32_e32 v16, v178
	v_mov_b32_e32 v242, v133
	v_mov_b32_e32 v13, v128
	v_mov_b32_e32 v17, v178
	v_mov_b32_e32 v243, v133
	v_mov_b32_e32 v14, v128
	v_mov_b32_e32 v18, v178
	v_mov_b32_e32 v244, v133
	v_mov_b32_e32 v15, v128
	v_mov_b32_e32 v19, v178
	v_mov_b32_e32 v245, v133
	ds_write_b128 v134, v[230:233]
	ds_write_b128 v134, v[234:237] offset:4608
	ds_write_b128 v135, v[238:241]
	s_add_u32 s26, s50, 0x4000
	s_addc_u32 s27, s51, 0
	global_load_dwordx4 v[230:233], v154, s[26:27]
	global_load_dwordx4 v[234:237], v155, s[26:27]
	global_load_dwordx4 v[238:241], v159, s[26:27]
	s_mov_b32 s4, 0
	s_waitcnt lgkmcnt(0)
	s_barrier
.Lrec2_loopA_d0:
	ds_read_b128 v[198:201], v130 offset:0
	ds_read_b128 v[214:217], v130 offset:576
	ds_read_b128 v[202:205], v131 offset:0
	ds_read_b128 v[218:221], v131 offset:576
	ds_read_b128 v[206:209], v130 offset:144
	ds_read_b128 v[222:225], v130 offset:720
	ds_read_b128 v[210:213], v131 offset:144
	s_waitcnt lgkmcnt(14)
	ds_read_b128 v[226:229], v131 offset:720
	s_waitcnt lgkmcnt(6)
	v_mfma_f32_16x16x32_bf16 v[100:103], v[198:201], v[20:23], v[12:15]
	v_mfma_f32_16x16x32_bf16 v[104:107], v[198:201], v[52:55], v[16:19]
	v_mfma_f32_16x16x32_bf16 v[108:111], v[198:201], v[84:87], v[242:245]
	v_mfma_f32_16x16x32_bf16 v[112:115], v[214:217], v[20:23], v[12:15]
	v_mfma_f32_16x16x32_bf16 v[138:141], v[214:217], v[52:55], v[16:19]
	v_mfma_f32_16x16x32_bf16 v[142:145], v[214:217], v[84:87], v[242:245]
	s_waitcnt lgkmcnt(4)
	v_mfma_f32_16x16x32_bf16 v[100:103], v[202:205], v[24:27], v[100:103]
	v_mfma_f32_16x16x32_bf16 v[104:107], v[202:205], v[56:59], v[104:107]
	v_mfma_f32_16x16x32_bf16 v[112:115], v[218:221], v[24:27], v[112:115]
	v_mfma_f32_16x16x32_bf16 v[138:141], v[218:221], v[56:59], v[138:141]
	ds_read_b128 v[198:201], v130 offset:288
	ds_read_b128 v[214:217], v130 offset:864
	ds_read_b128 v[202:205], v131 offset:288
	ds_read_b128 v[218:221], v131 offset:864
	s_waitcnt lgkmcnt(6)
	v_mfma_f32_16x16x32_bf16 v[100:103], v[206:209], v[28:31], v[100:103]
	v_mfma_f32_16x16x32_bf16 v[104:107], v[206:209], v[60:63], v[104:107]
	v_mfma_f32_16x16x32_bf16 v[108:111], v[206:209], v[88:91], v[108:111]
	v_mfma_f32_16x16x32_bf16 v[112:115], v[222:225], v[28:31], v[112:115]
	v_mfma_f32_16x16x32_bf16 v[138:141], v[222:225], v[60:63], v[138:141]
	v_mfma_f32_16x16x32_bf16 v[142:145], v[222:225], v[88:91], v[142:145]
	s_waitcnt lgkmcnt(4)
	v_mfma_f32_16x16x32_bf16 v[100:103], v[210:213], v[32:35], v[100:103]
	v_mfma_f32_16x16x32_bf16 v[104:107], v[210:213], v[64:67], v[104:107]
	v_mfma_f32_16x16x32_bf16 v[112:115], v[226:229], v[32:35], v[112:115]
	v_mfma_f32_16x16x32_bf16 v[138:141], v[226:229], v[64:67], v[138:141]
	ds_read_b128 v[206:209], v130 offset:432
	ds_read_b128 v[222:225], v130 offset:1008
	ds_read_b128 v[210:213], v131 offset:432
	ds_read_b128 v[226:229], v131 offset:1008
	s_waitcnt lgkmcnt(6)
	v_mfma_f32_16x16x32_bf16 v[100:103], v[198:201], v[36:39], v[100:103]
	v_mfma_f32_16x16x32_bf16 v[104:107], v[198:201], v[68:71], v[104:107]
	v_mfma_f32_16x16x32_bf16 v[108:111], v[198:201], v[92:95], v[108:111]
	v_mfma_f32_16x16x32_bf16 v[112:115], v[214:217], v[36:39], v[112:115]
	v_mfma_f32_16x16x32_bf16 v[138:141], v[214:217], v[68:71], v[138:141]
	v_mfma_f32_16x16x32_bf16 v[142:145], v[214:217], v[92:95], v[142:145]
	s_waitcnt lgkmcnt(4)
	v_mfma_f32_16x16x32_bf16 v[100:103], v[202:205], v[40:43], v[100:103]
	v_mfma_f32_16x16x32_bf16 v[104:107], v[202:205], v[72:75], v[104:107]
	v_mfma_f32_16x16x32_bf16 v[112:115], v[218:221], v[40:43], v[112:115]
	v_mfma_f32_16x16x32_bf16 v[138:141], v[218:221], v[72:75], v[138:141]
	s_waitcnt lgkmcnt(2)
	v_mfma_f32_16x16x32_bf16 v[100:103], v[206:209], v[44:47], v[100:103]
	v_mfma_f32_16x16x32_bf16 v[104:107], v[206:209], v[76:79], v[104:107]
	v_mfma_f32_16x16x32_bf16 v[108:111], v[206:209], v[96:99], v[108:111]
	v_mfma_f32_16x16x32_bf16 v[112:115], v[222:225], v[44:47], v[112:115]
	v_mfma_f32_16x16x32_bf16 v[138:141], v[222:225], v[76:79], v[138:141]
	v_mfma_f32_16x16x32_bf16 v[142:145], v[222:225], v[96:99], v[142:145]
	s_waitcnt lgkmcnt(0)
	v_mfma_f32_16x16x32_bf16 v[100:103], v[210:213], v[48:51], v[100:103]
	v_mfma_f32_16x16x32_bf16 v[104:107], v[210:213], v[80:83], v[104:107]
	v_mfma_f32_16x16x32_bf16 v[112:115], v[226:229], v[48:51], v[112:115]
	v_mfma_f32_16x16x32_bf16 v[138:141], v[226:229], v[80:83], v[138:141]
	s_waitcnt lgkmcnt(0)
	s_barrier
	s_waitcnt vmcnt(3)
	ds_write_b128 v134, v[146:149]
	ds_write_b128 v134, v[150:153] offset:4608
	ds_write_b128 v135, v[160:163]
	s_add_i32 s52, s4, 3
	s_min_u32 s52, s52, 31
	s_lshl_b32 s52, s52, 13
	s_add_u32 s26, s50, s52
	s_addc_u32 s27, s51, 0
	global_load_dwordx4 v[146:149], v154, s[26:27]
	global_load_dwordx4 v[150:153], v155, s[26:27]
	global_load_dwordx4 v[160:163], v159, s[26:27]
	v_exp_f32_e32 v198, v100
	v_exp_f32_e32 v199, v101
	v_exp_f32_e32 v200, v102
	v_exp_f32_e32 v201, v103
	v_exp_f32_e32 v202, v112
	v_exp_f32_e32 v203, v113
	v_exp_f32_e32 v204, v114
	v_exp_f32_e32 v205, v115
	v_exp_f32_e32 v214, v104
	v_add_f32_e32 v198, 1.0, v198
	v_exp_f32_e32 v215, v105
	v_add_f32_e32 v199, 1.0, v199
	v_exp_f32_e32 v216, v106
	v_add_f32_e32 v200, 1.0, v200
	v_exp_f32_e32 v217, v107
	v_add_f32_e32 v201, 1.0, v201
	v_exp_f32_e32 v218, v138
	v_add_f32_e32 v202, 1.0, v202
	v_exp_f32_e32 v219, v139
	v_add_f32_e32 v203, 1.0, v203
	v_exp_f32_e32 v220, v140
	v_add_f32_e32 v204, 1.0, v204
	v_exp_f32_e32 v221, v141
	v_add_f32_e32 v205, 1.0, v205
	v_rcp_f32_e32 v198, v198
	v_add_f32_e32 v214, 1.0, v214
	v_rcp_f32_e32 v199, v199
	v_add_f32_e32 v215, 1.0, v215
	v_rcp_f32_e32 v200, v200
	v_add_f32_e32 v216, 1.0, v216
	v_rcp_f32_e32 v201, v201
	v_add_f32_e32 v217, 1.0, v217
	v_rcp_f32_e32 v202, v202
	v_add_f32_e32 v218, 1.0, v218
	v_rcp_f32_e32 v203, v203
	v_add_f32_e32 v219, 1.0, v219
	v_rcp_f32_e32 v204, v204
	v_add_f32_e32 v220, 1.0, v220
	v_rcp_f32_e32 v205, v205
	v_add_f32_e32 v221, 1.0, v221
	v_mul_f32_e32 v198, v179, v198
	v_mul_f32_e32 v199, v179, v199
	v_mul_f32_e32 v200, v179, v200
	v_mul_f32_e32 v201, v179, v201
	v_mul_f32_e32 v202, v179, v202
	v_mul_f32_e32 v203, v179, v203
	v_mul_f32_e32 v204, v179, v204
	v_mul_f32_e32 v205, v179, v205
	v_exp_f32_e32 v120, v198
	v_exp_f32_e32 v121, v199
	v_exp_f32_e32 v122, v200
	v_exp_f32_e32 v123, v201
	v_exp_f32_e32 v124, v202
	v_exp_f32_e32 v125, v203
	v_exp_f32_e32 v126, v204
	v_exp_f32_e32 v127, v205
	v_fma_f32 v206, -v120, v120, 1.0
	v_fma_f32 v207, -v121, v121, 1.0
	v_fma_f32 v208, -v122, v122, 1.0
	v_fma_f32 v209, -v123, v123, 1.0
	v_fma_f32 v210, -v124, v124, 1.0
	v_fma_f32 v211, -v125, v125, 1.0
	v_fma_f32 v212, -v126, v126, 1.0
	v_fma_f32 v213, -v127, v127, 1.0
	v_max_f32_e32 v206, 0xda24260, v206
	v_max_f32_e32 v207, 0xda24260, v207
	v_max_f32_e32 v208, 0xda24260, v208
	v_max_f32_e32 v209, 0xda24260, v209
	v_max_f32_e32 v210, 0xda24260, v210
	v_max_f32_e32 v211, 0xda24260, v211
	v_max_f32_e32 v212, 0xda24260, v212
	v_max_f32_e32 v213, 0xda24260, v213
	v_mul_f32_e32 v198, v214, v206
	v_mul_f32_e32 v199, v215, v207
	v_mul_f32_e32 v200, v216, v208
	v_mul_f32_e32 v201, v217, v209
	v_mul_f32_e32 v202, v218, v210
	v_mul_f32_e32 v203, v219, v211
	v_mul_f32_e32 v204, v220, v212
	v_mul_f32_e32 v205, v221, v213
	v_mul_f32_e32 v214, v214, v198
	v_mul_f32_e32 v215, v215, v199
	v_mul_f32_e32 v216, v216, v200
	v_mul_f32_e32 v217, v217, v201
	v_mul_f32_e32 v218, v218, v202
	v_mul_f32_e32 v219, v219, v203
	v_mul_f32_e32 v220, v220, v204
	v_mul_f32_e32 v221, v221, v205
	v_rsq_f32_e32 v214, v214
	v_mul_f32_e32 v222, v108, v206
	v_rsq_f32_e32 v215, v215
	v_mul_f32_e32 v223, v109, v207
	v_rsq_f32_e32 v216, v216
	v_mul_f32_e32 v224, v110, v208
	v_rsq_f32_e32 v217, v217
	v_mul_f32_e32 v225, v111, v209
	v_rsq_f32_e32 v218, v218
	v_mul_f32_e32 v226, v142, v210
	v_rsq_f32_e32 v219, v219
	v_mul_f32_e32 v227, v143, v211
	v_rsq_f32_e32 v220, v220
	v_mul_f32_e32 v228, v144, v212
	v_rsq_f32_e32 v221, v221
	v_mul_f32_e32 v229, v145, v213
	v_mul_f32_e32 v170, v222, v214
	v_mul_f32_e32 v171, v223, v215
	v_mul_f32_e32 v172, v224, v216
	v_mul_f32_e32 v173, v225, v217
	v_mul_f32_e32 v174, v226, v218
	v_mul_f32_e32 v175, v227, v219
	v_mul_f32_e32 v176, v228, v220
	v_mul_f32_e32 v177, v229, v221
	v_mov_b32_e32 v198, v170
	v_mov_b32_e32 v199, v120
	v_fma_f32 v198, v121, v198, v171
	v_mul_f32_e32 v199, v199, v121
	v_fma_f32 v198, v122, v198, v172
	v_mul_f32_e32 v199, v199, v122
	v_fma_f32 v198, v123, v198, v173
	v_mul_f32_e32 v199, v199, v123
	v_fma_f32 v198, v124, v198, v174
	v_mul_f32_e32 v199, v199, v124
	v_fma_f32 v198, v125, v198, v175
	v_mul_f32_e32 v199, v199, v125
	v_fma_f32 v198, v126, v198, v176
	v_mul_f32_e32 v199, v199, v126
	v_fma_f32 v198, v127, v198, v177
	v_mul_f32_e32 v199, v199, v127
	ds_bpermute_b32 v164, v185, v199 offset:0
	ds_bpermute_b32 v246, v185, v198 offset:0
	ds_bpermute_b32 v165, v185, v199 offset:64
	ds_bpermute_b32 v247, v185, v198 offset:64
	ds_bpermute_b32 v166, v185, v199 offset:128
	ds_bpermute_b32 v248, v185, v198 offset:128
	ds_bpermute_b32 v167, v185, v199 offset:192
	ds_bpermute_b32 v249, v185, v198 offset:192
	s_waitcnt lgkmcnt(0)
	v_mov_b32_e32 v251, v246
	v_mov_b32_e32 v250, v164
	v_fma_f32 v251, v251, v165, v247
	v_mul_f32_e32 v250, v250, v165
	v_fma_f32 v251, v251, v166, v248
	v_mul_f32_e32 v250, v250, v166
	v_fma_f32 v251, v251, v167, v249
	v_mul_f32_e32 v250, v250, v167
	s_mov_b64 exec, s[10:11]
	ds_write_b64 v182, v[250:251] offset:0
	s_mov_b64 exec, -1
	s_waitcnt lgkmcnt(0)
	s_barrier
	ds_read2_b64 v[4:7], v183 offset0:0 offset1:16
	s_add_i32 s52, s4, 0
	s_lshl_b32 s52, s52, 12
	v_add_u32_e32 v197, s52, v184
	s_waitcnt lgkmcnt(0)
	v_fma_f32 v198, v180, v4, v5
	v_cndmask_b32_e64 v199, v180, v198, s[24:25]
	v_fma_f32 v180, v198, v6, v7
	v_fma_f32 v200, v199, v164, v246
	v_cndmask_b32_e64 v199, v199, v200, s[16:17]
	v_fma_f32 v200, v199, v165, v247
	v_cndmask_b32_e64 v199, v199, v200, s[20:21]
	v_fma_f32 v200, v199, v166, v248
	v_cndmask_b32_e64 v199, v199, v200, s[22:23]
	v_fma_f32 v214, v120, v199, v170
	v_fma_f32 v215, v121, v214, v171
	v_fma_f32 v216, v122, v215, v172
	v_fma_f32 v217, v123, v216, v173
	v_fma_f32 v218, v124, v217, v174
	v_fma_f32 v219, v125, v218, v175
	v_fma_f32 v220, v126, v219, v176
	v_fma_f32 v221, v127, v220, v177
	v_cvt_pk_bf16_f32 v206, v214, v215
	v_cvt_pk_bf16_f32 v208, v216, v217
	v_cvt_pk_bf16_f32 v210, v218, v219
	v_cvt_pk_bf16_f32 v212, v220, v221
	ds_write_b16 v197, v206 offset:0
	ds_write_b16_d16_hi v197, v206 offset:64
	ds_write_b16 v197, v208 offset:128
	ds_write_b16_d16_hi v197, v208 offset:192
	ds_write_b16 v197, v210 offset:256
	ds_write_b16_d16_hi v197, v210 offset:320
	ds_write_b16 v197, v212 offset:384
	ds_write_b16_d16_hi v197, v212 offset:448
	ds_read_b128 v[198:201], v130 offset:0
	ds_read_b128 v[214:217], v130 offset:576
	ds_read_b128 v[202:205], v131 offset:0
	ds_read_b128 v[218:221], v131 offset:576
	ds_read_b128 v[206:209], v130 offset:144
	ds_read_b128 v[222:225], v130 offset:720
	ds_read_b128 v[210:213], v131 offset:144
	s_waitcnt lgkmcnt(14)
	ds_read_b128 v[226:229], v131 offset:720
	s_waitcnt lgkmcnt(6)
	v_mfma_f32_16x16x32_bf16 v[100:103], v[198:201], v[20:23], v[12:15]
	v_mfma_f32_16x16x32_bf16 v[104:107], v[198:201], v[52:55], v[16:19]
	v_mfma_f32_16x16x32_bf16 v[108:111], v[198:201], v[84:87], v[242:245]
	v_mfma_f32_16x16x32_bf16 v[112:115], v[214:217], v[20:23], v[12:15]
	v_mfma_f32_16x16x32_bf16 v[138:141], v[214:217], v[52:55], v[16:19]
	v_mfma_f32_16x16x32_bf16 v[142:145], v[214:217], v[84:87], v[242:245]
	s_waitcnt lgkmcnt(4)
	v_mfma_f32_16x16x32_bf16 v[100:103], v[202:205], v[24:27], v[100:103]
	v_mfma_f32_16x16x32_bf16 v[104:107], v[202:205], v[56:59], v[104:107]
	v_mfma_f32_16x16x32_bf16 v[112:115], v[218:221], v[24:27], v[112:115]
	v_mfma_f32_16x16x32_bf16 v[138:141], v[218:221], v[56:59], v[138:141]
	ds_read_b128 v[198:201], v130 offset:288
	ds_read_b128 v[214:217], v130 offset:864
	ds_read_b128 v[202:205], v131 offset:288
	ds_read_b128 v[218:221], v131 offset:864
	s_waitcnt lgkmcnt(6)
	v_mfma_f32_16x16x32_bf16 v[100:103], v[206:209], v[28:31], v[100:103]
	v_mfma_f32_16x16x32_bf16 v[104:107], v[206:209], v[60:63], v[104:107]
	v_mfma_f32_16x16x32_bf16 v[108:111], v[206:209], v[88:91], v[108:111]
	v_mfma_f32_16x16x32_bf16 v[112:115], v[222:225], v[28:31], v[112:115]
	v_mfma_f32_16x16x32_bf16 v[138:141], v[222:225], v[60:63], v[138:141]
	v_mfma_f32_16x16x32_bf16 v[142:145], v[222:225], v[88:91], v[142:145]
	s_waitcnt lgkmcnt(4)
	v_mfma_f32_16x16x32_bf16 v[100:103], v[210:213], v[32:35], v[100:103]
	v_mfma_f32_16x16x32_bf16 v[104:107], v[210:213], v[64:67], v[104:107]
	v_mfma_f32_16x16x32_bf16 v[112:115], v[226:229], v[32:35], v[112:115]
	v_mfma_f32_16x16x32_bf16 v[138:141], v[226:229], v[64:67], v[138:141]
	ds_read_b128 v[206:209], v130 offset:432
	ds_read_b128 v[222:225], v130 offset:1008
	ds_read_b128 v[210:213], v131 offset:432
	ds_read_b128 v[226:229], v131 offset:1008
	s_waitcnt lgkmcnt(6)
	v_mfma_f32_16x16x32_bf16 v[100:103], v[198:201], v[36:39], v[100:103]
	v_mfma_f32_16x16x32_bf16 v[104:107], v[198:201], v[68:71], v[104:107]
	v_mfma_f32_16x16x32_bf16 v[108:111], v[198:201], v[92:95], v[108:111]
	v_mfma_f32_16x16x32_bf16 v[112:115], v[214:217], v[36:39], v[112:115]
	v_mfma_f32_16x16x32_bf16 v[138:141], v[214:217], v[68:71], v[138:141]
	v_mfma_f32_16x16x32_bf16 v[142:145], v[214:217], v[92:95], v[142:145]
	s_waitcnt lgkmcnt(4)
	v_mfma_f32_16x16x32_bf16 v[100:103], v[202:205], v[40:43], v[100:103]
	v_mfma_f32_16x16x32_bf16 v[104:107], v[202:205], v[72:75], v[104:107]
	v_mfma_f32_16x16x32_bf16 v[112:115], v[218:221], v[40:43], v[112:115]
	v_mfma_f32_16x16x32_bf16 v[138:141], v[218:221], v[72:75], v[138:141]
	s_waitcnt lgkmcnt(2)
	v_mfma_f32_16x16x32_bf16 v[100:103], v[206:209], v[44:47], v[100:103]
	v_mfma_f32_16x16x32_bf16 v[104:107], v[206:209], v[76:79], v[104:107]
	v_mfma_f32_16x16x32_bf16 v[108:111], v[206:209], v[96:99], v[108:111]
	v_mfma_f32_16x16x32_bf16 v[112:115], v[222:225], v[44:47], v[112:115]
	v_mfma_f32_16x16x32_bf16 v[138:141], v[222:225], v[76:79], v[138:141]
	v_mfma_f32_16x16x32_bf16 v[142:145], v[222:225], v[96:99], v[142:145]
	s_waitcnt lgkmcnt(0)
	v_mfma_f32_16x16x32_bf16 v[100:103], v[210:213], v[48:51], v[100:103]
	v_mfma_f32_16x16x32_bf16 v[104:107], v[210:213], v[80:83], v[104:107]
	v_mfma_f32_16x16x32_bf16 v[112:115], v[226:229], v[48:51], v[112:115]
	v_mfma_f32_16x16x32_bf16 v[138:141], v[226:229], v[80:83], v[138:141]
	s_waitcnt lgkmcnt(0)
	s_barrier
	s_waitcnt vmcnt(3)
	ds_write_b128 v134, v[230:233]
	ds_write_b128 v134, v[234:237] offset:4608
	ds_write_b128 v135, v[238:241]
	s_add_i32 s52, s4, 4
	s_min_u32 s52, s52, 31
	s_lshl_b32 s52, s52, 13
	s_add_u32 s26, s50, s52
	s_addc_u32 s27, s51, 0
	global_load_dwordx4 v[230:233], v154, s[26:27]
	global_load_dwordx4 v[234:237], v155, s[26:27]
	global_load_dwordx4 v[238:241], v159, s[26:27]
	v_exp_f32_e32 v198, v100
	v_exp_f32_e32 v199, v101
	v_exp_f32_e32 v200, v102
	v_exp_f32_e32 v201, v103
	v_exp_f32_e32 v202, v112
	v_exp_f32_e32 v203, v113
	v_exp_f32_e32 v204, v114
	v_exp_f32_e32 v205, v115
	v_exp_f32_e32 v214, v104
	v_add_f32_e32 v198, 1.0, v198
	v_exp_f32_e32 v215, v105
	v_add_f32_e32 v199, 1.0, v199
	v_exp_f32_e32 v216, v106
	v_add_f32_e32 v200, 1.0, v200
	v_exp_f32_e32 v217, v107
	v_add_f32_e32 v201, 1.0, v201
	v_exp_f32_e32 v218, v138
	v_add_f32_e32 v202, 1.0, v202
	v_exp_f32_e32 v219, v139
	v_add_f32_e32 v203, 1.0, v203
	v_exp_f32_e32 v220, v140
	v_add_f32_e32 v204, 1.0, v204
	v_exp_f32_e32 v221, v141
	v_add_f32_e32 v205, 1.0, v205
	v_rcp_f32_e32 v198, v198
	v_add_f32_e32 v214, 1.0, v214
	v_rcp_f32_e32 v199, v199
	v_add_f32_e32 v215, 1.0, v215
	v_rcp_f32_e32 v200, v200
	v_add_f32_e32 v216, 1.0, v216
	v_rcp_f32_e32 v201, v201
	v_add_f32_e32 v217, 1.0, v217
	v_rcp_f32_e32 v202, v202
	v_add_f32_e32 v218, 1.0, v218
	v_rcp_f32_e32 v203, v203
	v_add_f32_e32 v219, 1.0, v219
	v_rcp_f32_e32 v204, v204
	v_add_f32_e32 v220, 1.0, v220
	v_rcp_f32_e32 v205, v205
	v_add_f32_e32 v221, 1.0, v221
	v_mul_f32_e32 v198, v179, v198
	v_mul_f32_e32 v199, v179, v199
	v_mul_f32_e32 v200, v179, v200
	v_mul_f32_e32 v201, v179, v201
	v_mul_f32_e32 v202, v179, v202
	v_mul_f32_e32 v203, v179, v203
	v_mul_f32_e32 v204, v179, v204
	v_mul_f32_e32 v205, v179, v205
	v_exp_f32_e32 v120, v198
	v_exp_f32_e32 v121, v199
	v_exp_f32_e32 v122, v200
	v_exp_f32_e32 v123, v201
	v_exp_f32_e32 v124, v202
	v_exp_f32_e32 v125, v203
	v_exp_f32_e32 v126, v204
	v_exp_f32_e32 v127, v205
	v_fma_f32 v206, -v120, v120, 1.0
	v_fma_f32 v207, -v121, v121, 1.0
	v_fma_f32 v208, -v122, v122, 1.0
	v_fma_f32 v209, -v123, v123, 1.0
	v_fma_f32 v210, -v124, v124, 1.0
	v_fma_f32 v211, -v125, v125, 1.0
	v_fma_f32 v212, -v126, v126, 1.0
	v_fma_f32 v213, -v127, v127, 1.0
	v_max_f32_e32 v206, 0xda24260, v206
	v_max_f32_e32 v207, 0xda24260, v207
	v_max_f32_e32 v208, 0xda24260, v208
	v_max_f32_e32 v209, 0xda24260, v209
	v_max_f32_e32 v210, 0xda24260, v210
	v_max_f32_e32 v211, 0xda24260, v211
	v_max_f32_e32 v212, 0xda24260, v212
	v_max_f32_e32 v213, 0xda24260, v213
	v_mul_f32_e32 v198, v214, v206
	v_mul_f32_e32 v199, v215, v207
	v_mul_f32_e32 v200, v216, v208
	v_mul_f32_e32 v201, v217, v209
	v_mul_f32_e32 v202, v218, v210
	v_mul_f32_e32 v203, v219, v211
	v_mul_f32_e32 v204, v220, v212
	v_mul_f32_e32 v205, v221, v213
	v_mul_f32_e32 v214, v214, v198
	v_mul_f32_e32 v215, v215, v199
	v_mul_f32_e32 v216, v216, v200
	v_mul_f32_e32 v217, v217, v201
	v_mul_f32_e32 v218, v218, v202
	v_mul_f32_e32 v219, v219, v203
	v_mul_f32_e32 v220, v220, v204
	v_mul_f32_e32 v221, v221, v205
	v_rsq_f32_e32 v214, v214
	v_mul_f32_e32 v222, v108, v206
	v_rsq_f32_e32 v215, v215
	v_mul_f32_e32 v223, v109, v207
	v_rsq_f32_e32 v216, v216
	v_mul_f32_e32 v224, v110, v208
	v_rsq_f32_e32 v217, v217
	v_mul_f32_e32 v225, v111, v209
	v_rsq_f32_e32 v218, v218
	v_mul_f32_e32 v226, v142, v210
	v_rsq_f32_e32 v219, v219
	v_mul_f32_e32 v227, v143, v211
	v_rsq_f32_e32 v220, v220
	v_mul_f32_e32 v228, v144, v212
	v_rsq_f32_e32 v221, v221
	v_mul_f32_e32 v229, v145, v213
	v_mul_f32_e32 v170, v222, v214
	v_mul_f32_e32 v171, v223, v215
	v_mul_f32_e32 v172, v224, v216
	v_mul_f32_e32 v173, v225, v217
	v_mul_f32_e32 v174, v226, v218
	v_mul_f32_e32 v175, v227, v219
	v_mul_f32_e32 v176, v228, v220
	v_mul_f32_e32 v177, v229, v221
	v_mov_b32_e32 v198, v170
	v_mov_b32_e32 v199, v120
	v_fma_f32 v198, v121, v198, v171
	v_mul_f32_e32 v199, v199, v121
	v_fma_f32 v198, v122, v198, v172
	v_mul_f32_e32 v199, v199, v122
	v_fma_f32 v198, v123, v198, v173
	v_mul_f32_e32 v199, v199, v123
	v_fma_f32 v198, v124, v198, v174
	v_mul_f32_e32 v199, v199, v124
	v_fma_f32 v198, v125, v198, v175
	v_mul_f32_e32 v199, v199, v125
	v_fma_f32 v198, v126, v198, v176
	v_mul_f32_e32 v199, v199, v126
	v_fma_f32 v198, v127, v198, v177
	v_mul_f32_e32 v199, v199, v127
	ds_bpermute_b32 v164, v185, v199 offset:0
	ds_bpermute_b32 v246, v185, v198 offset:0
	ds_bpermute_b32 v165, v185, v199 offset:64
	ds_bpermute_b32 v247, v185, v198 offset:64
	ds_bpermute_b32 v166, v185, v199 offset:128
	ds_bpermute_b32 v248, v185, v198 offset:128
	ds_bpermute_b32 v167, v185, v199 offset:192
	ds_bpermute_b32 v249, v185, v198 offset:192
	s_waitcnt lgkmcnt(0)
	v_mov_b32_e32 v251, v246
	v_mov_b32_e32 v250, v164
	v_fma_f32 v251, v251, v165, v247
	v_mul_f32_e32 v250, v250, v165
	v_fma_f32 v251, v251, v166, v248
	v_mul_f32_e32 v250, v250, v166
	v_fma_f32 v251, v251, v167, v249
	v_mul_f32_e32 v250, v250, v167
	s_mov_b64 exec, s[10:11]
	ds_write_b64 v182, v[250:251] offset:1024
	s_mov_b64 exec, -1
	s_waitcnt lgkmcnt(0)
	s_barrier
	ds_read2_b64 v[4:7], v183 offset0:128 offset1:144
	s_add_i32 s52, s4, 1
	s_lshl_b32 s52, s52, 12
	v_add_u32_e32 v197, s52, v184
	s_waitcnt lgkmcnt(0)
	v_fma_f32 v198, v180, v4, v5
	v_cndmask_b32_e64 v199, v180, v198, s[24:25]
	v_fma_f32 v180, v198, v6, v7
	v_fma_f32 v200, v199, v164, v246
	v_cndmask_b32_e64 v199, v199, v200, s[16:17]
	v_fma_f32 v200, v199, v165, v247
	v_cndmask_b32_e64 v199, v199, v200, s[20:21]
	v_fma_f32 v200, v199, v166, v248
	v_cndmask_b32_e64 v199, v199, v200, s[22:23]
	v_fma_f32 v214, v120, v199, v170
	v_fma_f32 v215, v121, v214, v171
	v_fma_f32 v216, v122, v215, v172
	v_fma_f32 v217, v123, v216, v173
	v_fma_f32 v218, v124, v217, v174
	v_fma_f32 v219, v125, v218, v175
	v_fma_f32 v220, v126, v219, v176
	v_fma_f32 v221, v127, v220, v177
	v_cvt_pk_bf16_f32 v206, v214, v215
	v_cvt_pk_bf16_f32 v208, v216, v217
	v_cvt_pk_bf16_f32 v210, v218, v219
	v_cvt_pk_bf16_f32 v212, v220, v221
	ds_write_b16 v197, v206 offset:0
	ds_write_b16_d16_hi v197, v206 offset:64
	ds_write_b16 v197, v208 offset:128
	ds_write_b16_d16_hi v197, v208 offset:192
	ds_write_b16 v197, v210 offset:256
	ds_write_b16_d16_hi v197, v210 offset:320
	ds_write_b16 v197, v212 offset:384
	ds_write_b16_d16_hi v197, v212 offset:448
	s_add_i32 s4, s4, 2
	s_cmp_lt_u32 s4, 16
	s_cbranch_scc1 .Lrec2_loopA_d0
	ds_read_b128 v[198:201], v130 offset:0
	ds_read_b128 v[214:217], v130 offset:576
	ds_read_b128 v[202:205], v131 offset:0
	ds_read_b128 v[218:221], v131 offset:576
	ds_read_b128 v[206:209], v130 offset:144
	ds_read_b128 v[222:225], v130 offset:720
	ds_read_b128 v[210:213], v131 offset:144
	s_waitcnt lgkmcnt(14)
	ds_read_b128 v[226:229], v131 offset:720
	s_waitcnt lgkmcnt(6)
	v_mfma_f32_16x16x32_bf16 v[100:103], v[198:201], v[20:23], v[12:15]
	v_mfma_f32_16x16x32_bf16 v[104:107], v[198:201], v[52:55], v[16:19]
	v_mfma_f32_16x16x32_bf16 v[108:111], v[198:201], v[84:87], v[242:245]
	v_mfma_f32_16x16x32_bf16 v[112:115], v[214:217], v[20:23], v[12:15]
	v_mfma_f32_16x16x32_bf16 v[138:141], v[214:217], v[52:55], v[16:19]
	v_mfma_f32_16x16x32_bf16 v[142:145], v[214:217], v[84:87], v[242:245]
	s_waitcnt lgkmcnt(4)
	v_mfma_f32_16x16x32_bf16 v[100:103], v[202:205], v[24:27], v[100:103]
	v_mfma_f32_16x16x32_bf16 v[104:107], v[202:205], v[56:59], v[104:107]
	v_mfma_f32_16x16x32_bf16 v[112:115], v[218:221], v[24:27], v[112:115]
	v_mfma_f32_16x16x32_bf16 v[138:141], v[218:221], v[56:59], v[138:141]
	ds_read_b128 v[198:201], v130 offset:288
	ds_read_b128 v[214:217], v130 offset:864
	ds_read_b128 v[202:205], v131 offset:288
	ds_read_b128 v[218:221], v131 offset:864
	s_waitcnt lgkmcnt(6)
	v_mfma_f32_16x16x32_bf16 v[100:103], v[206:209], v[28:31], v[100:103]
	v_mfma_f32_16x16x32_bf16 v[104:107], v[206:209], v[60:63], v[104:107]
	v_mfma_f32_16x16x32_bf16 v[108:111], v[206:209], v[88:91], v[108:111]
	v_mfma_f32_16x16x32_bf16 v[112:115], v[222:225], v[28:31], v[112:115]
	v_mfma_f32_16x16x32_bf16 v[138:141], v[222:225], v[60:63], v[138:141]
	v_mfma_f32_16x16x32_bf16 v[142:145], v[222:225], v[88:91], v[142:145]
	s_waitcnt lgkmcnt(4)
	v_mfma_f32_16x16x32_bf16 v[100:103], v[210:213], v[32:35], v[100:103]
	v_mfma_f32_16x16x32_bf16 v[104:107], v[210:213], v[64:67], v[104:107]
	v_mfma_f32_16x16x32_bf16 v[112:115], v[226:229], v[32:35], v[112:115]
	v_mfma_f32_16x16x32_bf16 v[138:141], v[226:229], v[64:67], v[138:141]
	ds_read_b128 v[206:209], v130 offset:432
	ds_read_b128 v[222:225], v130 offset:1008
	ds_read_b128 v[210:213], v131 offset:432
	ds_read_b128 v[226:229], v131 offset:1008
	s_waitcnt lgkmcnt(6)
	v_mfma_f32_16x16x32_bf16 v[100:103], v[198:201], v[36:39], v[100:103]
	v_mfma_f32_16x16x32_bf16 v[104:107], v[198:201], v[68:71], v[104:107]
	v_mfma_f32_16x16x32_bf16 v[108:111], v[198:201], v[92:95], v[108:111]
	v_mfma_f32_16x16x32_bf16 v[112:115], v[214:217], v[36:39], v[112:115]
	v_mfma_f32_16x16x32_bf16 v[138:141], v[214:217], v[68:71], v[138:141]
	v_mfma_f32_16x16x32_bf16 v[142:145], v[214:217], v[92:95], v[142:145]
	s_waitcnt lgkmcnt(4)
	v_mfma_f32_16x16x32_bf16 v[100:103], v[202:205], v[40:43], v[100:103]
	v_mfma_f32_16x16x32_bf16 v[104:107], v[202:205], v[72:75], v[104:107]
	v_mfma_f32_16x16x32_bf16 v[112:115], v[218:221], v[40:43], v[112:115]
	v_mfma_f32_16x16x32_bf16 v[138:141], v[218:221], v[72:75], v[138:141]
	s_waitcnt lgkmcnt(2)
	v_mfma_f32_16x16x32_bf16 v[100:103], v[206:209], v[44:47], v[100:103]
	v_mfma_f32_16x16x32_bf16 v[104:107], v[206:209], v[76:79], v[104:107]
	v_mfma_f32_16x16x32_bf16 v[108:111], v[206:209], v[96:99], v[108:111]
	v_mfma_f32_16x16x32_bf16 v[112:115], v[222:225], v[44:47], v[112:115]
	v_mfma_f32_16x16x32_bf16 v[138:141], v[222:225], v[76:79], v[138:141]
	v_mfma_f32_16x16x32_bf16 v[142:145], v[222:225], v[96:99], v[142:145]
	s_waitcnt lgkmcnt(0)
	v_mfma_f32_16x16x32_bf16 v[100:103], v[210:213], v[48:51], v[100:103]
	v_mfma_f32_16x16x32_bf16 v[104:107], v[210:213], v[80:83], v[104:107]
	v_mfma_f32_16x16x32_bf16 v[112:115], v[226:229], v[48:51], v[112:115]
	v_mfma_f32_16x16x32_bf16 v[138:141], v[226:229], v[80:83], v[138:141]
	s_waitcnt lgkmcnt(0)
	s_barrier
	s_waitcnt vmcnt(3)
	ds_write_b128 v134, v[146:149]
	ds_write_b128 v134, v[150:153] offset:4608
	ds_write_b128 v135, v[160:163]
	s_add_i32 s64, s4, 0
	s_mul_i32 s71, s64, 0x30000
	s_add_u32 s38, s60, s71
	s_addc_u32 s39, s61, 0
	s_lshl_b32 s64, s64, 12
	global_load_dwordx4 v[8:11], v255, s[38:39]
	s_add_i32 s52, s4, 3
	s_min_u32 s52, s52, 31
	s_lshl_b32 s52, s52, 13
	s_add_u32 s26, s50, s52
	s_addc_u32 s27, s51, 0
	global_load_dwordx4 v[146:149], v154, s[26:27]
	global_load_dwordx4 v[150:153], v155, s[26:27]
	global_load_dwordx4 v[160:163], v159, s[26:27]
	v_exp_f32_e32 v198, v100
	v_exp_f32_e32 v199, v101
	v_exp_f32_e32 v200, v102
	v_exp_f32_e32 v201, v103
	v_exp_f32_e32 v202, v112
	v_exp_f32_e32 v203, v113
	v_exp_f32_e32 v204, v114
	v_exp_f32_e32 v205, v115
	v_exp_f32_e32 v214, v104
	v_add_f32_e32 v198, 1.0, v198
	v_exp_f32_e32 v215, v105
	v_add_f32_e32 v199, 1.0, v199
	v_exp_f32_e32 v216, v106
	v_add_f32_e32 v200, 1.0, v200
	v_exp_f32_e32 v217, v107
	v_add_f32_e32 v201, 1.0, v201
	v_exp_f32_e32 v218, v138
	v_add_f32_e32 v202, 1.0, v202
	v_exp_f32_e32 v219, v139
	v_add_f32_e32 v203, 1.0, v203
	v_exp_f32_e32 v220, v140
	v_add_f32_e32 v204, 1.0, v204
	v_exp_f32_e32 v221, v141
	v_add_f32_e32 v205, 1.0, v205
	v_rcp_f32_e32 v198, v198
	v_add_f32_e32 v214, 1.0, v214
	v_rcp_f32_e32 v199, v199
	v_add_f32_e32 v215, 1.0, v215
	v_rcp_f32_e32 v200, v200
	v_add_f32_e32 v216, 1.0, v216
	v_rcp_f32_e32 v201, v201
	v_add_f32_e32 v217, 1.0, v217
	v_rcp_f32_e32 v202, v202
	v_add_f32_e32 v218, 1.0, v218
	v_rcp_f32_e32 v203, v203
	v_add_f32_e32 v219, 1.0, v219
	v_rcp_f32_e32 v204, v204
	v_add_f32_e32 v220, 1.0, v220
	v_rcp_f32_e32 v205, v205
	v_add_f32_e32 v221, 1.0, v221
	v_mul_f32_e32 v198, v179, v198
	v_mul_f32_e32 v199, v179, v199
	v_mul_f32_e32 v200, v179, v200
	v_mul_f32_e32 v201, v179, v201
	v_mul_f32_e32 v202, v179, v202
	v_mul_f32_e32 v203, v179, v203
	v_mul_f32_e32 v204, v179, v204
	v_mul_f32_e32 v205, v179, v205
	v_exp_f32_e32 v120, v198
	v_exp_f32_e32 v121, v199
	v_exp_f32_e32 v122, v200
	v_exp_f32_e32 v123, v201
	v_exp_f32_e32 v124, v202
	v_exp_f32_e32 v125, v203
	v_exp_f32_e32 v126, v204
	v_exp_f32_e32 v127, v205
	v_fma_f32 v206, -v120, v120, 1.0
	v_fma_f32 v207, -v121, v121, 1.0
	v_fma_f32 v208, -v122, v122, 1.0
	v_fma_f32 v209, -v123, v123, 1.0
	v_fma_f32 v210, -v124, v124, 1.0
	v_fma_f32 v211, -v125, v125, 1.0
	v_fma_f32 v212, -v126, v126, 1.0
	v_fma_f32 v213, -v127, v127, 1.0
	v_max_f32_e32 v206, 0xda24260, v206
	v_max_f32_e32 v207, 0xda24260, v207
	v_max_f32_e32 v208, 0xda24260, v208
	v_max_f32_e32 v209, 0xda24260, v209
	v_max_f32_e32 v210, 0xda24260, v210
	v_max_f32_e32 v211, 0xda24260, v211
	v_max_f32_e32 v212, 0xda24260, v212
	v_max_f32_e32 v213, 0xda24260, v213
	v_mul_f32_e32 v198, v214, v206
	v_mul_f32_e32 v199, v215, v207
	v_mul_f32_e32 v200, v216, v208
	v_mul_f32_e32 v201, v217, v209
	v_mul_f32_e32 v202, v218, v210
	v_mul_f32_e32 v203, v219, v211
	v_mul_f32_e32 v204, v220, v212
	v_mul_f32_e32 v205, v221, v213
	v_mul_f32_e32 v214, v214, v198
	v_mul_f32_e32 v215, v215, v199
	v_mul_f32_e32 v216, v216, v200
	v_mul_f32_e32 v217, v217, v201
	v_mul_f32_e32 v218, v218, v202
	v_mul_f32_e32 v219, v219, v203
	v_mul_f32_e32 v220, v220, v204
	v_mul_f32_e32 v221, v221, v205
	v_rsq_f32_e32 v214, v214
	v_mul_f32_e32 v222, v108, v206
	v_rsq_f32_e32 v215, v215
	v_mul_f32_e32 v223, v109, v207
	v_rsq_f32_e32 v216, v216
	v_mul_f32_e32 v224, v110, v208
	v_rsq_f32_e32 v217, v217
	v_mul_f32_e32 v225, v111, v209
	v_rsq_f32_e32 v218, v218
	v_mul_f32_e32 v226, v142, v210
	v_rsq_f32_e32 v219, v219
	v_mul_f32_e32 v227, v143, v211
	v_rsq_f32_e32 v220, v220
	v_mul_f32_e32 v228, v144, v212
	v_rsq_f32_e32 v221, v221
	v_mul_f32_e32 v229, v145, v213
	v_mul_f32_e32 v170, v222, v214
	v_mul_f32_e32 v171, v223, v215
	v_mul_f32_e32 v172, v224, v216
	v_mul_f32_e32 v173, v225, v217
	v_mul_f32_e32 v174, v226, v218
	v_mul_f32_e32 v175, v227, v219
	v_mul_f32_e32 v176, v228, v220
	v_mul_f32_e32 v177, v229, v221
	v_mov_b32_e32 v198, v170
	v_mov_b32_e32 v199, v120
	v_fma_f32 v198, v121, v198, v171
	v_mul_f32_e32 v199, v199, v121
	v_fma_f32 v198, v122, v198, v172
	v_mul_f32_e32 v199, v199, v122
	v_fma_f32 v198, v123, v198, v173
	v_mul_f32_e32 v199, v199, v123
	v_fma_f32 v198, v124, v198, v174
	v_mul_f32_e32 v199, v199, v124
	v_fma_f32 v198, v125, v198, v175
	v_mul_f32_e32 v199, v199, v125
	v_fma_f32 v198, v126, v198, v176
	v_mul_f32_e32 v199, v199, v126
	v_fma_f32 v198, v127, v198, v177
	v_mul_f32_e32 v199, v199, v127
	ds_bpermute_b32 v164, v185, v199 offset:0
	ds_bpermute_b32 v246, v185, v198 offset:0
	ds_bpermute_b32 v165, v185, v199 offset:64
	ds_bpermute_b32 v247, v185, v198 offset:64
	ds_bpermute_b32 v166, v185, v199 offset:128
	ds_bpermute_b32 v248, v185, v198 offset:128
	ds_bpermute_b32 v167, v185, v199 offset:192
	ds_bpermute_b32 v249, v185, v198 offset:192
	s_waitcnt lgkmcnt(0)
	v_mov_b32_e32 v251, v246
	v_mov_b32_e32 v250, v164
	v_fma_f32 v251, v251, v165, v247
	v_mul_f32_e32 v250, v250, v165
	v_fma_f32 v251, v251, v166, v248
	v_mul_f32_e32 v250, v250, v166
	v_fma_f32 v251, v251, v167, v249
	v_mul_f32_e32 v250, v250, v167
	s_mov_b64 exec, s[10:11]
	ds_write_b64 v182, v[250:251] offset:0
	s_mov_b64 exec, -1
	s_waitcnt lgkmcnt(0)
	s_barrier
	ds_read2_b64 v[4:7], v183 offset0:0 offset1:16
	s_add_i32 s52, s4, 0
	s_lshl_b32 s52, s52, 12
	v_add_u32_e32 v197, s52, v184
	s_waitcnt lgkmcnt(0)
	v_fma_f32 v198, v180, v4, v5
	v_cndmask_b32_e64 v199, v180, v198, s[24:25]
	v_fma_f32 v180, v198, v6, v7
	v_fma_f32 v200, v199, v164, v246
	v_cndmask_b32_e64 v199, v199, v200, s[16:17]
	v_fma_f32 v200, v199, v165, v247
	v_cndmask_b32_e64 v199, v199, v200, s[20:21]
	v_fma_f32 v200, v199, v166, v248
	v_cndmask_b32_e64 v199, v199, v200, s[22:23]
	v_fma_f32 v214, v120, v199, v170
	v_fma_f32 v215, v121, v214, v171
	v_fma_f32 v216, v122, v215, v172
	v_fma_f32 v217, v123, v216, v173
	v_fma_f32 v218, v124, v217, v174
	v_fma_f32 v219, v125, v218, v175
	v_fma_f32 v220, v126, v219, v176
	v_fma_f32 v221, v127, v220, v177
	ds_read_u16 v206, v197 offset:0
	ds_read_u16 v207, v197 offset:64
	ds_read_u16 v208, v197 offset:128
	ds_read_u16 v209, v197 offset:192
	ds_read_u16 v210, v197 offset:256
	ds_read_u16 v211, v197 offset:320
	ds_read_u16 v212, v197 offset:384
	ds_read_u16 v213, v197 offset:448
	s_waitcnt lgkmcnt(0)
	v_lshlrev_b32_e32 v206, 16, v206
	v_lshlrev_b32_e32 v207, 16, v207
	v_lshlrev_b32_e32 v208, 16, v208
	v_lshlrev_b32_e32 v209, 16, v209
	v_lshlrev_b32_e32 v210, 16, v210
	v_lshlrev_b32_e32 v211, 16, v211
	v_lshlrev_b32_e32 v212, 16, v212
	v_lshlrev_b32_e32 v213, 16, v213
	v_add_f32_e32 v214, v214, v206
	v_add_f32_e32 v215, v215, v207
	v_add_f32_e32 v216, v216, v208
	v_add_f32_e32 v217, v217, v209
	v_add_f32_e32 v218, v218, v210
	v_add_f32_e32 v219, v219, v211
	v_add_f32_e32 v220, v220, v212
	v_add_f32_e32 v221, v221, v213
	v_cvt_pk_bf16_f32 v206, v214, v215
	v_cvt_pk_bf16_f32 v208, v216, v217
	v_cvt_pk_bf16_f32 v210, v218, v219
	v_cvt_pk_bf16_f32 v212, v220, v221
	ds_write_b16 v197, v206 offset:0
	ds_write_b16_d16_hi v197, v206 offset:64
	ds_write_b16 v197, v208 offset:128
	ds_write_b16_d16_hi v197, v208 offset:192
	ds_write_b16 v197, v210 offset:256
	ds_write_b16_d16_hi v197, v210 offset:320
	ds_write_b16 v197, v212 offset:384
	ds_write_b16_d16_hi v197, v212 offset:448
	ds_read_b128 v[198:201], v130 offset:0
	ds_read_b128 v[214:217], v130 offset:576
	ds_read_b128 v[202:205], v131 offset:0
	ds_read_b128 v[218:221], v131 offset:576
	ds_read_b128 v[206:209], v130 offset:144
	ds_read_b128 v[222:225], v130 offset:720
	ds_read_b128 v[210:213], v131 offset:144
	s_waitcnt lgkmcnt(14)
	ds_read_b128 v[226:229], v131 offset:720
	s_waitcnt lgkmcnt(6)
	v_mfma_f32_16x16x32_bf16 v[100:103], v[198:201], v[20:23], v[12:15]
	v_mfma_f32_16x16x32_bf16 v[104:107], v[198:201], v[52:55], v[16:19]
	v_mfma_f32_16x16x32_bf16 v[108:111], v[198:201], v[84:87], v[242:245]
	v_mfma_f32_16x16x32_bf16 v[112:115], v[214:217], v[20:23], v[12:15]
	v_mfma_f32_16x16x32_bf16 v[138:141], v[214:217], v[52:55], v[16:19]
	v_mfma_f32_16x16x32_bf16 v[142:145], v[214:217], v[84:87], v[242:245]
	s_waitcnt lgkmcnt(4)
	v_mfma_f32_16x16x32_bf16 v[100:103], v[202:205], v[24:27], v[100:103]
	v_mfma_f32_16x16x32_bf16 v[104:107], v[202:205], v[56:59], v[104:107]
	v_mfma_f32_16x16x32_bf16 v[112:115], v[218:221], v[24:27], v[112:115]
	v_mfma_f32_16x16x32_bf16 v[138:141], v[218:221], v[56:59], v[138:141]
	ds_read_b128 v[198:201], v130 offset:288
	ds_read_b128 v[214:217], v130 offset:864
	ds_read_b128 v[202:205], v131 offset:288
	ds_read_b128 v[218:221], v131 offset:864
	s_waitcnt lgkmcnt(6)
	v_mfma_f32_16x16x32_bf16 v[100:103], v[206:209], v[28:31], v[100:103]
	v_mfma_f32_16x16x32_bf16 v[104:107], v[206:209], v[60:63], v[104:107]
	v_mfma_f32_16x16x32_bf16 v[108:111], v[206:209], v[88:91], v[108:111]
	v_mfma_f32_16x16x32_bf16 v[112:115], v[222:225], v[28:31], v[112:115]
	v_mfma_f32_16x16x32_bf16 v[138:141], v[222:225], v[60:63], v[138:141]
	v_mfma_f32_16x16x32_bf16 v[142:145], v[222:225], v[88:91], v[142:145]
	s_waitcnt lgkmcnt(4)
	v_mfma_f32_16x16x32_bf16 v[100:103], v[210:213], v[32:35], v[100:103]
	v_mfma_f32_16x16x32_bf16 v[104:107], v[210:213], v[64:67], v[104:107]
	v_mfma_f32_16x16x32_bf16 v[112:115], v[226:229], v[32:35], v[112:115]
	v_mfma_f32_16x16x32_bf16 v[138:141], v[226:229], v[64:67], v[138:141]
	ds_read_b128 v[206:209], v130 offset:432
	ds_read_b128 v[222:225], v130 offset:1008
	ds_read_b128 v[210:213], v131 offset:432
	ds_read_b128 v[226:229], v131 offset:1008
	s_waitcnt lgkmcnt(6)
	v_mfma_f32_16x16x32_bf16 v[100:103], v[198:201], v[36:39], v[100:103]
	v_mfma_f32_16x16x32_bf16 v[104:107], v[198:201], v[68:71], v[104:107]
	v_mfma_f32_16x16x32_bf16 v[108:111], v[198:201], v[92:95], v[108:111]
	v_mfma_f32_16x16x32_bf16 v[112:115], v[214:217], v[36:39], v[112:115]
	v_mfma_f32_16x16x32_bf16 v[138:141], v[214:217], v[68:71], v[138:141]
	v_mfma_f32_16x16x32_bf16 v[142:145], v[214:217], v[92:95], v[142:145]
	s_waitcnt lgkmcnt(4)
	v_mfma_f32_16x16x32_bf16 v[100:103], v[202:205], v[40:43], v[100:103]
	v_mfma_f32_16x16x32_bf16 v[104:107], v[202:205], v[72:75], v[104:107]
	v_mfma_f32_16x16x32_bf16 v[112:115], v[218:221], v[40:43], v[112:115]
	v_mfma_f32_16x16x32_bf16 v[138:141], v[218:221], v[72:75], v[138:141]
	s_waitcnt lgkmcnt(2)
	v_mfma_f32_16x16x32_bf16 v[100:103], v[206:209], v[44:47], v[100:103]
	v_mfma_f32_16x16x32_bf16 v[104:107], v[206:209], v[76:79], v[104:107]
	v_mfma_f32_16x16x32_bf16 v[108:111], v[206:209], v[96:99], v[108:111]
	v_mfma_f32_16x16x32_bf16 v[112:115], v[222:225], v[44:47], v[112:115]
	v_mfma_f32_16x16x32_bf16 v[138:141], v[222:225], v[76:79], v[138:141]
	v_mfma_f32_16x16x32_bf16 v[142:145], v[222:225], v[96:99], v[142:145]
	s_waitcnt lgkmcnt(0)
	v_mfma_f32_16x16x32_bf16 v[100:103], v[210:213], v[48:51], v[100:103]
	v_mfma_f32_16x16x32_bf16 v[104:107], v[210:213], v[80:83], v[104:107]
	v_mfma_f32_16x16x32_bf16 v[112:115], v[226:229], v[48:51], v[112:115]
	v_mfma_f32_16x16x32_bf16 v[138:141], v[226:229], v[80:83], v[138:141]
	s_waitcnt lgkmcnt(0)
	s_barrier
	s_waitcnt vmcnt(4)
	ds_write_b128 v134, v[230:233]
	ds_write_b128 v134, v[234:237] offset:4608
	ds_write_b128 v135, v[238:241]
	s_add_i32 s64, s4, 0
	s_mul_i32 s71, s64, 0x30000
	s_add_u32 s38, s60, s71
	s_addc_u32 s39, s61, 0
	s_lshl_b32 s64, s64, 12
	v_add_u32_e32 v136, s64, v195
	ds_read_b128 v[116:119], v136
	s_waitcnt vmcnt(3)
	s_waitcnt lgkmcnt(0)
	v_lshlrev_b32_e32 v136, 16, v116
	v_lshlrev_b32_e32 v137, 16, v8
	v_and_b32_e32 v168, 0xffff0000, v116
	v_and_b32_e32 v169, 0xffff0000, v8
	v_mul_f32_e32 v136, v136, v137
	v_mul_f32_e32 v168, v168, v169
	v_cvt_pk_bf16_f32 v116, v136, v168
	v_lshlrev_b32_e32 v136, 16, v117
	v_lshlrev_b32_e32 v137, 16, v9
	v_and_b32_e32 v168, 0xffff0000, v117
	v_and_b32_e32 v169, 0xffff0000, v9
	v_mul_f32_e32 v136, v136, v137
	v_mul_f32_e32 v168, v168, v169
	v_cvt_pk_bf16_f32 v117, v136, v168
	v_lshlrev_b32_e32 v136, 16, v118
	v_lshlrev_b32_e32 v137, 16, v10
	v_and_b32_e32 v168, 0xffff0000, v118
	v_and_b32_e32 v169, 0xffff0000, v10
	v_mul_f32_e32 v136, v136, v137
	v_mul_f32_e32 v168, v168, v169
	v_cvt_pk_bf16_f32 v118, v136, v168
	v_lshlrev_b32_e32 v136, 16, v119
	v_lshlrev_b32_e32 v137, 16, v11
	v_and_b32_e32 v168, 0xffff0000, v119
	v_and_b32_e32 v169, 0xffff0000, v11
	v_mul_f32_e32 v136, v136, v137
	v_mul_f32_e32 v168, v168, v169
	v_cvt_pk_bf16_f32 v119, v136, v168
	global_store_dwordx4 v255, v[116:119], s[38:39]
	s_add_i32 s64, s4, 1
	s_mul_i32 s71, s64, 0x30000
	s_add_u32 s38, s60, s71
	s_addc_u32 s39, s61, 0
	s_lshl_b32 s64, s64, 12
	global_load_dwordx4 v[8:11], v255, s[38:39]
	s_add_i32 s52, s4, 4
	s_min_u32 s52, s52, 31
	s_lshl_b32 s52, s52, 13
	s_add_u32 s26, s50, s52
	s_addc_u32 s27, s51, 0
	global_load_dwordx4 v[230:233], v154, s[26:27]
	global_load_dwordx4 v[234:237], v155, s[26:27]
	global_load_dwordx4 v[238:241], v159, s[26:27]
	v_exp_f32_e32 v198, v100
	v_exp_f32_e32 v199, v101
	v_exp_f32_e32 v200, v102
	v_exp_f32_e32 v201, v103
	v_exp_f32_e32 v202, v112
	v_exp_f32_e32 v203, v113
	v_exp_f32_e32 v204, v114
	v_exp_f32_e32 v205, v115
	v_exp_f32_e32 v214, v104
	v_add_f32_e32 v198, 1.0, v198
	v_exp_f32_e32 v215, v105
	v_add_f32_e32 v199, 1.0, v199
	v_exp_f32_e32 v216, v106
	v_add_f32_e32 v200, 1.0, v200
	v_exp_f32_e32 v217, v107
	v_add_f32_e32 v201, 1.0, v201
	v_exp_f32_e32 v218, v138
	v_add_f32_e32 v202, 1.0, v202
	v_exp_f32_e32 v219, v139
	v_add_f32_e32 v203, 1.0, v203
	v_exp_f32_e32 v220, v140
	v_add_f32_e32 v204, 1.0, v204
	v_exp_f32_e32 v221, v141
	v_add_f32_e32 v205, 1.0, v205
	v_rcp_f32_e32 v198, v198
	v_add_f32_e32 v214, 1.0, v214
	v_rcp_f32_e32 v199, v199
	v_add_f32_e32 v215, 1.0, v215
	v_rcp_f32_e32 v200, v200
	v_add_f32_e32 v216, 1.0, v216
	v_rcp_f32_e32 v201, v201
	v_add_f32_e32 v217, 1.0, v217
	v_rcp_f32_e32 v202, v202
	v_add_f32_e32 v218, 1.0, v218
	v_rcp_f32_e32 v203, v203
	v_add_f32_e32 v219, 1.0, v219
	v_rcp_f32_e32 v204, v204
	v_add_f32_e32 v220, 1.0, v220
	v_rcp_f32_e32 v205, v205
	v_add_f32_e32 v221, 1.0, v221
	v_mul_f32_e32 v198, v179, v198
	v_mul_f32_e32 v199, v179, v199
	v_mul_f32_e32 v200, v179, v200
	v_mul_f32_e32 v201, v179, v201
	v_mul_f32_e32 v202, v179, v202
	v_mul_f32_e32 v203, v179, v203
	v_mul_f32_e32 v204, v179, v204
	v_mul_f32_e32 v205, v179, v205
	v_exp_f32_e32 v120, v198
	v_exp_f32_e32 v121, v199
	v_exp_f32_e32 v122, v200
	v_exp_f32_e32 v123, v201
	v_exp_f32_e32 v124, v202
	v_exp_f32_e32 v125, v203
	v_exp_f32_e32 v126, v204
	v_exp_f32_e32 v127, v205
	v_fma_f32 v206, -v120, v120, 1.0
	v_fma_f32 v207, -v121, v121, 1.0
	v_fma_f32 v208, -v122, v122, 1.0
	v_fma_f32 v209, -v123, v123, 1.0
	v_fma_f32 v210, -v124, v124, 1.0
	v_fma_f32 v211, -v125, v125, 1.0
	v_fma_f32 v212, -v126, v126, 1.0
	v_fma_f32 v213, -v127, v127, 1.0
	v_max_f32_e32 v206, 0xda24260, v206
	v_max_f32_e32 v207, 0xda24260, v207
	v_max_f32_e32 v208, 0xda24260, v208
	v_max_f32_e32 v209, 0xda24260, v209
	v_max_f32_e32 v210, 0xda24260, v210
	v_max_f32_e32 v211, 0xda24260, v211
	v_max_f32_e32 v212, 0xda24260, v212
	v_max_f32_e32 v213, 0xda24260, v213
	v_mul_f32_e32 v198, v214, v206
	v_mul_f32_e32 v199, v215, v207
	v_mul_f32_e32 v200, v216, v208
	v_mul_f32_e32 v201, v217, v209
	v_mul_f32_e32 v202, v218, v210
	v_mul_f32_e32 v203, v219, v211
	v_mul_f32_e32 v204, v220, v212
	v_mul_f32_e32 v205, v221, v213
	v_mul_f32_e32 v214, v214, v198
	v_mul_f32_e32 v215, v215, v199
	v_mul_f32_e32 v216, v216, v200
	v_mul_f32_e32 v217, v217, v201
	v_mul_f32_e32 v218, v218, v202
	v_mul_f32_e32 v219, v219, v203
	v_mul_f32_e32 v220, v220, v204
	v_mul_f32_e32 v221, v221, v205
	v_rsq_f32_e32 v214, v214
	v_mul_f32_e32 v222, v108, v206
	v_rsq_f32_e32 v215, v215
	v_mul_f32_e32 v223, v109, v207
	v_rsq_f32_e32 v216, v216
	v_mul_f32_e32 v224, v110, v208
	v_rsq_f32_e32 v217, v217
	v_mul_f32_e32 v225, v111, v209
	v_rsq_f32_e32 v218, v218
	v_mul_f32_e32 v226, v142, v210
	v_rsq_f32_e32 v219, v219
	v_mul_f32_e32 v227, v143, v211
	v_rsq_f32_e32 v220, v220
	v_mul_f32_e32 v228, v144, v212
	v_rsq_f32_e32 v221, v221
	v_mul_f32_e32 v229, v145, v213
	v_mul_f32_e32 v170, v222, v214
	v_mul_f32_e32 v171, v223, v215
	v_mul_f32_e32 v172, v224, v216
	v_mul_f32_e32 v173, v225, v217
	v_mul_f32_e32 v174, v226, v218
	v_mul_f32_e32 v175, v227, v219
	v_mul_f32_e32 v176, v228, v220
	v_mul_f32_e32 v177, v229, v221
	v_mov_b32_e32 v198, v170
	v_mov_b32_e32 v199, v120
	v_fma_f32 v198, v121, v198, v171
	v_mul_f32_e32 v199, v199, v121
	v_fma_f32 v198, v122, v198, v172
	v_mul_f32_e32 v199, v199, v122
	v_fma_f32 v198, v123, v198, v173
	v_mul_f32_e32 v199, v199, v123
	v_fma_f32 v198, v124, v198, v174
	v_mul_f32_e32 v199, v199, v124
	v_fma_f32 v198, v125, v198, v175
	v_mul_f32_e32 v199, v199, v125
	v_fma_f32 v198, v126, v198, v176
	v_mul_f32_e32 v199, v199, v126
	v_fma_f32 v198, v127, v198, v177
	v_mul_f32_e32 v199, v199, v127
	ds_bpermute_b32 v164, v185, v199 offset:0
	ds_bpermute_b32 v246, v185, v198 offset:0
	ds_bpermute_b32 v165, v185, v199 offset:64
	ds_bpermute_b32 v247, v185, v198 offset:64
	ds_bpermute_b32 v166, v185, v199 offset:128
	ds_bpermute_b32 v248, v185, v198 offset:128
	ds_bpermute_b32 v167, v185, v199 offset:192
	ds_bpermute_b32 v249, v185, v198 offset:192
	s_waitcnt lgkmcnt(0)
	v_mov_b32_e32 v251, v246
	v_mov_b32_e32 v250, v164
	v_fma_f32 v251, v251, v165, v247
	v_mul_f32_e32 v250, v250, v165
	v_fma_f32 v251, v251, v166, v248
	v_mul_f32_e32 v250, v250, v166
	v_fma_f32 v251, v251, v167, v249
	v_mul_f32_e32 v250, v250, v167
	s_mov_b64 exec, s[10:11]
	ds_write_b64 v182, v[250:251] offset:1024
	s_mov_b64 exec, -1
	s_waitcnt lgkmcnt(0)
	s_barrier
	ds_read2_b64 v[4:7], v183 offset0:128 offset1:144
	s_add_i32 s52, s4, 1
	s_lshl_b32 s52, s52, 12
	v_add_u32_e32 v197, s52, v184
	s_waitcnt lgkmcnt(0)
	v_fma_f32 v198, v180, v4, v5
	v_cndmask_b32_e64 v199, v180, v198, s[24:25]
	v_fma_f32 v180, v198, v6, v7
	v_fma_f32 v200, v199, v164, v246
	v_cndmask_b32_e64 v199, v199, v200, s[16:17]
	v_fma_f32 v200, v199, v165, v247
	v_cndmask_b32_e64 v199, v199, v200, s[20:21]
	v_fma_f32 v200, v199, v166, v248
	v_cndmask_b32_e64 v199, v199, v200, s[22:23]
	v_fma_f32 v214, v120, v199, v170
	v_fma_f32 v215, v121, v214, v171
	v_fma_f32 v216, v122, v215, v172
	v_fma_f32 v217, v123, v216, v173
	v_fma_f32 v218, v124, v217, v174
	v_fma_f32 v219, v125, v218, v175
	v_fma_f32 v220, v126, v219, v176
	v_fma_f32 v221, v127, v220, v177
	ds_read_u16 v206, v197 offset:0
	ds_read_u16 v207, v197 offset:64
	ds_read_u16 v208, v197 offset:128
	ds_read_u16 v209, v197 offset:192
	ds_read_u16 v210, v197 offset:256
	ds_read_u16 v211, v197 offset:320
	ds_read_u16 v212, v197 offset:384
	ds_read_u16 v213, v197 offset:448
	s_waitcnt lgkmcnt(0)
	v_lshlrev_b32_e32 v206, 16, v206
	v_lshlrev_b32_e32 v207, 16, v207
	v_lshlrev_b32_e32 v208, 16, v208
	v_lshlrev_b32_e32 v209, 16, v209
	v_lshlrev_b32_e32 v210, 16, v210
	v_lshlrev_b32_e32 v211, 16, v211
	v_lshlrev_b32_e32 v212, 16, v212
	v_lshlrev_b32_e32 v213, 16, v213
	v_add_f32_e32 v214, v214, v206
	v_add_f32_e32 v215, v215, v207
	v_add_f32_e32 v216, v216, v208
	v_add_f32_e32 v217, v217, v209
	v_add_f32_e32 v218, v218, v210
	v_add_f32_e32 v219, v219, v211
	v_add_f32_e32 v220, v220, v212
	v_add_f32_e32 v221, v221, v213
	v_cvt_pk_bf16_f32 v206, v214, v215
	v_cvt_pk_bf16_f32 v208, v216, v217
	v_cvt_pk_bf16_f32 v210, v218, v219
	v_cvt_pk_bf16_f32 v212, v220, v221
	ds_write_b16 v197, v206 offset:0
	ds_write_b16_d16_hi v197, v206 offset:64
	ds_write_b16 v197, v208 offset:128
	ds_write_b16_d16_hi v197, v208 offset:192
	ds_write_b16 v197, v210 offset:256
	ds_write_b16_d16_hi v197, v210 offset:320
	ds_write_b16 v197, v212 offset:384
	ds_write_b16_d16_hi v197, v212 offset:448
	s_add_i32 s4, s4, 2
.Lrec2_loopB_d0:
	ds_read_b128 v[198:201], v130 offset:0
	ds_read_b128 v[214:217], v130 offset:576
	ds_read_b128 v[202:205], v131 offset:0
	ds_read_b128 v[218:221], v131 offset:576
	ds_read_b128 v[206:209], v130 offset:144
	ds_read_b128 v[222:225], v130 offset:720
	ds_read_b128 v[210:213], v131 offset:144
	s_waitcnt lgkmcnt(14)
	ds_read_b128 v[226:229], v131 offset:720
	s_waitcnt lgkmcnt(6)
	v_mfma_f32_16x16x32_bf16 v[100:103], v[198:201], v[20:23], v[12:15]
	v_mfma_f32_16x16x32_bf16 v[104:107], v[198:201], v[52:55], v[16:19]
	v_mfma_f32_16x16x32_bf16 v[108:111], v[198:201], v[84:87], v[242:245]
	v_mfma_f32_16x16x32_bf16 v[112:115], v[214:217], v[20:23], v[12:15]
	v_mfma_f32_16x16x32_bf16 v[138:141], v[214:217], v[52:55], v[16:19]
	v_mfma_f32_16x16x32_bf16 v[142:145], v[214:217], v[84:87], v[242:245]
	s_waitcnt lgkmcnt(4)
	v_mfma_f32_16x16x32_bf16 v[100:103], v[202:205], v[24:27], v[100:103]
	v_mfma_f32_16x16x32_bf16 v[104:107], v[202:205], v[56:59], v[104:107]
	v_mfma_f32_16x16x32_bf16 v[112:115], v[218:221], v[24:27], v[112:115]
	v_mfma_f32_16x16x32_bf16 v[138:141], v[218:221], v[56:59], v[138:141]
	ds_read_b128 v[198:201], v130 offset:288
	ds_read_b128 v[214:217], v130 offset:864
	ds_read_b128 v[202:205], v131 offset:288
	ds_read_b128 v[218:221], v131 offset:864
	s_waitcnt lgkmcnt(6)
	v_mfma_f32_16x16x32_bf16 v[100:103], v[206:209], v[28:31], v[100:103]
	v_mfma_f32_16x16x32_bf16 v[104:107], v[206:209], v[60:63], v[104:107]
	v_mfma_f32_16x16x32_bf16 v[108:111], v[206:209], v[88:91], v[108:111]
	v_mfma_f32_16x16x32_bf16 v[112:115], v[222:225], v[28:31], v[112:115]
	v_mfma_f32_16x16x32_bf16 v[138:141], v[222:225], v[60:63], v[138:141]
	v_mfma_f32_16x16x32_bf16 v[142:145], v[222:225], v[88:91], v[142:145]
	s_waitcnt lgkmcnt(4)
	v_mfma_f32_16x16x32_bf16 v[100:103], v[210:213], v[32:35], v[100:103]
	v_mfma_f32_16x16x32_bf16 v[104:107], v[210:213], v[64:67], v[104:107]
	v_mfma_f32_16x16x32_bf16 v[112:115], v[226:229], v[32:35], v[112:115]
	v_mfma_f32_16x16x32_bf16 v[138:141], v[226:229], v[64:67], v[138:141]
	ds_read_b128 v[206:209], v130 offset:432
	ds_read_b128 v[222:225], v130 offset:1008
	ds_read_b128 v[210:213], v131 offset:432
	ds_read_b128 v[226:229], v131 offset:1008
	s_waitcnt lgkmcnt(6)
	v_mfma_f32_16x16x32_bf16 v[100:103], v[198:201], v[36:39], v[100:103]
	v_mfma_f32_16x16x32_bf16 v[104:107], v[198:201], v[68:71], v[104:107]
	v_mfma_f32_16x16x32_bf16 v[108:111], v[198:201], v[92:95], v[108:111]
	v_mfma_f32_16x16x32_bf16 v[112:115], v[214:217], v[36:39], v[112:115]
	v_mfma_f32_16x16x32_bf16 v[138:141], v[214:217], v[68:71], v[138:141]
	v_mfma_f32_16x16x32_bf16 v[142:145], v[214:217], v[92:95], v[142:145]
	s_waitcnt lgkmcnt(4)
	v_mfma_f32_16x16x32_bf16 v[100:103], v[202:205], v[40:43], v[100:103]
	v_mfma_f32_16x16x32_bf16 v[104:107], v[202:205], v[72:75], v[104:107]
	v_mfma_f32_16x16x32_bf16 v[112:115], v[218:221], v[40:43], v[112:115]
	v_mfma_f32_16x16x32_bf16 v[138:141], v[218:221], v[72:75], v[138:141]
	s_waitcnt lgkmcnt(2)
	v_mfma_f32_16x16x32_bf16 v[100:103], v[206:209], v[44:47], v[100:103]
	v_mfma_f32_16x16x32_bf16 v[104:107], v[206:209], v[76:79], v[104:107]
	v_mfma_f32_16x16x32_bf16 v[108:111], v[206:209], v[96:99], v[108:111]
	v_mfma_f32_16x16x32_bf16 v[112:115], v[222:225], v[44:47], v[112:115]
	v_mfma_f32_16x16x32_bf16 v[138:141], v[222:225], v[76:79], v[138:141]
	v_mfma_f32_16x16x32_bf16 v[142:145], v[222:225], v[96:99], v[142:145]
	s_waitcnt lgkmcnt(0)
	v_mfma_f32_16x16x32_bf16 v[100:103], v[210:213], v[48:51], v[100:103]
	v_mfma_f32_16x16x32_bf16 v[104:107], v[210:213], v[80:83], v[104:107]
	v_mfma_f32_16x16x32_bf16 v[112:115], v[226:229], v[48:51], v[112:115]
	v_mfma_f32_16x16x32_bf16 v[138:141], v[226:229], v[80:83], v[138:141]
	s_waitcnt lgkmcnt(0)
	s_barrier
	s_waitcnt vmcnt(5)
	ds_write_b128 v134, v[146:149]
	ds_write_b128 v134, v[150:153] offset:4608
	ds_write_b128 v135, v[160:163]
	s_add_i32 s64, s4, -1
	s_mul_i32 s71, s64, 0x30000
	s_add_u32 s38, s60, s71
	s_addc_u32 s39, s61, 0
	s_lshl_b32 s64, s64, 12
	v_add_u32_e32 v136, s64, v195
	ds_read_b128 v[116:119], v136
	s_waitcnt vmcnt(3)
	s_waitcnt lgkmcnt(0)
	v_lshlrev_b32_e32 v136, 16, v116
	v_lshlrev_b32_e32 v137, 16, v8
	v_and_b32_e32 v168, 0xffff0000, v116
	v_and_b32_e32 v169, 0xffff0000, v8
	v_mul_f32_e32 v136, v136, v137
	v_mul_f32_e32 v168, v168, v169
	v_cvt_pk_bf16_f32 v116, v136, v168
	v_lshlrev_b32_e32 v136, 16, v117
	v_lshlrev_b32_e32 v137, 16, v9
	v_and_b32_e32 v168, 0xffff0000, v117
	v_and_b32_e32 v169, 0xffff0000, v9
	v_mul_f32_e32 v136, v136, v137
	v_mul_f32_e32 v168, v168, v169
	v_cvt_pk_bf16_f32 v117, v136, v168
	v_lshlrev_b32_e32 v136, 16, v118
	v_lshlrev_b32_e32 v137, 16, v10
	v_and_b32_e32 v168, 0xffff0000, v118
	v_and_b32_e32 v169, 0xffff0000, v10
	v_mul_f32_e32 v136, v136, v137
	v_mul_f32_e32 v168, v168, v169
	v_cvt_pk_bf16_f32 v118, v136, v168
	v_lshlrev_b32_e32 v136, 16, v119
	v_lshlrev_b32_e32 v137, 16, v11
	v_and_b32_e32 v168, 0xffff0000, v119
	v_and_b32_e32 v169, 0xffff0000, v11
	v_mul_f32_e32 v136, v136, v137
	v_mul_f32_e32 v168, v168, v169
	v_cvt_pk_bf16_f32 v119, v136, v168
	global_store_dwordx4 v255, v[116:119], s[38:39]
	s_add_i32 s64, s4, 0
	s_mul_i32 s71, s64, 0x30000
	s_add_u32 s38, s60, s71
	s_addc_u32 s39, s61, 0
	s_lshl_b32 s64, s64, 12
	global_load_dwordx4 v[8:11], v255, s[38:39]
	s_add_i32 s52, s4, 3
	s_min_u32 s52, s52, 31
	s_lshl_b32 s52, s52, 13
	s_add_u32 s26, s50, s52
	s_addc_u32 s27, s51, 0
	global_load_dwordx4 v[146:149], v154, s[26:27]
	global_load_dwordx4 v[150:153], v155, s[26:27]
	global_load_dwordx4 v[160:163], v159, s[26:27]
	v_exp_f32_e32 v198, v100
	v_exp_f32_e32 v199, v101
	v_exp_f32_e32 v200, v102
	v_exp_f32_e32 v201, v103
	v_exp_f32_e32 v202, v112
	v_exp_f32_e32 v203, v113
	v_exp_f32_e32 v204, v114
	v_exp_f32_e32 v205, v115
	v_exp_f32_e32 v214, v104
	v_add_f32_e32 v198, 1.0, v198
	v_exp_f32_e32 v215, v105
	v_add_f32_e32 v199, 1.0, v199
	v_exp_f32_e32 v216, v106
	v_add_f32_e32 v200, 1.0, v200
	v_exp_f32_e32 v217, v107
	v_add_f32_e32 v201, 1.0, v201
	v_exp_f32_e32 v218, v138
	v_add_f32_e32 v202, 1.0, v202
	v_exp_f32_e32 v219, v139
	v_add_f32_e32 v203, 1.0, v203
	v_exp_f32_e32 v220, v140
	v_add_f32_e32 v204, 1.0, v204
	v_exp_f32_e32 v221, v141
	v_add_f32_e32 v205, 1.0, v205
	v_rcp_f32_e32 v198, v198
	v_add_f32_e32 v214, 1.0, v214
	v_rcp_f32_e32 v199, v199
	v_add_f32_e32 v215, 1.0, v215
	v_rcp_f32_e32 v200, v200
	v_add_f32_e32 v216, 1.0, v216
	v_rcp_f32_e32 v201, v201
	v_add_f32_e32 v217, 1.0, v217
	v_rcp_f32_e32 v202, v202
	v_add_f32_e32 v218, 1.0, v218
	v_rcp_f32_e32 v203, v203
	v_add_f32_e32 v219, 1.0, v219
	v_rcp_f32_e32 v204, v204
	v_add_f32_e32 v220, 1.0, v220
	v_rcp_f32_e32 v205, v205
	v_add_f32_e32 v221, 1.0, v221
	v_mul_f32_e32 v198, v179, v198
	v_mul_f32_e32 v199, v179, v199
	v_mul_f32_e32 v200, v179, v200
	v_mul_f32_e32 v201, v179, v201
	v_mul_f32_e32 v202, v179, v202
	v_mul_f32_e32 v203, v179, v203
	v_mul_f32_e32 v204, v179, v204
	v_mul_f32_e32 v205, v179, v205
	v_exp_f32_e32 v120, v198
	v_exp_f32_e32 v121, v199
	v_exp_f32_e32 v122, v200
	v_exp_f32_e32 v123, v201
	v_exp_f32_e32 v124, v202
	v_exp_f32_e32 v125, v203
	v_exp_f32_e32 v126, v204
	v_exp_f32_e32 v127, v205
	v_fma_f32 v206, -v120, v120, 1.0
	v_fma_f32 v207, -v121, v121, 1.0
	v_fma_f32 v208, -v122, v122, 1.0
	v_fma_f32 v209, -v123, v123, 1.0
	v_fma_f32 v210, -v124, v124, 1.0
	v_fma_f32 v211, -v125, v125, 1.0
	v_fma_f32 v212, -v126, v126, 1.0
	v_fma_f32 v213, -v127, v127, 1.0
	v_max_f32_e32 v206, 0xda24260, v206
	v_max_f32_e32 v207, 0xda24260, v207
	v_max_f32_e32 v208, 0xda24260, v208
	v_max_f32_e32 v209, 0xda24260, v209
	v_max_f32_e32 v210, 0xda24260, v210
	v_max_f32_e32 v211, 0xda24260, v211
	v_max_f32_e32 v212, 0xda24260, v212
	v_max_f32_e32 v213, 0xda24260, v213
	v_mul_f32_e32 v198, v214, v206
	v_mul_f32_e32 v199, v215, v207
	v_mul_f32_e32 v200, v216, v208
	v_mul_f32_e32 v201, v217, v209
	v_mul_f32_e32 v202, v218, v210
	v_mul_f32_e32 v203, v219, v211
	v_mul_f32_e32 v204, v220, v212
	v_mul_f32_e32 v205, v221, v213
	v_mul_f32_e32 v214, v214, v198
	v_mul_f32_e32 v215, v215, v199
	v_mul_f32_e32 v216, v216, v200
	v_mul_f32_e32 v217, v217, v201
	v_mul_f32_e32 v218, v218, v202
	v_mul_f32_e32 v219, v219, v203
	v_mul_f32_e32 v220, v220, v204
	v_mul_f32_e32 v221, v221, v205
	v_rsq_f32_e32 v214, v214
	v_mul_f32_e32 v222, v108, v206
	v_rsq_f32_e32 v215, v215
	v_mul_f32_e32 v223, v109, v207
	v_rsq_f32_e32 v216, v216
	v_mul_f32_e32 v224, v110, v208
	v_rsq_f32_e32 v217, v217
	v_mul_f32_e32 v225, v111, v209
	v_rsq_f32_e32 v218, v218
	v_mul_f32_e32 v226, v142, v210
	v_rsq_f32_e32 v219, v219
	v_mul_f32_e32 v227, v143, v211
	v_rsq_f32_e32 v220, v220
	v_mul_f32_e32 v228, v144, v212
	v_rsq_f32_e32 v221, v221
	v_mul_f32_e32 v229, v145, v213
	v_mul_f32_e32 v170, v222, v214
	v_mul_f32_e32 v171, v223, v215
	v_mul_f32_e32 v172, v224, v216
	v_mul_f32_e32 v173, v225, v217
	v_mul_f32_e32 v174, v226, v218
	v_mul_f32_e32 v175, v227, v219
	v_mul_f32_e32 v176, v228, v220
	v_mul_f32_e32 v177, v229, v221
	v_mov_b32_e32 v198, v170
	v_mov_b32_e32 v199, v120
	v_fma_f32 v198, v121, v198, v171
	v_mul_f32_e32 v199, v199, v121
	v_fma_f32 v198, v122, v198, v172
	v_mul_f32_e32 v199, v199, v122
	v_fma_f32 v198, v123, v198, v173
	v_mul_f32_e32 v199, v199, v123
	v_fma_f32 v198, v124, v198, v174
	v_mul_f32_e32 v199, v199, v124
	v_fma_f32 v198, v125, v198, v175
	v_mul_f32_e32 v199, v199, v125
	v_fma_f32 v198, v126, v198, v176
	v_mul_f32_e32 v199, v199, v126
	v_fma_f32 v198, v127, v198, v177
	v_mul_f32_e32 v199, v199, v127
	ds_bpermute_b32 v164, v185, v199 offset:0
	ds_bpermute_b32 v246, v185, v198 offset:0
	ds_bpermute_b32 v165, v185, v199 offset:64
	ds_bpermute_b32 v247, v185, v198 offset:64
	ds_bpermute_b32 v166, v185, v199 offset:128
	ds_bpermute_b32 v248, v185, v198 offset:128
	ds_bpermute_b32 v167, v185, v199 offset:192
	ds_bpermute_b32 v249, v185, v198 offset:192
	s_waitcnt lgkmcnt(0)
	v_mov_b32_e32 v251, v246
	v_mov_b32_e32 v250, v164
	v_fma_f32 v251, v251, v165, v247
	v_mul_f32_e32 v250, v250, v165
	v_fma_f32 v251, v251, v166, v248
	v_mul_f32_e32 v250, v250, v166
	v_fma_f32 v251, v251, v167, v249
	v_mul_f32_e32 v250, v250, v167
	s_mov_b64 exec, s[10:11]
	ds_write_b64 v182, v[250:251] offset:0
	s_mov_b64 exec, -1
	s_waitcnt lgkmcnt(0)
	s_barrier
	ds_read2_b64 v[4:7], v183 offset0:0 offset1:16
	s_add_i32 s52, s4, 0
	s_lshl_b32 s52, s52, 12
	v_add_u32_e32 v197, s52, v184
	s_waitcnt lgkmcnt(0)
	v_fma_f32 v198, v180, v4, v5
	v_cndmask_b32_e64 v199, v180, v198, s[24:25]
	v_fma_f32 v180, v198, v6, v7
	v_fma_f32 v200, v199, v164, v246
	v_cndmask_b32_e64 v199, v199, v200, s[16:17]
	v_fma_f32 v200, v199, v165, v247
	v_cndmask_b32_e64 v199, v199, v200, s[20:21]
	v_fma_f32 v200, v199, v166, v248
	v_cndmask_b32_e64 v199, v199, v200, s[22:23]
	v_fma_f32 v214, v120, v199, v170
	v_fma_f32 v215, v121, v214, v171
	v_fma_f32 v216, v122, v215, v172
	v_fma_f32 v217, v123, v216, v173
	v_fma_f32 v218, v124, v217, v174
	v_fma_f32 v219, v125, v218, v175
	v_fma_f32 v220, v126, v219, v176
	v_fma_f32 v221, v127, v220, v177
	ds_read_u16 v206, v197 offset:0
	ds_read_u16 v207, v197 offset:64
	ds_read_u16 v208, v197 offset:128
	ds_read_u16 v209, v197 offset:192
	ds_read_u16 v210, v197 offset:256
	ds_read_u16 v211, v197 offset:320
	ds_read_u16 v212, v197 offset:384
	ds_read_u16 v213, v197 offset:448
	s_waitcnt lgkmcnt(0)
	v_lshlrev_b32_e32 v206, 16, v206
	v_lshlrev_b32_e32 v207, 16, v207
	v_lshlrev_b32_e32 v208, 16, v208
	v_lshlrev_b32_e32 v209, 16, v209
	v_lshlrev_b32_e32 v210, 16, v210
	v_lshlrev_b32_e32 v211, 16, v211
	v_lshlrev_b32_e32 v212, 16, v212
	v_lshlrev_b32_e32 v213, 16, v213
	v_add_f32_e32 v214, v214, v206
	v_add_f32_e32 v215, v215, v207
	v_add_f32_e32 v216, v216, v208
	v_add_f32_e32 v217, v217, v209
	v_add_f32_e32 v218, v218, v210
	v_add_f32_e32 v219, v219, v211
	v_add_f32_e32 v220, v220, v212
	v_add_f32_e32 v221, v221, v213
	v_cvt_pk_bf16_f32 v206, v214, v215
	v_cvt_pk_bf16_f32 v208, v216, v217
	v_cvt_pk_bf16_f32 v210, v218, v219
	v_cvt_pk_bf16_f32 v212, v220, v221
	ds_write_b16 v197, v206 offset:0
	ds_write_b16_d16_hi v197, v206 offset:64
	ds_write_b16 v197, v208 offset:128
	ds_write_b16_d16_hi v197, v208 offset:192
	ds_write_b16 v197, v210 offset:256
	ds_write_b16_d16_hi v197, v210 offset:320
	ds_write_b16 v197, v212 offset:384
	ds_write_b16_d16_hi v197, v212 offset:448
	ds_read_b128 v[198:201], v130 offset:0
	ds_read_b128 v[214:217], v130 offset:576
	ds_read_b128 v[202:205], v131 offset:0
	ds_read_b128 v[218:221], v131 offset:576
	ds_read_b128 v[206:209], v130 offset:144
	ds_read_b128 v[222:225], v130 offset:720
	ds_read_b128 v[210:213], v131 offset:144
	s_waitcnt lgkmcnt(14)
	ds_read_b128 v[226:229], v131 offset:720
	s_waitcnt lgkmcnt(6)
	v_mfma_f32_16x16x32_bf16 v[100:103], v[198:201], v[20:23], v[12:15]
	v_mfma_f32_16x16x32_bf16 v[104:107], v[198:201], v[52:55], v[16:19]
	v_mfma_f32_16x16x32_bf16 v[108:111], v[198:201], v[84:87], v[242:245]
	v_mfma_f32_16x16x32_bf16 v[112:115], v[214:217], v[20:23], v[12:15]
	v_mfma_f32_16x16x32_bf16 v[138:141], v[214:217], v[52:55], v[16:19]
	v_mfma_f32_16x16x32_bf16 v[142:145], v[214:217], v[84:87], v[242:245]
	s_waitcnt lgkmcnt(4)
	v_mfma_f32_16x16x32_bf16 v[100:103], v[202:205], v[24:27], v[100:103]
	v_mfma_f32_16x16x32_bf16 v[104:107], v[202:205], v[56:59], v[104:107]
	v_mfma_f32_16x16x32_bf16 v[112:115], v[218:221], v[24:27], v[112:115]
	v_mfma_f32_16x16x32_bf16 v[138:141], v[218:221], v[56:59], v[138:141]
	ds_read_b128 v[198:201], v130 offset:288
	ds_read_b128 v[214:217], v130 offset:864
	ds_read_b128 v[202:205], v131 offset:288
	ds_read_b128 v[218:221], v131 offset:864
	s_waitcnt lgkmcnt(6)
	v_mfma_f32_16x16x32_bf16 v[100:103], v[206:209], v[28:31], v[100:103]
	v_mfma_f32_16x16x32_bf16 v[104:107], v[206:209], v[60:63], v[104:107]
	v_mfma_f32_16x16x32_bf16 v[108:111], v[206:209], v[88:91], v[108:111]
	v_mfma_f32_16x16x32_bf16 v[112:115], v[222:225], v[28:31], v[112:115]
	v_mfma_f32_16x16x32_bf16 v[138:141], v[222:225], v[60:63], v[138:141]
	v_mfma_f32_16x16x32_bf16 v[142:145], v[222:225], v[88:91], v[142:145]
	s_waitcnt lgkmcnt(4)
	v_mfma_f32_16x16x32_bf16 v[100:103], v[210:213], v[32:35], v[100:103]
	v_mfma_f32_16x16x32_bf16 v[104:107], v[210:213], v[64:67], v[104:107]
	v_mfma_f32_16x16x32_bf16 v[112:115], v[226:229], v[32:35], v[112:115]
	v_mfma_f32_16x16x32_bf16 v[138:141], v[226:229], v[64:67], v[138:141]
	ds_read_b128 v[206:209], v130 offset:432
	ds_read_b128 v[222:225], v130 offset:1008
	ds_read_b128 v[210:213], v131 offset:432
	ds_read_b128 v[226:229], v131 offset:1008
	s_waitcnt lgkmcnt(6)
	v_mfma_f32_16x16x32_bf16 v[100:103], v[198:201], v[36:39], v[100:103]
	v_mfma_f32_16x16x32_bf16 v[104:107], v[198:201], v[68:71], v[104:107]
	v_mfma_f32_16x16x32_bf16 v[108:111], v[198:201], v[92:95], v[108:111]
	v_mfma_f32_16x16x32_bf16 v[112:115], v[214:217], v[36:39], v[112:115]
	v_mfma_f32_16x16x32_bf16 v[138:141], v[214:217], v[68:71], v[138:141]
	v_mfma_f32_16x16x32_bf16 v[142:145], v[214:217], v[92:95], v[142:145]
	s_waitcnt lgkmcnt(4)
	v_mfma_f32_16x16x32_bf16 v[100:103], v[202:205], v[40:43], v[100:103]
	v_mfma_f32_16x16x32_bf16 v[104:107], v[202:205], v[72:75], v[104:107]
	v_mfma_f32_16x16x32_bf16 v[112:115], v[218:221], v[40:43], v[112:115]
	v_mfma_f32_16x16x32_bf16 v[138:141], v[218:221], v[72:75], v[138:141]
	s_waitcnt lgkmcnt(2)
	v_mfma_f32_16x16x32_bf16 v[100:103], v[206:209], v[44:47], v[100:103]
	v_mfma_f32_16x16x32_bf16 v[104:107], v[206:209], v[76:79], v[104:107]
	v_mfma_f32_16x16x32_bf16 v[108:111], v[206:209], v[96:99], v[108:111]
	v_mfma_f32_16x16x32_bf16 v[112:115], v[222:225], v[44:47], v[112:115]
	v_mfma_f32_16x16x32_bf16 v[138:141], v[222:225], v[76:79], v[138:141]
	v_mfma_f32_16x16x32_bf16 v[142:145], v[222:225], v[96:99], v[142:145]
	s_waitcnt lgkmcnt(0)
	v_mfma_f32_16x16x32_bf16 v[100:103], v[210:213], v[48:51], v[100:103]
	v_mfma_f32_16x16x32_bf16 v[104:107], v[210:213], v[80:83], v[104:107]
	v_mfma_f32_16x16x32_bf16 v[112:115], v[226:229], v[48:51], v[112:115]
	v_mfma_f32_16x16x32_bf16 v[138:141], v[226:229], v[80:83], v[138:141]
	s_waitcnt lgkmcnt(0)
	s_barrier
	s_waitcnt vmcnt(5)
	ds_write_b128 v134, v[230:233]
	ds_write_b128 v134, v[234:237] offset:4608
	ds_write_b128 v135, v[238:241]
	s_add_i32 s64, s4, 0
	s_mul_i32 s71, s64, 0x30000
	s_add_u32 s38, s60, s71
	s_addc_u32 s39, s61, 0
	s_lshl_b32 s64, s64, 12
	v_add_u32_e32 v136, s64, v195
	ds_read_b128 v[116:119], v136
	s_waitcnt vmcnt(3)
	s_waitcnt lgkmcnt(0)
	v_lshlrev_b32_e32 v136, 16, v116
	v_lshlrev_b32_e32 v137, 16, v8
	v_and_b32_e32 v168, 0xffff0000, v116
	v_and_b32_e32 v169, 0xffff0000, v8
	v_mul_f32_e32 v136, v136, v137
	v_mul_f32_e32 v168, v168, v169
	v_cvt_pk_bf16_f32 v116, v136, v168
	v_lshlrev_b32_e32 v136, 16, v117
	v_lshlrev_b32_e32 v137, 16, v9
	v_and_b32_e32 v168, 0xffff0000, v117
	v_and_b32_e32 v169, 0xffff0000, v9
	v_mul_f32_e32 v136, v136, v137
	v_mul_f32_e32 v168, v168, v169
	v_cvt_pk_bf16_f32 v117, v136, v168
	v_lshlrev_b32_e32 v136, 16, v118
	v_lshlrev_b32_e32 v137, 16, v10
	v_and_b32_e32 v168, 0xffff0000, v118
	v_and_b32_e32 v169, 0xffff0000, v10
	v_mul_f32_e32 v136, v136, v137
	v_mul_f32_e32 v168, v168, v169
	v_cvt_pk_bf16_f32 v118, v136, v168
	v_lshlrev_b32_e32 v136, 16, v119
	v_lshlrev_b32_e32 v137, 16, v11
	v_and_b32_e32 v168, 0xffff0000, v119
	v_and_b32_e32 v169, 0xffff0000, v11
	v_mul_f32_e32 v136, v136, v137
	v_mul_f32_e32 v168, v168, v169
	v_cvt_pk_bf16_f32 v119, v136, v168
	global_store_dwordx4 v255, v[116:119], s[38:39]
	s_add_i32 s64, s4, 1
	s_mul_i32 s71, s64, 0x30000
	s_add_u32 s38, s60, s71
	s_addc_u32 s39, s61, 0
	s_lshl_b32 s64, s64, 12
	global_load_dwordx4 v[8:11], v255, s[38:39]
	s_add_i32 s52, s4, 4
	s_min_u32 s52, s52, 31
	s_lshl_b32 s52, s52, 13
	s_add_u32 s26, s50, s52
	s_addc_u32 s27, s51, 0
	global_load_dwordx4 v[230:233], v154, s[26:27]
	global_load_dwordx4 v[234:237], v155, s[26:27]
	global_load_dwordx4 v[238:241], v159, s[26:27]
	v_exp_f32_e32 v198, v100
	v_exp_f32_e32 v199, v101
	v_exp_f32_e32 v200, v102
	v_exp_f32_e32 v201, v103
	v_exp_f32_e32 v202, v112
	v_exp_f32_e32 v203, v113
	v_exp_f32_e32 v204, v114
	v_exp_f32_e32 v205, v115
	v_exp_f32_e32 v214, v104
	v_add_f32_e32 v198, 1.0, v198
	v_exp_f32_e32 v215, v105
	v_add_f32_e32 v199, 1.0, v199
	v_exp_f32_e32 v216, v106
	v_add_f32_e32 v200, 1.0, v200
	v_exp_f32_e32 v217, v107
	v_add_f32_e32 v201, 1.0, v201
	v_exp_f32_e32 v218, v138
	v_add_f32_e32 v202, 1.0, v202
	v_exp_f32_e32 v219, v139
	v_add_f32_e32 v203, 1.0, v203
	v_exp_f32_e32 v220, v140
	v_add_f32_e32 v204, 1.0, v204
	v_exp_f32_e32 v221, v141
	v_add_f32_e32 v205, 1.0, v205
	v_rcp_f32_e32 v198, v198
	v_add_f32_e32 v214, 1.0, v214
	v_rcp_f32_e32 v199, v199
	v_add_f32_e32 v215, 1.0, v215
	v_rcp_f32_e32 v200, v200
	v_add_f32_e32 v216, 1.0, v216
	v_rcp_f32_e32 v201, v201
	v_add_f32_e32 v217, 1.0, v217
	v_rcp_f32_e32 v202, v202
	v_add_f32_e32 v218, 1.0, v218
	v_rcp_f32_e32 v203, v203
	v_add_f32_e32 v219, 1.0, v219
	v_rcp_f32_e32 v204, v204
	v_add_f32_e32 v220, 1.0, v220
	v_rcp_f32_e32 v205, v205
	v_add_f32_e32 v221, 1.0, v221
	v_mul_f32_e32 v198, v179, v198
	v_mul_f32_e32 v199, v179, v199
	v_mul_f32_e32 v200, v179, v200
	v_mul_f32_e32 v201, v179, v201
	v_mul_f32_e32 v202, v179, v202
	v_mul_f32_e32 v203, v179, v203
	v_mul_f32_e32 v204, v179, v204
	v_mul_f32_e32 v205, v179, v205
	v_exp_f32_e32 v120, v198
	v_exp_f32_e32 v121, v199
	v_exp_f32_e32 v122, v200
	v_exp_f32_e32 v123, v201
	v_exp_f32_e32 v124, v202
	v_exp_f32_e32 v125, v203
	v_exp_f32_e32 v126, v204
	v_exp_f32_e32 v127, v205
	v_fma_f32 v206, -v120, v120, 1.0
	v_fma_f32 v207, -v121, v121, 1.0
	v_fma_f32 v208, -v122, v122, 1.0
	v_fma_f32 v209, -v123, v123, 1.0
	v_fma_f32 v210, -v124, v124, 1.0
	v_fma_f32 v211, -v125, v125, 1.0
	v_fma_f32 v212, -v126, v126, 1.0
	v_fma_f32 v213, -v127, v127, 1.0
	v_max_f32_e32 v206, 0xda24260, v206
	v_max_f32_e32 v207, 0xda24260, v207
	v_max_f32_e32 v208, 0xda24260, v208
	v_max_f32_e32 v209, 0xda24260, v209
	v_max_f32_e32 v210, 0xda24260, v210
	v_max_f32_e32 v211, 0xda24260, v211
	v_max_f32_e32 v212, 0xda24260, v212
	v_max_f32_e32 v213, 0xda24260, v213
	v_mul_f32_e32 v198, v214, v206
	v_mul_f32_e32 v199, v215, v207
	v_mul_f32_e32 v200, v216, v208
	v_mul_f32_e32 v201, v217, v209
	v_mul_f32_e32 v202, v218, v210
	v_mul_f32_e32 v203, v219, v211
	v_mul_f32_e32 v204, v220, v212
	v_mul_f32_e32 v205, v221, v213
	v_mul_f32_e32 v214, v214, v198
	v_mul_f32_e32 v215, v215, v199
	v_mul_f32_e32 v216, v216, v200
	v_mul_f32_e32 v217, v217, v201
	v_mul_f32_e32 v218, v218, v202
	v_mul_f32_e32 v219, v219, v203
	v_mul_f32_e32 v220, v220, v204
	v_mul_f32_e32 v221, v221, v205
	v_rsq_f32_e32 v214, v214
	v_mul_f32_e32 v222, v108, v206
	v_rsq_f32_e32 v215, v215
	v_mul_f32_e32 v223, v109, v207
	v_rsq_f32_e32 v216, v216
	v_mul_f32_e32 v224, v110, v208
	v_rsq_f32_e32 v217, v217
	v_mul_f32_e32 v225, v111, v209
	v_rsq_f32_e32 v218, v218
	v_mul_f32_e32 v226, v142, v210
	v_rsq_f32_e32 v219, v219
	v_mul_f32_e32 v227, v143, v211
	v_rsq_f32_e32 v220, v220
	v_mul_f32_e32 v228, v144, v212
	v_rsq_f32_e32 v221, v221
	v_mul_f32_e32 v229, v145, v213
	v_mul_f32_e32 v170, v222, v214
	v_mul_f32_e32 v171, v223, v215
	v_mul_f32_e32 v172, v224, v216
	v_mul_f32_e32 v173, v225, v217
	v_mul_f32_e32 v174, v226, v218
	v_mul_f32_e32 v175, v227, v219
	v_mul_f32_e32 v176, v228, v220
	v_mul_f32_e32 v177, v229, v221
	v_mov_b32_e32 v198, v170
	v_mov_b32_e32 v199, v120
	v_fma_f32 v198, v121, v198, v171
	v_mul_f32_e32 v199, v199, v121
	v_fma_f32 v198, v122, v198, v172
	v_mul_f32_e32 v199, v199, v122
	v_fma_f32 v198, v123, v198, v173
	v_mul_f32_e32 v199, v199, v123
	v_fma_f32 v198, v124, v198, v174
	v_mul_f32_e32 v199, v199, v124
	v_fma_f32 v198, v125, v198, v175
	v_mul_f32_e32 v199, v199, v125
	v_fma_f32 v198, v126, v198, v176
	v_mul_f32_e32 v199, v199, v126
	v_fma_f32 v198, v127, v198, v177
	v_mul_f32_e32 v199, v199, v127
	ds_bpermute_b32 v164, v185, v199 offset:0
	ds_bpermute_b32 v246, v185, v198 offset:0
	ds_bpermute_b32 v165, v185, v199 offset:64
	ds_bpermute_b32 v247, v185, v198 offset:64
	ds_bpermute_b32 v166, v185, v199 offset:128
	ds_bpermute_b32 v248, v185, v198 offset:128
	ds_bpermute_b32 v167, v185, v199 offset:192
	ds_bpermute_b32 v249, v185, v198 offset:192
	s_waitcnt lgkmcnt(0)
	v_mov_b32_e32 v251, v246
	v_mov_b32_e32 v250, v164
	v_fma_f32 v251, v251, v165, v247
	v_mul_f32_e32 v250, v250, v165
	v_fma_f32 v251, v251, v166, v248
	v_mul_f32_e32 v250, v250, v166
	v_fma_f32 v251, v251, v167, v249
	v_mul_f32_e32 v250, v250, v167
	s_mov_b64 exec, s[10:11]
	ds_write_b64 v182, v[250:251] offset:1024
	s_mov_b64 exec, -1
	s_waitcnt lgkmcnt(0)
	s_barrier
	ds_read2_b64 v[4:7], v183 offset0:128 offset1:144
	s_add_i32 s52, s4, 1
	s_lshl_b32 s52, s52, 12
	v_add_u32_e32 v197, s52, v184
	s_waitcnt lgkmcnt(0)
	v_fma_f32 v198, v180, v4, v5
	v_cndmask_b32_e64 v199, v180, v198, s[24:25]
	v_fma_f32 v180, v198, v6, v7
	v_fma_f32 v200, v199, v164, v246
	v_cndmask_b32_e64 v199, v199, v200, s[16:17]
	v_fma_f32 v200, v199, v165, v247
	v_cndmask_b32_e64 v199, v199, v200, s[20:21]
	v_fma_f32 v200, v199, v166, v248
	v_cndmask_b32_e64 v199, v199, v200, s[22:23]
	v_fma_f32 v214, v120, v199, v170
	v_fma_f32 v215, v121, v214, v171
	v_fma_f32 v216, v122, v215, v172
	v_fma_f32 v217, v123, v216, v173
	v_fma_f32 v218, v124, v217, v174
	v_fma_f32 v219, v125, v218, v175
	v_fma_f32 v220, v126, v219, v176
	v_fma_f32 v221, v127, v220, v177
	ds_read_u16 v206, v197 offset:0
	ds_read_u16 v207, v197 offset:64
	ds_read_u16 v208, v197 offset:128
	ds_read_u16 v209, v197 offset:192
	ds_read_u16 v210, v197 offset:256
	ds_read_u16 v211, v197 offset:320
	ds_read_u16 v212, v197 offset:384
	ds_read_u16 v213, v197 offset:448
	s_waitcnt lgkmcnt(0)
	v_lshlrev_b32_e32 v206, 16, v206
	v_lshlrev_b32_e32 v207, 16, v207
	v_lshlrev_b32_e32 v208, 16, v208
	v_lshlrev_b32_e32 v209, 16, v209
	v_lshlrev_b32_e32 v210, 16, v210
	v_lshlrev_b32_e32 v211, 16, v211
	v_lshlrev_b32_e32 v212, 16, v212
	v_lshlrev_b32_e32 v213, 16, v213
	v_add_f32_e32 v214, v214, v206
	v_add_f32_e32 v215, v215, v207
	v_add_f32_e32 v216, v216, v208
	v_add_f32_e32 v217, v217, v209
	v_add_f32_e32 v218, v218, v210
	v_add_f32_e32 v219, v219, v211
	v_add_f32_e32 v220, v220, v212
	v_add_f32_e32 v221, v221, v213
	v_cvt_pk_bf16_f32 v206, v214, v215
	v_cvt_pk_bf16_f32 v208, v216, v217
	v_cvt_pk_bf16_f32 v210, v218, v219
	v_cvt_pk_bf16_f32 v212, v220, v221
	ds_write_b16 v197, v206 offset:0
	ds_write_b16_d16_hi v197, v206 offset:64
	ds_write_b16 v197, v208 offset:128
	ds_write_b16_d16_hi v197, v208 offset:192
	ds_write_b16 v197, v210 offset:256
	ds_write_b16_d16_hi v197, v210 offset:320
	ds_write_b16 v197, v212 offset:384
	ds_write_b16_d16_hi v197, v212 offset:448
	s_add_i32 s4, s4, 2
	s_cmp_lt_u32 s4, 32
	s_cbranch_scc1 .Lrec2_loopB_d0
	s_waitcnt lgkmcnt(0)
	s_barrier
	s_add_i32 s64, s4, -1
	s_mul_i32 s71, s64, 0x30000
	s_add_u32 s38, s60, s71
	s_addc_u32 s39, s61, 0
	s_lshl_b32 s64, s64, 12
	v_add_u32_e32 v136, s64, v195
	ds_read_b128 v[116:119], v136
	s_waitcnt vmcnt(3)
	s_waitcnt lgkmcnt(0)
	v_lshlrev_b32_e32 v136, 16, v116
	v_lshlrev_b32_e32 v137, 16, v8
	v_and_b32_e32 v168, 0xffff0000, v116
	v_and_b32_e32 v169, 0xffff0000, v8
	v_mul_f32_e32 v136, v136, v137
	v_mul_f32_e32 v168, v168, v169
	v_cvt_pk_bf16_f32 v116, v136, v168
	v_lshlrev_b32_e32 v136, 16, v117
	v_lshlrev_b32_e32 v137, 16, v9
	v_and_b32_e32 v168, 0xffff0000, v117
	v_and_b32_e32 v169, 0xffff0000, v9
	v_mul_f32_e32 v136, v136, v137
	v_mul_f32_e32 v168, v168, v169
	v_cvt_pk_bf16_f32 v117, v136, v168
	v_lshlrev_b32_e32 v136, 16, v118
	v_lshlrev_b32_e32 v137, 16, v10
	v_and_b32_e32 v168, 0xffff0000, v118
	v_and_b32_e32 v169, 0xffff0000, v10
	v_mul_f32_e32 v136, v136, v137
	v_mul_f32_e32 v168, v168, v169
	v_cvt_pk_bf16_f32 v118, v136, v168
	v_lshlrev_b32_e32 v136, 16, v119
	v_lshlrev_b32_e32 v137, 16, v11
	v_and_b32_e32 v168, 0xffff0000, v119
	v_and_b32_e32 v169, 0xffff0000, v11
	v_mul_f32_e32 v136, v136, v137
	v_mul_f32_e32 v168, v168, v169
	v_cvt_pk_bf16_f32 v119, v136, v168
	global_store_dwordx4 v255, v[116:119], s[38:39]
	s_barrier
	s_branch .Lrec2_done
.Lrec2_bwd:
	v_and_b32_e32 v252, 15, v157
	v_lshrrev_b32_e32 v253, 4, v157
	s_bfe_u32 s5, s85, 0x10006
	s_bfe_u32 s6, s85, 0x10007
	s_and_b32 s8, s84, 1
	v_readlane_b32 s26, v254, 13
	v_readlane_b32 s27, v254, 14
	s_nop 3
	s_lshl_b32 s9, s70, 2
	s_add_i32 s9, s9, 2
	s_lshl_b32 s52, s9, 15
	s_add_u32 s26, s26, 0x100000
	s_addc_u32 s27, s27, 0
	s_add_u32 s26, s26, s52
	s_addc_u32 s27, s27, 0
	v_add_u32_e32 v8, s34, v252
	v_lshlrev_b32_e32 v9, 7, v8
	v_lshl_add_u32 v9, v253, 4, v9
	s_lshl_b32 s64, s8, 6
	s_xor_b32 s71, s64, 64
	v_add_u32_e32 v10, s64, v9
	v_add_u32_e32 v255, s71, v9
	s_add_u32 s38, s26, 0x0
	s_addc_u32 s39, s27, 0
	global_load_dwordx4 v[20:23], v10, s[38:39]
	global_load_dwordx4 v[24:27], v255, s[38:39]
	s_add_u32 s38, s26, 0x2000
	s_addc_u32 s39, s27, 0
	global_load_dwordx4 v[28:31], v10, s[38:39]
	global_load_dwordx4 v[32:35], v255, s[38:39]
	s_add_u32 s38, s26, 0x4000
	s_addc_u32 s39, s27, 0
	global_load_dwordx4 v[36:39], v10, s[38:39]
	global_load_dwordx4 v[40:43], v255, s[38:39]
	s_add_u32 s38, s26, 0x6000
	s_addc_u32 s39, s27, 0
	global_load_dwordx4 v[44:47], v10, s[38:39]
	global_load_dwordx4 v[48:51], v255, s[38:39]
	s_add_u32 s38, s26, 0x8000
	s_addc_u32 s39, s27, 0
	global_load_dwordx4 v[52:55], v10, s[38:39]
	global_load_dwordx4 v[56:59], v255, s[38:39]
	s_add_u32 s38, s26, 0xa000
	s_addc_u32 s39, s27, 0
	global_load_dwordx4 v[60:63], v10, s[38:39]
	global_load_dwordx4 v[64:67], v255, s[38:39]
	s_add_u32 s38, s26, 0xc000
	s_addc_u32 s39, s27, 0
	global_load_dwordx4 v[68:71], v10, s[38:39]
	global_load_dwordx4 v[72:75], v255, s[38:39]
	s_add_u32 s38, s26, 0xe000
	s_addc_u32 s39, s27, 0
	global_load_dwordx4 v[76:79], v10, s[38:39]
	global_load_dwordx4 v[80:83], v255, s[38:39]
	s_lshl_b32 s52, s9, 8
	s_add_i32 s52, s52, 0x15240
	v_lshlrev_b32_e32 v8, 2, v8
	v_add_u32_e32 v9, s52, v8
	global_load_dword v128, v9, s[90:91]
	global_load_dword v178, v9, s[90:91] offset:256
	s_lshl_b32 s52, s70, 8
	s_add_i32 s52, s52, 0x13240
	v_add_u32_e32 v9, s52, v8
	global_load_dword v179, v9, s[90:91]
	v_lshlrev_b32_e32 v198, 3, v253
	v_sub_u32_e32 v198, v252, v198
	v_lshl_add_u32 v198, s6, 4, v198
	v_cmp_gt_u32_e32 vcc, 8, v198
	v_and_b32_e32 v199, 1, v198
	v_lshlrev_b32_e32 v199, 4, v199
	v_lshrrev_b32_e32 v200, 1, v198
	s_nop 1
	v_cndmask_b32_e32 v200, 7, v200, vcc
	v_cmp_eq_u32_e64 s[58:59], 0, v200
	v_cmp_eq_u32_e64 s[60:61], 1, v200
	v_cmp_eq_u32_e64 s[98:99], 2, v200
	v_cmp_eq_u32_e64 s[100:101], 3, v200
	s_nop 1
	v_lshrrev_b32_e32 v201, 16, v184
	v_lshlrev_b32_e32 v201, v199, v201
	v_cndmask_b32_e64 v84, 0, v201, s[58:59]
	v_cndmask_b32_e64 v85, 0, v201, s[60:61]
	v_cndmask_b32_e64 v86, 0, v201, s[98:99]
	v_cndmask_b32_e64 v87, 0, v201, s[100:101]
	v_lshrrev_b32_e32 v201, 16, v185
	v_lshlrev_b32_e32 v201, v199, v201
	v_cndmask_b32_e64 v88, 0, v201, s[58:59]
	v_cndmask_b32_e64 v89, 0, v201, s[60:61]
	v_cndmask_b32_e64 v90, 0, v201, s[98:99]
	v_cndmask_b32_e64 v91, 0, v201, s[100:101]
	v_lshrrev_b32_e32 v201, 16, v195
	v_lshlrev_b32_e32 v201, v199, v201
	v_cndmask_b32_e64 v92, 0, v201, s[58:59]
	v_cndmask_b32_e64 v93, 0, v201, s[60:61]
	v_cndmask_b32_e64 v94, 0, v201, s[98:99]
	v_cndmask_b32_e64 v95, 0, v201, s[100:101]
	v_lshrrev_b32_e32 v201, 16, v197
	v_lshlrev_b32_e32 v201, v199, v201
	v_cndmask_b32_e64 v96, 0, v201, s[58:59]
	v_cndmask_b32_e64 v97, 0, v201, s[60:61]
	v_cndmask_b32_e64 v98, 0, v201, s[98:99]
	v_cndmask_b32_e64 v99, 0, v201, s[100:101]
	v_mov_b32_e32 v184, 1.0
	v_mov_b32_e32 v185, 1.0
	v_lshrrev_b32_e32 v8, 2, v252
	v_and_b32_e32 v9, 3, v252
	v_lshl_add_u32 v8, v8, 3, v9
	v_lshl_add_u32 v8, s5, 5, v8
	v_mul_u32_u24_e32 v8, 0x90, v8
	v_lshl_add_u32 v8, v253, 4, v8
	v_add_u32_e32 v8, 0x22f00, v8
	v_add_u32_e32 v130, s64, v8
	v_add_u32_e32 v131, s71, v8
	v_and_b32_e32 v8, 0xff, v156
	v_lshrrev_b32_e32 v9, 3, v8
	v_mul_u32_u24_e32 v9, 0x90, v9
	v_and_b32_e32 v10, 7, v8
	v_lshl_add_u32 v9, v10, 4, v9
	v_add_u32_e32 v134, 0x22f00, v9
	v_lshlrev_b32_e32 v154, 4, v8
	v_add_u32_e32 v155, 0x1000, v154
	v_min_u32_e32 v9, 23, v8
	v_add_u32_e32 v9, 0x200, v9
	v_lshlrev_b32_e32 v159, 4, v9
	v_lshrrev_b32_e32 v10, 3, v9
	v_mul_u32_u24_e32 v10, 0x90, v10
	v_and_b32_e32 v9, 7, v9
	v_lshl_add_u32 v10, v9, 4, v10
	v_add_u32_e32 v135, 0x22f00, v10
	s_lshl_b32 s52, s6, 8
	s_add_i32 s52, s52, 0x20300
	v_lshl_add_u32 v183, v252, 3, s52
	s_lshl_b32 s52, s5, 7
	v_add_u32_e32 v182, s52, v183
	s_lshl_b32 s52, s5, 11
	s_lshl_b32 s9, s6, 5
	s_add_i32 s52, s52, s9
	s_add_i32 s52, s52, 0x100
	v_lshlrev_b32_e32 v8, 9, v253
	v_lshl_add_u32 v8, v252, 1, v8
	v_add_u32_e32 v184, s52, v8
	v_lshlrev_b32_e32 v185, 2, v252
	s_mul_i32 s52, s69, 0x600000
	s_add_u32 s60, s30, s52
	s_addc_u32 s61, s31, 0
	s_add_i32 s52, s68, s67
	s_lshl_b32 s52, s52, 1
	s_addk_i32 s52, 0x400
	s_add_u32 s60, s60, s52
	s_addc_u32 s61, s61, 0
	v_and_b32_e32 v8, 0xff, v156
	v_lshlrev_b32_e32 v195, 4, v8
	v_add_u32_e32 v195, 0x100, v195
	v_lshrrev_b32_e32 v9, 2, v8
	v_mul_u32_u24_e32 v9, 0xc00, v9
	v_and_b32_e32 v8, 3, v8
	v_lshl_add_u32 v255, v8, 4, v9
	v_cmp_eq_u32_e64 s[10:11], 0, v253
	v_cmp_gt_u32_e64 s[16:17], 3, v253
	v_cmp_gt_u32_e64 s[20:21], 2, v253
	v_cmp_gt_u32_e64 s[22:23], 1, v253
	s_cmp_eq_u32 s5, 0
	s_cselect_b64 s[24:25], -1, 0
	v_mov_b32_e32 v180, 0
	s_add_u32 s26, s50, 0x3e000
	s_addc_u32 s27, s51, 0
	global_load_dwordx4 v[230:233], v154, s[26:27]
	global_load_dwordx4 v[234:237], v155, s[26:27]
	global_load_dwordx4 v[238:241], v159, s[26:27]
	s_add_u32 s26, s50, 0x3c000
	s_addc_u32 s27, s51, 0
	global_load_dwordx4 v[146:149], v154, s[26:27]
	global_load_dwordx4 v[150:153], v155, s[26:27]
	global_load_dwordx4 v[160:163], v159, s[26:27]
	s_waitcnt vmcnt(0)
	v_mov_b32_e32 v12, v128
	v_mov_b32_e32 v16, v178
	v_mov_b32_e32 v242, v133
	v_mov_b32_e32 v13, v128
	v_mov_b32_e32 v17, v178
	v_mov_b32_e32 v243, v133
	v_mov_b32_e32 v14, v128
	v_mov_b32_e32 v18, v178
	v_mov_b32_e32 v244, v133
	v_mov_b32_e32 v15, v128
	v_mov_b32_e32 v19, v178
	v_mov_b32_e32 v245, v133
	ds_write_b128 v134, v[230:233]
	ds_write_b128 v134, v[234:237] offset:4608
	ds_write_b128 v135, v[238:241]
	s_add_u32 s26, s50, 0x3a000
	s_addc_u32 s27, s51, 0
	global_load_dwordx4 v[230:233], v154, s[26:27]
	global_load_dwordx4 v[234:237], v155, s[26:27]
	global_load_dwordx4 v[238:241], v159, s[26:27]
	s_mov_b32 s4, 0
	s_waitcnt lgkmcnt(0)
	s_barrier
	s_barrier
.Lrec2_loopA_d1:
	ds_read_b128 v[198:201], v130 offset:0
	ds_read_b128 v[214:217], v130 offset:576
	ds_read_b128 v[202:205], v131 offset:0
	ds_read_b128 v[218:221], v131 offset:576
	ds_read_b128 v[206:209], v130 offset:144
	ds_read_b128 v[222:225], v130 offset:720
	ds_read_b128 v[210:213], v131 offset:144
	s_waitcnt lgkmcnt(14)
	ds_read_b128 v[226:229], v131 offset:720
	s_waitcnt lgkmcnt(6)
	v_mfma_f32_16x16x32_bf16 v[100:103], v[198:201], v[20:23], v[12:15]
	v_mfma_f32_16x16x32_bf16 v[104:107], v[198:201], v[52:55], v[16:19]
	v_mfma_f32_16x16x32_bf16 v[108:111], v[198:201], v[84:87], v[242:245]
	v_mfma_f32_16x16x32_bf16 v[112:115], v[214:217], v[20:23], v[12:15]
	v_mfma_f32_16x16x32_bf16 v[138:141], v[214:217], v[52:55], v[16:19]
	v_mfma_f32_16x16x32_bf16 v[142:145], v[214:217], v[84:87], v[242:245]
	s_waitcnt lgkmcnt(4)
	v_mfma_f32_16x16x32_bf16 v[100:103], v[202:205], v[24:27], v[100:103]
	v_mfma_f32_16x16x32_bf16 v[104:107], v[202:205], v[56:59], v[104:107]
	v_mfma_f32_16x16x32_bf16 v[112:115], v[218:221], v[24:27], v[112:115]
	v_mfma_f32_16x16x32_bf16 v[138:141], v[218:221], v[56:59], v[138:141]
	ds_read_b128 v[198:201], v130 offset:288
	ds_read_b128 v[214:217], v130 offset:864
	ds_read_b128 v[202:205], v131 offset:288
	ds_read_b128 v[218:221], v131 offset:864
	s_waitcnt lgkmcnt(6)
	v_mfma_f32_16x16x32_bf16 v[100:103], v[206:209], v[28:31], v[100:103]
	v_mfma_f32_16x16x32_bf16 v[104:107], v[206:209], v[60:63], v[104:107]
	v_mfma_f32_16x16x32_bf16 v[108:111], v[206:209], v[88:91], v[108:111]
	v_mfma_f32_16x16x32_bf16 v[112:115], v[222:225], v[28:31], v[112:115]
	v_mfma_f32_16x16x32_bf16 v[138:141], v[222:225], v[60:63], v[138:141]
	v_mfma_f32_16x16x32_bf16 v[142:145], v[222:225], v[88:91], v[142:145]
	s_waitcnt lgkmcnt(4)
	v_mfma_f32_16x16x32_bf16 v[100:103], v[210:213], v[32:35], v[100:103]
	v_mfma_f32_16x16x32_bf16 v[104:107], v[210:213], v[64:67], v[104:107]
	v_mfma_f32_16x16x32_bf16 v[112:115], v[226:229], v[32:35], v[112:115]
	v_mfma_f32_16x16x32_bf16 v[138:141], v[226:229], v[64:67], v[138:141]
	ds_read_b128 v[206:209], v130 offset:432
	ds_read_b128 v[222:225], v130 offset:1008
	ds_read_b128 v[210:213], v131 offset:432
	ds_read_b128 v[226:229], v131 offset:1008
	s_waitcnt lgkmcnt(6)
	v_mfma_f32_16x16x32_bf16 v[100:103], v[198:201], v[36:39], v[100:103]
	v_mfma_f32_16x16x32_bf16 v[104:107], v[198:201], v[68:71], v[104:107]
	v_mfma_f32_16x16x32_bf16 v[108:111], v[198:201], v[92:95], v[108:111]
	v_mfma_f32_16x16x32_bf16 v[112:115], v[214:217], v[36:39], v[112:115]
	v_mfma_f32_16x16x32_bf16 v[138:141], v[214:217], v[68:71], v[138:141]
	v_mfma_f32_16x16x32_bf16 v[142:145], v[214:217], v[92:95], v[142:145]
	s_waitcnt lgkmcnt(4)
	v_mfma_f32_16x16x32_bf16 v[100:103], v[202:205], v[40:43], v[100:103]
	v_mfma_f32_16x16x32_bf16 v[104:107], v[202:205], v[72:75], v[104:107]
	v_mfma_f32_16x16x32_bf16 v[112:115], v[218:221], v[40:43], v[112:115]
	v_mfma_f32_16x16x32_bf16 v[138:141], v[218:221], v[72:75], v[138:141]
	s_waitcnt lgkmcnt(2)
	v_mfma_f32_16x16x32_bf16 v[100:103], v[206:209], v[44:47], v[100:103]
	v_mfma_f32_16x16x32_bf16 v[104:107], v[206:209], v[76:79], v[104:107]
	v_mfma_f32_16x16x32_bf16 v[108:111], v[206:209], v[96:99], v[108:111]
	v_mfma_f32_16x16x32_bf16 v[112:115], v[222:225], v[44:47], v[112:115]
	v_mfma_f32_16x16x32_bf16 v[138:141], v[222:225], v[76:79], v[138:141]
	v_mfma_f32_16x16x32_bf16 v[142:145], v[222:225], v[96:99], v[142:145]
	s_waitcnt lgkmcnt(0)
	v_mfma_f32_16x16x32_bf16 v[100:103], v[210:213], v[48:51], v[100:103]
	v_mfma_f32_16x16x32_bf16 v[104:107], v[210:213], v[80:83], v[104:107]
	v_mfma_f32_16x16x32_bf16 v[112:115], v[226:229], v[48:51], v[112:115]
	v_mfma_f32_16x16x32_bf16 v[138:141], v[226:229], v[80:83], v[138:141]
	s_waitcnt lgkmcnt(0)
	s_barrier
	s_waitcnt vmcnt(3)
	ds_write_b128 v134, v[146:149]
	ds_write_b128 v134, v[150:153] offset:4608
	ds_write_b128 v135, v[160:163]
	s_add_i32 s52, s4, 3
	s_min_u32 s52, s52, 31
	s_sub_i32 s52, 31, s52
	s_lshl_b32 s52, s52, 13
	s_add_u32 s26, s50, s52
	s_addc_u32 s27, s51, 0
	global_load_dwordx4 v[146:149], v154, s[26:27]
	global_load_dwordx4 v[150:153], v155, s[26:27]
	global_load_dwordx4 v[160:163], v159, s[26:27]
	v_exp_f32_e32 v198, v100
	v_exp_f32_e32 v199, v101
	v_exp_f32_e32 v200, v102
	v_exp_f32_e32 v201, v103
	v_exp_f32_e32 v202, v112
	v_exp_f32_e32 v203, v113
	v_exp_f32_e32 v204, v114
	v_exp_f32_e32 v205, v115
	v_exp_f32_e32 v214, v104
	v_add_f32_e32 v198, 1.0, v198
	v_exp_f32_e32 v215, v105
	v_add_f32_e32 v199, 1.0, v199
	v_exp_f32_e32 v216, v106
	v_add_f32_e32 v200, 1.0, v200
	v_exp_f32_e32 v217, v107
	v_add_f32_e32 v201, 1.0, v201
	v_exp_f32_e32 v218, v138
	v_add_f32_e32 v202, 1.0, v202
	v_exp_f32_e32 v219, v139
	v_add_f32_e32 v203, 1.0, v203
	v_exp_f32_e32 v220, v140
	v_add_f32_e32 v204, 1.0, v204
	v_exp_f32_e32 v221, v141
	v_add_f32_e32 v205, 1.0, v205
	v_rcp_f32_e32 v198, v198
	v_add_f32_e32 v214, 1.0, v214
	v_rcp_f32_e32 v199, v199
	v_add_f32_e32 v215, 1.0, v215
	v_rcp_f32_e32 v200, v200
	v_add_f32_e32 v216, 1.0, v216
	v_rcp_f32_e32 v201, v201
	v_add_f32_e32 v217, 1.0, v217
	v_rcp_f32_e32 v202, v202
	v_add_f32_e32 v218, 1.0, v218
	v_rcp_f32_e32 v203, v203
	v_add_f32_e32 v219, 1.0, v219
	v_rcp_f32_e32 v204, v204
	v_add_f32_e32 v220, 1.0, v220
	v_rcp_f32_e32 v205, v205
	v_add_f32_e32 v221, 1.0, v221
	v_mul_f32_e32 v198, v179, v198
	v_mul_f32_e32 v199, v179, v199
	v_mul_f32_e32 v200, v179, v200
	v_mul_f32_e32 v201, v179, v201
	v_mul_f32_e32 v202, v179, v202
	v_mul_f32_e32 v203, v179, v203
	v_mul_f32_e32 v204, v179, v204
	v_mul_f32_e32 v205, v179, v205
	v_exp_f32_e32 v120, v198
	v_exp_f32_e32 v121, v199
	v_exp_f32_e32 v122, v200
	v_exp_f32_e32 v123, v201
	v_exp_f32_e32 v124, v202
	v_exp_f32_e32 v125, v203
	v_exp_f32_e32 v126, v204
	v_exp_f32_e32 v127, v205
	v_fma_f32 v206, -v120, v120, 1.0
	v_fma_f32 v207, -v121, v121, 1.0
	v_fma_f32 v208, -v122, v122, 1.0
	v_fma_f32 v209, -v123, v123, 1.0
	v_fma_f32 v210, -v124, v124, 1.0
	v_fma_f32 v211, -v125, v125, 1.0
	v_fma_f32 v212, -v126, v126, 1.0
	v_fma_f32 v213, -v127, v127, 1.0
	v_max_f32_e32 v206, 0xda24260, v206
	v_max_f32_e32 v207, 0xda24260, v207
	v_max_f32_e32 v208, 0xda24260, v208
	v_max_f32_e32 v209, 0xda24260, v209
	v_max_f32_e32 v210, 0xda24260, v210
	v_max_f32_e32 v211, 0xda24260, v211
	v_max_f32_e32 v212, 0xda24260, v212
	v_max_f32_e32 v213, 0xda24260, v213
	v_mul_f32_e32 v198, v214, v206
	v_mul_f32_e32 v199, v215, v207
	v_mul_f32_e32 v200, v216, v208
	v_mul_f32_e32 v201, v217, v209
	v_mul_f32_e32 v202, v218, v210
	v_mul_f32_e32 v203, v219, v211
	v_mul_f32_e32 v204, v220, v212
	v_mul_f32_e32 v205, v221, v213
	v_mul_f32_e32 v214, v214, v198
	v_mul_f32_e32 v215, v215, v199
	v_mul_f32_e32 v216, v216, v200
	v_mul_f32_e32 v217, v217, v201
	v_mul_f32_e32 v218, v218, v202
	v_mul_f32_e32 v219, v219, v203
	v_mul_f32_e32 v220, v220, v204
	v_mul_f32_e32 v221, v221, v205
	v_rsq_f32_e32 v214, v214
	v_mul_f32_e32 v222, v108, v206
	v_rsq_f32_e32 v215, v215
	v_mul_f32_e32 v223, v109, v207
	v_rsq_f32_e32 v216, v216
	v_mul_f32_e32 v224, v110, v208
	v_rsq_f32_e32 v217, v217
	v_mul_f32_e32 v225, v111, v209
	v_rsq_f32_e32 v218, v218
	v_mul_f32_e32 v226, v142, v210
	v_rsq_f32_e32 v219, v219
	v_mul_f32_e32 v227, v143, v211
	v_rsq_f32_e32 v220, v220
	v_mul_f32_e32 v228, v144, v212
	v_rsq_f32_e32 v221, v221
	v_mul_f32_e32 v229, v145, v213
	v_mul_f32_e32 v170, v222, v214
	v_mul_f32_e32 v171, v223, v215
	v_mul_f32_e32 v172, v224, v216
	v_mul_f32_e32 v173, v225, v217
	v_mul_f32_e32 v174, v226, v218
	v_mul_f32_e32 v175, v227, v219
	v_mul_f32_e32 v176, v228, v220
	v_mul_f32_e32 v177, v229, v221
	v_mov_b32_e32 v198, v177
	v_mov_b32_e32 v199, v127
	v_fma_f32 v198, v126, v198, v176
	v_mul_f32_e32 v199, v199, v126
	v_fma_f32 v198, v125, v198, v175
	v_mul_f32_e32 v199, v199, v125
	v_fma_f32 v198, v124, v198, v174
	v_mul_f32_e32 v199, v199, v124
	v_fma_f32 v198, v123, v198, v173
	v_mul_f32_e32 v199, v199, v123
	v_fma_f32 v198, v122, v198, v172
	v_mul_f32_e32 v199, v199, v122
	v_fma_f32 v198, v121, v198, v171
	v_mul_f32_e32 v199, v199, v121
	v_fma_f32 v198, v120, v198, v170
	v_mul_f32_e32 v199, v199, v120
	ds_bpermute_b32 v164, v185, v199 offset:0
	ds_bpermute_b32 v246, v185, v198 offset:0
	ds_bpermute_b32 v165, v185, v199 offset:64
	ds_bpermute_b32 v247, v185, v198 offset:64
	ds_bpermute_b32 v166, v185, v199 offset:128
	ds_bpermute_b32 v248, v185, v198 offset:128
	ds_bpermute_b32 v167, v185, v199 offset:192
	ds_bpermute_b32 v249, v185, v198 offset:192
	s_waitcnt lgkmcnt(0)
	v_mov_b32_e32 v251, v249
	v_mov_b32_e32 v250, v167
	v_fma_f32 v251, v251, v166, v248
	v_mul_f32_e32 v250, v250, v166
	v_fma_f32 v251, v251, v165, v247
	v_mul_f32_e32 v250, v250, v165
	v_fma_f32 v251, v251, v164, v246
	v_mul_f32_e32 v250, v250, v164
	s_mov_b64 exec, s[10:11]
	ds_write_b64 v182, v[250:251] offset:0
	s_mov_b64 exec, -1
	s_waitcnt lgkmcnt(0)
	s_barrier
	ds_read2_b64 v[4:7], v183 offset0:0 offset1:16
	s_add_i32 s52, s4, 0
	s_sub_i32 s52, 31, s52
	s_lshl_b32 s52, s52, 12
	v_add_u32_e32 v197, s52, v184
	s_waitcnt lgkmcnt(0)
	v_fma_f32 v198, v180, v6, v7
	v_cndmask_b32_e64 v199, v180, v198, s[24:25]
	v_fma_f32 v180, v198, v4, v5
	v_fma_f32 v200, v199, v167, v249
	v_cndmask_b32_e64 v199, v199, v200, s[16:17]
	v_fma_f32 v200, v199, v166, v248
	v_cndmask_b32_e64 v199, v199, v200, s[20:21]
	v_fma_f32 v200, v199, v165, v247
	v_cndmask_b32_e64 v199, v199, v200, s[22:23]
	v_fma_f32 v221, v127, v199, v177
	v_fma_f32 v220, v126, v221, v176
	v_fma_f32 v219, v125, v220, v175
	v_fma_f32 v218, v124, v219, v174
	v_fma_f32 v217, v123, v218, v173
	v_fma_f32 v216, v122, v217, v172
	v_fma_f32 v215, v121, v216, v171
	v_fma_f32 v214, v120, v215, v170
	v_cvt_pk_bf16_f32 v206, v214, v215
	v_cvt_pk_bf16_f32 v208, v216, v217
	v_cvt_pk_bf16_f32 v210, v218, v219
	v_cvt_pk_bf16_f32 v212, v220, v221
	ds_write_b16 v197, v206 offset:0
	ds_write_b16_d16_hi v197, v206 offset:64
	ds_write_b16 v197, v208 offset:128
	ds_write_b16_d16_hi v197, v208 offset:192
	ds_write_b16 v197, v210 offset:256
	ds_write_b16_d16_hi v197, v210 offset:320
	ds_write_b16 v197, v212 offset:384
	ds_write_b16_d16_hi v197, v212 offset:448
	ds_read_b128 v[198:201], v130 offset:0
	ds_read_b128 v[214:217], v130 offset:576
	ds_read_b128 v[202:205], v131 offset:0
	ds_read_b128 v[218:221], v131 offset:576
	ds_read_b128 v[206:209], v130 offset:144
	ds_read_b128 v[222:225], v130 offset:720
	ds_read_b128 v[210:213], v131 offset:144
	s_waitcnt lgkmcnt(14)
	ds_read_b128 v[226:229], v131 offset:720
	s_waitcnt lgkmcnt(6)
	v_mfma_f32_16x16x32_bf16 v[100:103], v[198:201], v[20:23], v[12:15]
	v_mfma_f32_16x16x32_bf16 v[104:107], v[198:201], v[52:55], v[16:19]
	v_mfma_f32_16x16x32_bf16 v[108:111], v[198:201], v[84:87], v[242:245]
	v_mfma_f32_16x16x32_bf16 v[112:115], v[214:217], v[20:23], v[12:15]
	v_mfma_f32_16x16x32_bf16 v[138:141], v[214:217], v[52:55], v[16:19]
	v_mfma_f32_16x16x32_bf16 v[142:145], v[214:217], v[84:87], v[242:245]
	s_waitcnt lgkmcnt(4)
	v_mfma_f32_16x16x32_bf16 v[100:103], v[202:205], v[24:27], v[100:103]
	v_mfma_f32_16x16x32_bf16 v[104:107], v[202:205], v[56:59], v[104:107]
	v_mfma_f32_16x16x32_bf16 v[112:115], v[218:221], v[24:27], v[112:115]
	v_mfma_f32_16x16x32_bf16 v[138:141], v[218:221], v[56:59], v[138:141]
	ds_read_b128 v[198:201], v130 offset:288
	ds_read_b128 v[214:217], v130 offset:864
	ds_read_b128 v[202:205], v131 offset:288
	ds_read_b128 v[218:221], v131 offset:864
	s_waitcnt lgkmcnt(6)
	v_mfma_f32_16x16x32_bf16 v[100:103], v[206:209], v[28:31], v[100:103]
	v_mfma_f32_16x16x32_bf16 v[104:107], v[206:209], v[60:63], v[104:107]
	v_mfma_f32_16x16x32_bf16 v[108:111], v[206:209], v[88:91], v[108:111]
	v_mfma_f32_16x16x32_bf16 v[112:115], v[222:225], v[28:31], v[112:115]
	v_mfma_f32_16x16x32_bf16 v[138:141], v[222:225], v[60:63], v[138:141]
	v_mfma_f32_16x16x32_bf16 v[142:145], v[222:225], v[88:91], v[142:145]
	s_waitcnt lgkmcnt(4)
	v_mfma_f32_16x16x32_bf16 v[100:103], v[210:213], v[32:35], v[100:103]
	v_mfma_f32_16x16x32_bf16 v[104:107], v[210:213], v[64:67], v[104:107]
	v_mfma_f32_16x16x32_bf16 v[112:115], v[226:229], v[32:35], v[112:115]
	v_mfma_f32_16x16x32_bf16 v[138:141], v[226:229], v[64:67], v[138:141]
	ds_read_b128 v[206:209], v130 offset:432
	ds_read_b128 v[222:225], v130 offset:1008
	ds_read_b128 v[210:213], v131 offset:432
	ds_read_b128 v[226:229], v131 offset:1008
	s_waitcnt lgkmcnt(6)
	v_mfma_f32_16x16x32_bf16 v[100:103], v[198:201], v[36:39], v[100:103]
	v_mfma_f32_16x16x32_bf16 v[104:107], v[198:201], v[68:71], v[104:107]
	v_mfma_f32_16x16x32_bf16 v[108:111], v[198:201], v[92:95], v[108:111]
	v_mfma_f32_16x16x32_bf16 v[112:115], v[214:217], v[36:39], v[112:115]
	v_mfma_f32_16x16x32_bf16 v[138:141], v[214:217], v[68:71], v[138:141]
	v_mfma_f32_16x16x32_bf16 v[142:145], v[214:217], v[92:95], v[142:145]
	s_waitcnt lgkmcnt(4)
	v_mfma_f32_16x16x32_bf16 v[100:103], v[202:205], v[40:43], v[100:103]
	v_mfma_f32_16x16x32_bf16 v[104:107], v[202:205], v[72:75], v[104:107]
	v_mfma_f32_16x16x32_bf16 v[112:115], v[218:221], v[40:43], v[112:115]
	v_mfma_f32_16x16x32_bf16 v[138:141], v[218:221], v[72:75], v[138:141]
	s_waitcnt lgkmcnt(2)
	v_mfma_f32_16x16x32_bf16 v[100:103], v[206:209], v[44:47], v[100:103]
	v_mfma_f32_16x16x32_bf16 v[104:107], v[206:209], v[76:79], v[104:107]
	v_mfma_f32_16x16x32_bf16 v[108:111], v[206:209], v[96:99], v[108:111]
	v_mfma_f32_16x16x32_bf16 v[112:115], v[222:225], v[44:47], v[112:115]
	v_mfma_f32_16x16x32_bf16 v[138:141], v[222:225], v[76:79], v[138:141]
	v_mfma_f32_16x16x32_bf16 v[142:145], v[222:225], v[96:99], v[142:145]
	s_waitcnt lgkmcnt(0)
	v_mfma_f32_16x16x32_bf16 v[100:103], v[210:213], v[48:51], v[100:103]
	v_mfma_f32_16x16x32_bf16 v[104:107], v[210:213], v[80:83], v[104:107]
	v_mfma_f32_16x16x32_bf16 v[112:115], v[226:229], v[48:51], v[112:115]
	v_mfma_f32_16x16x32_bf16 v[138:141], v[226:229], v[80:83], v[138:141]
	s_waitcnt lgkmcnt(0)
	s_barrier
	s_waitcnt vmcnt(3)
	ds_write_b128 v134, v[230:233]
	ds_write_b128 v134, v[234:237] offset:4608
	ds_write_b128 v135, v[238:241]
	s_add_i32 s52, s4, 4
	s_min_u32 s52, s52, 31
	s_sub_i32 s52, 31, s52
	s_lshl_b32 s52, s52, 13
	s_add_u32 s26, s50, s52
	s_addc_u32 s27, s51, 0
	global_load_dwordx4 v[230:233], v154, s[26:27]
	global_load_dwordx4 v[234:237], v155, s[26:27]
	global_load_dwordx4 v[238:241], v159, s[26:27]
	v_exp_f32_e32 v198, v100
	v_exp_f32_e32 v199, v101
	v_exp_f32_e32 v200, v102
	v_exp_f32_e32 v201, v103
	v_exp_f32_e32 v202, v112
	v_exp_f32_e32 v203, v113
	v_exp_f32_e32 v204, v114
	v_exp_f32_e32 v205, v115
	v_exp_f32_e32 v214, v104
	v_add_f32_e32 v198, 1.0, v198
	v_exp_f32_e32 v215, v105
	v_add_f32_e32 v199, 1.0, v199
	v_exp_f32_e32 v216, v106
	v_add_f32_e32 v200, 1.0, v200
	v_exp_f32_e32 v217, v107
	v_add_f32_e32 v201, 1.0, v201
	v_exp_f32_e32 v218, v138
	v_add_f32_e32 v202, 1.0, v202
	v_exp_f32_e32 v219, v139
	v_add_f32_e32 v203, 1.0, v203
	v_exp_f32_e32 v220, v140
	v_add_f32_e32 v204, 1.0, v204
	v_exp_f32_e32 v221, v141
	v_add_f32_e32 v205, 1.0, v205
	v_rcp_f32_e32 v198, v198
	v_add_f32_e32 v214, 1.0, v214
	v_rcp_f32_e32 v199, v199
	v_add_f32_e32 v215, 1.0, v215
	v_rcp_f32_e32 v200, v200
	v_add_f32_e32 v216, 1.0, v216
	v_rcp_f32_e32 v201, v201
	v_add_f32_e32 v217, 1.0, v217
	v_rcp_f32_e32 v202, v202
	v_add_f32_e32 v218, 1.0, v218
	v_rcp_f32_e32 v203, v203
	v_add_f32_e32 v219, 1.0, v219
	v_rcp_f32_e32 v204, v204
	v_add_f32_e32 v220, 1.0, v220
	v_rcp_f32_e32 v205, v205
	v_add_f32_e32 v221, 1.0, v221
	v_mul_f32_e32 v198, v179, v198
	v_mul_f32_e32 v199, v179, v199
	v_mul_f32_e32 v200, v179, v200
	v_mul_f32_e32 v201, v179, v201
	v_mul_f32_e32 v202, v179, v202
	v_mul_f32_e32 v203, v179, v203
	v_mul_f32_e32 v204, v179, v204
	v_mul_f32_e32 v205, v179, v205
	v_exp_f32_e32 v120, v198
	v_exp_f32_e32 v121, v199
	v_exp_f32_e32 v122, v200
	v_exp_f32_e32 v123, v201
	v_exp_f32_e32 v124, v202
	v_exp_f32_e32 v125, v203
	v_exp_f32_e32 v126, v204
	v_exp_f32_e32 v127, v205
	v_fma_f32 v206, -v120, v120, 1.0
	v_fma_f32 v207, -v121, v121, 1.0
	v_fma_f32 v208, -v122, v122, 1.0
	v_fma_f32 v209, -v123, v123, 1.0
	v_fma_f32 v210, -v124, v124, 1.0
	v_fma_f32 v211, -v125, v125, 1.0
	v_fma_f32 v212, -v126, v126, 1.0
	v_fma_f32 v213, -v127, v127, 1.0
	v_max_f32_e32 v206, 0xda24260, v206
	v_max_f32_e32 v207, 0xda24260, v207
	v_max_f32_e32 v208, 0xda24260, v208
	v_max_f32_e32 v209, 0xda24260, v209
	v_max_f32_e32 v210, 0xda24260, v210
	v_max_f32_e32 v211, 0xda24260, v211
	v_max_f32_e32 v212, 0xda24260, v212
	v_max_f32_e32 v213, 0xda24260, v213
	v_mul_f32_e32 v198, v214, v206
	v_mul_f32_e32 v199, v215, v207
	v_mul_f32_e32 v200, v216, v208
	v_mul_f32_e32 v201, v217, v209
	v_mul_f32_e32 v202, v218, v210
	v_mul_f32_e32 v203, v219, v211
	v_mul_f32_e32 v204, v220, v212
	v_mul_f32_e32 v205, v221, v213
	v_mul_f32_e32 v214, v214, v198
	v_mul_f32_e32 v215, v215, v199
	v_mul_f32_e32 v216, v216, v200
	v_mul_f32_e32 v217, v217, v201
	v_mul_f32_e32 v218, v218, v202
	v_mul_f32_e32 v219, v219, v203
	v_mul_f32_e32 v220, v220, v204
	v_mul_f32_e32 v221, v221, v205
	v_rsq_f32_e32 v214, v214
	v_mul_f32_e32 v222, v108, v206
	v_rsq_f32_e32 v215, v215
	v_mul_f32_e32 v223, v109, v207
	v_rsq_f32_e32 v216, v216
	v_mul_f32_e32 v224, v110, v208
	v_rsq_f32_e32 v217, v217
	v_mul_f32_e32 v225, v111, v209
	v_rsq_f32_e32 v218, v218
	v_mul_f32_e32 v226, v142, v210
	v_rsq_f32_e32 v219, v219
	v_mul_f32_e32 v227, v143, v211
	v_rsq_f32_e32 v220, v220
	v_mul_f32_e32 v228, v144, v212
	v_rsq_f32_e32 v221, v221
	v_mul_f32_e32 v229, v145, v213
	v_mul_f32_e32 v170, v222, v214
	v_mul_f32_e32 v171, v223, v215
	v_mul_f32_e32 v172, v224, v216
	v_mul_f32_e32 v173, v225, v217
	v_mul_f32_e32 v174, v226, v218
	v_mul_f32_e32 v175, v227, v219
	v_mul_f32_e32 v176, v228, v220
	v_mul_f32_e32 v177, v229, v221
	v_mov_b32_e32 v198, v177
	v_mov_b32_e32 v199, v127
	v_fma_f32 v198, v126, v198, v176
	v_mul_f32_e32 v199, v199, v126
	v_fma_f32 v198, v125, v198, v175
	v_mul_f32_e32 v199, v199, v125
	v_fma_f32 v198, v124, v198, v174
	v_mul_f32_e32 v199, v199, v124
	v_fma_f32 v198, v123, v198, v173
	v_mul_f32_e32 v199, v199, v123
	v_fma_f32 v198, v122, v198, v172
	v_mul_f32_e32 v199, v199, v122
	v_fma_f32 v198, v121, v198, v171
	v_mul_f32_e32 v199, v199, v121
	v_fma_f32 v198, v120, v198, v170
	v_mul_f32_e32 v199, v199, v120
	ds_bpermute_b32 v164, v185, v199 offset:0
	ds_bpermute_b32 v246, v185, v198 offset:0
	ds_bpermute_b32 v165, v185, v199 offset:64
	ds_bpermute_b32 v247, v185, v198 offset:64
	ds_bpermute_b32 v166, v185, v199 offset:128
	ds_bpermute_b32 v248, v185, v198 offset:128
	ds_bpermute_b32 v167, v185, v199 offset:192
	ds_bpermute_b32 v249, v185, v198 offset:192
	s_waitcnt lgkmcnt(0)
	v_mov_b32_e32 v251, v249
	v_mov_b32_e32 v250, v167
	v_fma_f32 v251, v251, v166, v248
	v_mul_f32_e32 v250, v250, v166
	v_fma_f32 v251, v251, v165, v247
	v_mul_f32_e32 v250, v250, v165
	v_fma_f32 v251, v251, v164, v246
	v_mul_f32_e32 v250, v250, v164
	s_mov_b64 exec, s[10:11]
	ds_write_b64 v182, v[250:251] offset:1024
	s_mov_b64 exec, -1
	s_waitcnt lgkmcnt(0)
	s_barrier
	ds_read2_b64 v[4:7], v183 offset0:128 offset1:144
	s_add_i32 s52, s4, 1
	s_sub_i32 s52, 31, s52
	s_lshl_b32 s52, s52, 12
	v_add_u32_e32 v197, s52, v184
	s_waitcnt lgkmcnt(0)
	v_fma_f32 v198, v180, v6, v7
	v_cndmask_b32_e64 v199, v180, v198, s[24:25]
	v_fma_f32 v180, v198, v4, v5
	v_fma_f32 v200, v199, v167, v249
	v_cndmask_b32_e64 v199, v199, v200, s[16:17]
	v_fma_f32 v200, v199, v166, v248
	v_cndmask_b32_e64 v199, v199, v200, s[20:21]
	v_fma_f32 v200, v199, v165, v247
	v_cndmask_b32_e64 v199, v199, v200, s[22:23]
	v_fma_f32 v221, v127, v199, v177
	v_fma_f32 v220, v126, v221, v176
	v_fma_f32 v219, v125, v220, v175
	v_fma_f32 v218, v124, v219, v174
	v_fma_f32 v217, v123, v218, v173
	v_fma_f32 v216, v122, v217, v172
	v_fma_f32 v215, v121, v216, v171
	v_fma_f32 v214, v120, v215, v170
	v_cvt_pk_bf16_f32 v206, v214, v215
	v_cvt_pk_bf16_f32 v208, v216, v217
	v_cvt_pk_bf16_f32 v210, v218, v219
	v_cvt_pk_bf16_f32 v212, v220, v221
	ds_write_b16 v197, v206 offset:0
	ds_write_b16_d16_hi v197, v206 offset:64
	ds_write_b16 v197, v208 offset:128
	ds_write_b16_d16_hi v197, v208 offset:192
	ds_write_b16 v197, v210 offset:256
	ds_write_b16_d16_hi v197, v210 offset:320
	ds_write_b16 v197, v212 offset:384
	ds_write_b16_d16_hi v197, v212 offset:448
	s_add_i32 s4, s4, 2
	s_cmp_lt_u32 s4, 16
	s_cbranch_scc1 .Lrec2_loopA_d1
	ds_read_b128 v[198:201], v130 offset:0
	ds_read_b128 v[214:217], v130 offset:576
	ds_read_b128 v[202:205], v131 offset:0
	ds_read_b128 v[218:221], v131 offset:576
	ds_read_b128 v[206:209], v130 offset:144
	ds_read_b128 v[222:225], v130 offset:720
	ds_read_b128 v[210:213], v131 offset:144
	s_waitcnt lgkmcnt(14)
	ds_read_b128 v[226:229], v131 offset:720
	s_waitcnt lgkmcnt(6)
	v_mfma_f32_16x16x32_bf16 v[100:103], v[198:201], v[20:23], v[12:15]
	v_mfma_f32_16x16x32_bf16 v[104:107], v[198:201], v[52:55], v[16:19]
	v_mfma_f32_16x16x32_bf16 v[108:111], v[198:201], v[84:87], v[242:245]
	v_mfma_f32_16x16x32_bf16 v[112:115], v[214:217], v[20:23], v[12:15]
	v_mfma_f32_16x16x32_bf16 v[138:141], v[214:217], v[52:55], v[16:19]
	v_mfma_f32_16x16x32_bf16 v[142:145], v[214:217], v[84:87], v[242:245]
	s_waitcnt lgkmcnt(4)
	v_mfma_f32_16x16x32_bf16 v[100:103], v[202:205], v[24:27], v[100:103]
	v_mfma_f32_16x16x32_bf16 v[104:107], v[202:205], v[56:59], v[104:107]
	v_mfma_f32_16x16x32_bf16 v[112:115], v[218:221], v[24:27], v[112:115]
	v_mfma_f32_16x16x32_bf16 v[138:141], v[218:221], v[56:59], v[138:141]
	ds_read_b128 v[198:201], v130 offset:288
	ds_read_b128 v[214:217], v130 offset:864
	ds_read_b128 v[202:205], v131 offset:288
	ds_read_b128 v[218:221], v131 offset:864
	s_waitcnt lgkmcnt(6)
	v_mfma_f32_16x16x32_bf16 v[100:103], v[206:209], v[28:31], v[100:103]
	v_mfma_f32_16x16x32_bf16 v[104:107], v[206:209], v[60:63], v[104:107]
	v_mfma_f32_16x16x32_bf16 v[108:111], v[206:209], v[88:91], v[108:111]
	v_mfma_f32_16x16x32_bf16 v[112:115], v[222:225], v[28:31], v[112:115]
	v_mfma_f32_16x16x32_bf16 v[138:141], v[222:225], v[60:63], v[138:141]
	v_mfma_f32_16x16x32_bf16 v[142:145], v[222:225], v[88:91], v[142:145]
	s_waitcnt lgkmcnt(4)
	v_mfma_f32_16x16x32_bf16 v[100:103], v[210:213], v[32:35], v[100:103]
	v_mfma_f32_16x16x32_bf16 v[104:107], v[210:213], v[64:67], v[104:107]
	v_mfma_f32_16x16x32_bf16 v[112:115], v[226:229], v[32:35], v[112:115]
	v_mfma_f32_16x16x32_bf16 v[138:141], v[226:229], v[64:67], v[138:141]
	ds_read_b128 v[206:209], v130 offset:432
	ds_read_b128 v[222:225], v130 offset:1008
	ds_read_b128 v[210:213], v131 offset:432
	ds_read_b128 v[226:229], v131 offset:1008
	s_waitcnt lgkmcnt(6)
	v_mfma_f32_16x16x32_bf16 v[100:103], v[198:201], v[36:39], v[100:103]
	v_mfma_f32_16x16x32_bf16 v[104:107], v[198:201], v[68:71], v[104:107]
	v_mfma_f32_16x16x32_bf16 v[108:111], v[198:201], v[92:95], v[108:111]
	v_mfma_f32_16x16x32_bf16 v[112:115], v[214:217], v[36:39], v[112:115]
	v_mfma_f32_16x16x32_bf16 v[138:141], v[214:217], v[68:71], v[138:141]
	v_mfma_f32_16x16x32_bf16 v[142:145], v[214:217], v[92:95], v[142:145]
	s_waitcnt lgkmcnt(4)
	v_mfma_f32_16x16x32_bf16 v[100:103], v[202:205], v[40:43], v[100:103]
	v_mfma_f32_16x16x32_bf16 v[104:107], v[202:205], v[72:75], v[104:107]
	v_mfma_f32_16x16x32_bf16 v[112:115], v[218:221], v[40:43], v[112:115]
	v_mfma_f32_16x16x32_bf16 v[138:141], v[218:221], v[72:75], v[138:141]
	s_waitcnt lgkmcnt(2)
	v_mfma_f32_16x16x32_bf16 v[100:103], v[206:209], v[44:47], v[100:103]
	v_mfma_f32_16x16x32_bf16 v[104:107], v[206:209], v[76:79], v[104:107]
	v_mfma_f32_16x16x32_bf16 v[108:111], v[206:209], v[96:99], v[108:111]
	v_mfma_f32_16x16x32_bf16 v[112:115], v[222:225], v[44:47], v[112:115]
	v_mfma_f32_16x16x32_bf16 v[138:141], v[222:225], v[76:79], v[138:141]
	v_mfma_f32_16x16x32_bf16 v[142:145], v[222:225], v[96:99], v[142:145]
	s_waitcnt lgkmcnt(0)
	v_mfma_f32_16x16x32_bf16 v[100:103], v[210:213], v[48:51], v[100:103]
	v_mfma_f32_16x16x32_bf16 v[104:107], v[210:213], v[80:83], v[104:107]
	v_mfma_f32_16x16x32_bf16 v[112:115], v[226:229], v[48:51], v[112:115]
	v_mfma_f32_16x16x32_bf16 v[138:141], v[226:229], v[80:83], v[138:141]
	s_waitcnt lgkmcnt(0)
	s_barrier
	s_waitcnt vmcnt(3)
	ds_write_b128 v134, v[146:149]
	ds_write_b128 v134, v[150:153] offset:4608
	ds_write_b128 v135, v[160:163]
	s_add_i32 s64, s4, 0
	s_sub_i32 s64, 31, s64
	s_mul_i32 s71, s64, 0x30000
	s_add_u32 s38, s60, s71
	s_addc_u32 s39, s61, 0
	s_lshl_b32 s64, s64, 12
	global_load_dwordx4 v[8:11], v255, s[38:39]
	s_add_i32 s52, s4, 3
	s_min_u32 s52, s52, 31
	s_sub_i32 s52, 31, s52
	s_lshl_b32 s52, s52, 13
	s_add_u32 s26, s50, s52
	s_addc_u32 s27, s51, 0
	global_load_dwordx4 v[146:149], v154, s[26:27]
	global_load_dwordx4 v[150:153], v155, s[26:27]
	global_load_dwordx4 v[160:163], v159, s[26:27]
	v_exp_f32_e32 v198, v100
	v_exp_f32_e32 v199, v101
	v_exp_f32_e32 v200, v102
	v_exp_f32_e32 v201, v103
	v_exp_f32_e32 v202, v112
	v_exp_f32_e32 v203, v113
	v_exp_f32_e32 v204, v114
	v_exp_f32_e32 v205, v115
	v_exp_f32_e32 v214, v104
	v_add_f32_e32 v198, 1.0, v198
	v_exp_f32_e32 v215, v105
	v_add_f32_e32 v199, 1.0, v199
	v_exp_f32_e32 v216, v106
	v_add_f32_e32 v200, 1.0, v200
	v_exp_f32_e32 v217, v107
	v_add_f32_e32 v201, 1.0, v201
	v_exp_f32_e32 v218, v138
	v_add_f32_e32 v202, 1.0, v202
	v_exp_f32_e32 v219, v139
	v_add_f32_e32 v203, 1.0, v203
	v_exp_f32_e32 v220, v140
	v_add_f32_e32 v204, 1.0, v204
	v_exp_f32_e32 v221, v141
	v_add_f32_e32 v205, 1.0, v205
	v_rcp_f32_e32 v198, v198
	v_add_f32_e32 v214, 1.0, v214
	v_rcp_f32_e32 v199, v199
	v_add_f32_e32 v215, 1.0, v215
	v_rcp_f32_e32 v200, v200
	v_add_f32_e32 v216, 1.0, v216
	v_rcp_f32_e32 v201, v201
	v_add_f32_e32 v217, 1.0, v217
	v_rcp_f32_e32 v202, v202
	v_add_f32_e32 v218, 1.0, v218
	v_rcp_f32_e32 v203, v203
	v_add_f32_e32 v219, 1.0, v219
	v_rcp_f32_e32 v204, v204
	v_add_f32_e32 v220, 1.0, v220
	v_rcp_f32_e32 v205, v205
	v_add_f32_e32 v221, 1.0, v221
	v_mul_f32_e32 v198, v179, v198
	v_mul_f32_e32 v199, v179, v199
	v_mul_f32_e32 v200, v179, v200
	v_mul_f32_e32 v201, v179, v201
	v_mul_f32_e32 v202, v179, v202
	v_mul_f32_e32 v203, v179, v203
	v_mul_f32_e32 v204, v179, v204
	v_mul_f32_e32 v205, v179, v205
	v_exp_f32_e32 v120, v198
	v_exp_f32_e32 v121, v199
	v_exp_f32_e32 v122, v200
	v_exp_f32_e32 v123, v201
	v_exp_f32_e32 v124, v202
	v_exp_f32_e32 v125, v203
	v_exp_f32_e32 v126, v204
	v_exp_f32_e32 v127, v205
	v_fma_f32 v206, -v120, v120, 1.0
	v_fma_f32 v207, -v121, v121, 1.0
	v_fma_f32 v208, -v122, v122, 1.0
	v_fma_f32 v209, -v123, v123, 1.0
	v_fma_f32 v210, -v124, v124, 1.0
	v_fma_f32 v211, -v125, v125, 1.0
	v_fma_f32 v212, -v126, v126, 1.0
	v_fma_f32 v213, -v127, v127, 1.0
	v_max_f32_e32 v206, 0xda24260, v206
	v_max_f32_e32 v207, 0xda24260, v207
	v_max_f32_e32 v208, 0xda24260, v208
	v_max_f32_e32 v209, 0xda24260, v209
	v_max_f32_e32 v210, 0xda24260, v210
	v_max_f32_e32 v211, 0xda24260, v211
	v_max_f32_e32 v212, 0xda24260, v212
	v_max_f32_e32 v213, 0xda24260, v213
	v_mul_f32_e32 v198, v214, v206
	v_mul_f32_e32 v199, v215, v207
	v_mul_f32_e32 v200, v216, v208
	v_mul_f32_e32 v201, v217, v209
	v_mul_f32_e32 v202, v218, v210
	v_mul_f32_e32 v203, v219, v211
	v_mul_f32_e32 v204, v220, v212
	v_mul_f32_e32 v205, v221, v213
	v_mul_f32_e32 v214, v214, v198
	v_mul_f32_e32 v215, v215, v199
	v_mul_f32_e32 v216, v216, v200
	v_mul_f32_e32 v217, v217, v201
	v_mul_f32_e32 v218, v218, v202
	v_mul_f32_e32 v219, v219, v203
	v_mul_f32_e32 v220, v220, v204
	v_mul_f32_e32 v221, v221, v205
	v_rsq_f32_e32 v214, v214
	v_mul_f32_e32 v222, v108, v206
	v_rsq_f32_e32 v215, v215
	v_mul_f32_e32 v223, v109, v207
	v_rsq_f32_e32 v216, v216
	v_mul_f32_e32 v224, v110, v208
	v_rsq_f32_e32 v217, v217
	v_mul_f32_e32 v225, v111, v209
	v_rsq_f32_e32 v218, v218
	v_mul_f32_e32 v226, v142, v210
	v_rsq_f32_e32 v219, v219
	v_mul_f32_e32 v227, v143, v211
	v_rsq_f32_e32 v220, v220
	v_mul_f32_e32 v228, v144, v212
	v_rsq_f32_e32 v221, v221
	v_mul_f32_e32 v229, v145, v213
	v_mul_f32_e32 v170, v222, v214
	v_mul_f32_e32 v171, v223, v215
	v_mul_f32_e32 v172, v224, v216
	v_mul_f32_e32 v173, v225, v217
	v_mul_f32_e32 v174, v226, v218
	v_mul_f32_e32 v175, v227, v219
	v_mul_f32_e32 v176, v228, v220
	v_mul_f32_e32 v177, v229, v221
	v_mov_b32_e32 v198, v177
	v_mov_b32_e32 v199, v127
	v_fma_f32 v198, v126, v198, v176
	v_mul_f32_e32 v199, v199, v126
	v_fma_f32 v198, v125, v198, v175
	v_mul_f32_e32 v199, v199, v125
	v_fma_f32 v198, v124, v198, v174
	v_mul_f32_e32 v199, v199, v124
	v_fma_f32 v198, v123, v198, v173
	v_mul_f32_e32 v199, v199, v123
	v_fma_f32 v198, v122, v198, v172
	v_mul_f32_e32 v199, v199, v122
	v_fma_f32 v198, v121, v198, v171
	v_mul_f32_e32 v199, v199, v121
	v_fma_f32 v198, v120, v198, v170
	v_mul_f32_e32 v199, v199, v120
	ds_bpermute_b32 v164, v185, v199 offset:0
	ds_bpermute_b32 v246, v185, v198 offset:0
	ds_bpermute_b32 v165, v185, v199 offset:64
	ds_bpermute_b32 v247, v185, v198 offset:64
	ds_bpermute_b32 v166, v185, v199 offset:128
	ds_bpermute_b32 v248, v185, v198 offset:128
	ds_bpermute_b32 v167, v185, v199 offset:192
	ds_bpermute_b32 v249, v185, v198 offset:192
	s_waitcnt lgkmcnt(0)
	v_mov_b32_e32 v251, v249
	v_mov_b32_e32 v250, v167
	v_fma_f32 v251, v251, v166, v248
	v_mul_f32_e32 v250, v250, v166
	v_fma_f32 v251, v251, v165, v247
	v_mul_f32_e32 v250, v250, v165
	v_fma_f32 v251, v251, v164, v246
	v_mul_f32_e32 v250, v250, v164
	s_mov_b64 exec, s[10:11]
	ds_write_b64 v182, v[250:251] offset:0
	s_mov_b64 exec, -1
	s_waitcnt lgkmcnt(0)
	s_barrier
	ds_read2_b64 v[4:7], v183 offset0:0 offset1:16
	s_add_i32 s52, s4, 0
	s_sub_i32 s52, 31, s52
	s_lshl_b32 s52, s52, 12
	v_add_u32_e32 v197, s52, v184
	s_waitcnt lgkmcnt(0)
	v_fma_f32 v198, v180, v6, v7
	v_cndmask_b32_e64 v199, v180, v198, s[24:25]
	v_fma_f32 v180, v198, v4, v5
	v_fma_f32 v200, v199, v167, v249
	v_cndmask_b32_e64 v199, v199, v200, s[16:17]
	v_fma_f32 v200, v199, v166, v248
	v_cndmask_b32_e64 v199, v199, v200, s[20:21]
	v_fma_f32 v200, v199, v165, v247
	v_cndmask_b32_e64 v199, v199, v200, s[22:23]
	v_fma_f32 v221, v127, v199, v177
	v_fma_f32 v220, v126, v221, v176
	v_fma_f32 v219, v125, v220, v175
	v_fma_f32 v218, v124, v219, v174
	v_fma_f32 v217, v123, v218, v173
	v_fma_f32 v216, v122, v217, v172
	v_fma_f32 v215, v121, v216, v171
	v_fma_f32 v214, v120, v215, v170
	ds_read_u16 v206, v197 offset:0
	ds_read_u16 v207, v197 offset:64
	ds_read_u16 v208, v197 offset:128
	ds_read_u16 v209, v197 offset:192
	ds_read_u16 v210, v197 offset:256
	ds_read_u16 v211, v197 offset:320
	ds_read_u16 v212, v197 offset:384
	ds_read_u16 v213, v197 offset:448
	s_waitcnt lgkmcnt(0)
	v_lshlrev_b32_e32 v206, 16, v206
	v_lshlrev_b32_e32 v207, 16, v207
	v_lshlrev_b32_e32 v208, 16, v208
	v_lshlrev_b32_e32 v209, 16, v209
	v_lshlrev_b32_e32 v210, 16, v210
	v_lshlrev_b32_e32 v211, 16, v211
	v_lshlrev_b32_e32 v212, 16, v212
	v_lshlrev_b32_e32 v213, 16, v213
	v_add_f32_e32 v214, v214, v206
	v_add_f32_e32 v215, v215, v207
	v_add_f32_e32 v216, v216, v208
	v_add_f32_e32 v217, v217, v209
	v_add_f32_e32 v218, v218, v210
	v_add_f32_e32 v219, v219, v211
	v_add_f32_e32 v220, v220, v212
	v_add_f32_e32 v221, v221, v213
	v_cvt_pk_bf16_f32 v206, v214, v215
	v_cvt_pk_bf16_f32 v208, v216, v217
	v_cvt_pk_bf16_f32 v210, v218, v219
	v_cvt_pk_bf16_f32 v212, v220, v221
	ds_write_b16 v197, v206 offset:0
	ds_write_b16_d16_hi v197, v206 offset:64
	ds_write_b16 v197, v208 offset:128
	ds_write_b16_d16_hi v197, v208 offset:192
	ds_write_b16 v197, v210 offset:256
	ds_write_b16_d16_hi v197, v210 offset:320
	ds_write_b16 v197, v212 offset:384
	ds_write_b16_d16_hi v197, v212 offset:448
	ds_read_b128 v[198:201], v130 offset:0
	ds_read_b128 v[214:217], v130 offset:576
	ds_read_b128 v[202:205], v131 offset:0
	ds_read_b128 v[218:221], v131 offset:576
	ds_read_b128 v[206:209], v130 offset:144
	ds_read_b128 v[222:225], v130 offset:720
	ds_read_b128 v[210:213], v131 offset:144
	s_waitcnt lgkmcnt(14)
	ds_read_b128 v[226:229], v131 offset:720
	s_waitcnt lgkmcnt(6)
	v_mfma_f32_16x16x32_bf16 v[100:103], v[198:201], v[20:23], v[12:15]
	v_mfma_f32_16x16x32_bf16 v[104:107], v[198:201], v[52:55], v[16:19]
	v_mfma_f32_16x16x32_bf16 v[108:111], v[198:201], v[84:87], v[242:245]
	v_mfma_f32_16x16x32_bf16 v[112:115], v[214:217], v[20:23], v[12:15]
	v_mfma_f32_16x16x32_bf16 v[138:141], v[214:217], v[52:55], v[16:19]
	v_mfma_f32_16x16x32_bf16 v[142:145], v[214:217], v[84:87], v[242:245]
	s_waitcnt lgkmcnt(4)
	v_mfma_f32_16x16x32_bf16 v[100:103], v[202:205], v[24:27], v[100:103]
	v_mfma_f32_16x16x32_bf16 v[104:107], v[202:205], v[56:59], v[104:107]
	v_mfma_f32_16x16x32_bf16 v[112:115], v[218:221], v[24:27], v[112:115]
	v_mfma_f32_16x16x32_bf16 v[138:141], v[218:221], v[56:59], v[138:141]
	ds_read_b128 v[198:201], v130 offset:288
	ds_read_b128 v[214:217], v130 offset:864
	ds_read_b128 v[202:205], v131 offset:288
	ds_read_b128 v[218:221], v131 offset:864
	s_waitcnt lgkmcnt(6)
	v_mfma_f32_16x16x32_bf16 v[100:103], v[206:209], v[28:31], v[100:103]
	v_mfma_f32_16x16x32_bf16 v[104:107], v[206:209], v[60:63], v[104:107]
	v_mfma_f32_16x16x32_bf16 v[108:111], v[206:209], v[88:91], v[108:111]
	v_mfma_f32_16x16x32_bf16 v[112:115], v[222:225], v[28:31], v[112:115]
	v_mfma_f32_16x16x32_bf16 v[138:141], v[222:225], v[60:63], v[138:141]
	v_mfma_f32_16x16x32_bf16 v[142:145], v[222:225], v[88:91], v[142:145]
	s_waitcnt lgkmcnt(4)
	v_mfma_f32_16x16x32_bf16 v[100:103], v[210:213], v[32:35], v[100:103]
	v_mfma_f32_16x16x32_bf16 v[104:107], v[210:213], v[64:67], v[104:107]
	v_mfma_f32_16x16x32_bf16 v[112:115], v[226:229], v[32:35], v[112:115]
	v_mfma_f32_16x16x32_bf16 v[138:141], v[226:229], v[64:67], v[138:141]
	ds_read_b128 v[206:209], v130 offset:432
	ds_read_b128 v[222:225], v130 offset:1008
	ds_read_b128 v[210:213], v131 offset:432
	ds_read_b128 v[226:229], v131 offset:1008
	s_waitcnt lgkmcnt(6)
	v_mfma_f32_16x16x32_bf16 v[100:103], v[198:201], v[36:39], v[100:103]
	v_mfma_f32_16x16x32_bf16 v[104:107], v[198:201], v[68:71], v[104:107]
	v_mfma_f32_16x16x32_bf16 v[108:111], v[198:201], v[92:95], v[108:111]
	v_mfma_f32_16x16x32_bf16 v[112:115], v[214:217], v[36:39], v[112:115]
	v_mfma_f32_16x16x32_bf16 v[138:141], v[214:217], v[68:71], v[138:141]
	v_mfma_f32_16x16x32_bf16 v[142:145], v[214:217], v[92:95], v[142:145]
	s_waitcnt lgkmcnt(4)
	v_mfma_f32_16x16x32_bf16 v[100:103], v[202:205], v[40:43], v[100:103]
	v_mfma_f32_16x16x32_bf16 v[104:107], v[202:205], v[72:75], v[104:107]
	v_mfma_f32_16x16x32_bf16 v[112:115], v[218:221], v[40:43], v[112:115]
	v_mfma_f32_16x16x32_bf16 v[138:141], v[218:221], v[72:75], v[138:141]
	s_waitcnt lgkmcnt(2)
	v_mfma_f32_16x16x32_bf16 v[100:103], v[206:209], v[44:47], v[100:103]
	v_mfma_f32_16x16x32_bf16 v[104:107], v[206:209], v[76:79], v[104:107]
	v_mfma_f32_16x16x32_bf16 v[108:111], v[206:209], v[96:99], v[108:111]
	v_mfma_f32_16x16x32_bf16 v[112:115], v[222:225], v[44:47], v[112:115]
	v_mfma_f32_16x16x32_bf16 v[138:141], v[222:225], v[76:79], v[138:141]
	v_mfma_f32_16x16x32_bf16 v[142:145], v[222:225], v[96:99], v[142:145]
	s_waitcnt lgkmcnt(0)
	v_mfma_f32_16x16x32_bf16 v[100:103], v[210:213], v[48:51], v[100:103]
	v_mfma_f32_16x16x32_bf16 v[104:107], v[210:213], v[80:83], v[104:107]
	v_mfma_f32_16x16x32_bf16 v[112:115], v[226:229], v[48:51], v[112:115]
	v_mfma_f32_16x16x32_bf16 v[138:141], v[226:229], v[80:83], v[138:141]
	s_waitcnt lgkmcnt(0)
	s_barrier
	s_waitcnt vmcnt(4)
	ds_write_b128 v134, v[230:233]
	ds_write_b128 v134, v[234:237] offset:4608
	ds_write_b128 v135, v[238:241]
	s_add_i32 s64, s4, 0
	s_sub_i32 s64, 31, s64
	s_mul_i32 s71, s64, 0x30000
	s_add_u32 s38, s60, s71
	s_addc_u32 s39, s61, 0
	s_lshl_b32 s64, s64, 12
	v_add_u32_e32 v136, s64, v195
	ds_read_b128 v[116:119], v136
	s_waitcnt vmcnt(3)
	s_waitcnt lgkmcnt(0)
	v_lshlrev_b32_e32 v136, 16, v116
	v_lshlrev_b32_e32 v137, 16, v8
	v_and_b32_e32 v168, 0xffff0000, v116
	v_and_b32_e32 v169, 0xffff0000, v8
	v_mul_f32_e32 v136, v136, v137
	v_mul_f32_e32 v168, v168, v169
	v_cvt_pk_bf16_f32 v116, v136, v168
	v_lshlrev_b32_e32 v136, 16, v117
	v_lshlrev_b32_e32 v137, 16, v9
	v_and_b32_e32 v168, 0xffff0000, v117
	v_and_b32_e32 v169, 0xffff0000, v9
	v_mul_f32_e32 v136, v136, v137
	v_mul_f32_e32 v168, v168, v169
	v_cvt_pk_bf16_f32 v117, v136, v168
	v_lshlrev_b32_e32 v136, 16, v118
	v_lshlrev_b32_e32 v137, 16, v10
	v_and_b32_e32 v168, 0xffff0000, v118
	v_and_b32_e32 v169, 0xffff0000, v10
	v_mul_f32_e32 v136, v136, v137
	v_mul_f32_e32 v168, v168, v169
	v_cvt_pk_bf16_f32 v118, v136, v168
	v_lshlrev_b32_e32 v136, 16, v119
	v_lshlrev_b32_e32 v137, 16, v11
	v_and_b32_e32 v168, 0xffff0000, v119
	v_and_b32_e32 v169, 0xffff0000, v11
	v_mul_f32_e32 v136, v136, v137
	v_mul_f32_e32 v168, v168, v169
	v_cvt_pk_bf16_f32 v119, v136, v168
	global_store_dwordx4 v255, v[116:119], s[38:39]
	s_add_i32 s64, s4, 1
	s_sub_i32 s64, 31, s64
	s_mul_i32 s71, s64, 0x30000
	s_add_u32 s38, s60, s71
	s_addc_u32 s39, s61, 0
	s_lshl_b32 s64, s64, 12
	global_load_dwordx4 v[8:11], v255, s[38:39]
	s_add_i32 s52, s4, 4
	s_min_u32 s52, s52, 31
	s_sub_i32 s52, 31, s52
	s_lshl_b32 s52, s52, 13
	s_add_u32 s26, s50, s52
	s_addc_u32 s27, s51, 0
	global_load_dwordx4 v[230:233], v154, s[26:27]
	global_load_dwordx4 v[234:237], v155, s[26:27]
	global_load_dwordx4 v[238:241], v159, s[26:27]
	v_exp_f32_e32 v198, v100
	v_exp_f32_e32 v199, v101
	v_exp_f32_e32 v200, v102
	v_exp_f32_e32 v201, v103
	v_exp_f32_e32 v202, v112
	v_exp_f32_e32 v203, v113
	v_exp_f32_e32 v204, v114
	v_exp_f32_e32 v205, v115
	v_exp_f32_e32 v214, v104
	v_add_f32_e32 v198, 1.0, v198
	v_exp_f32_e32 v215, v105
	v_add_f32_e32 v199, 1.0, v199
	v_exp_f32_e32 v216, v106
	v_add_f32_e32 v200, 1.0, v200
	v_exp_f32_e32 v217, v107
	v_add_f32_e32 v201, 1.0, v201
	v_exp_f32_e32 v218, v138
	v_add_f32_e32 v202, 1.0, v202
	v_exp_f32_e32 v219, v139
	v_add_f32_e32 v203, 1.0, v203
	v_exp_f32_e32 v220, v140
	v_add_f32_e32 v204, 1.0, v204
	v_exp_f32_e32 v221, v141
	v_add_f32_e32 v205, 1.0, v205
	v_rcp_f32_e32 v198, v198
	v_add_f32_e32 v214, 1.0, v214
	v_rcp_f32_e32 v199, v199
	v_add_f32_e32 v215, 1.0, v215
	v_rcp_f32_e32 v200, v200
	v_add_f32_e32 v216, 1.0, v216
	v_rcp_f32_e32 v201, v201
	v_add_f32_e32 v217, 1.0, v217
	v_rcp_f32_e32 v202, v202
	v_add_f32_e32 v218, 1.0, v218
	v_rcp_f32_e32 v203, v203
	v_add_f32_e32 v219, 1.0, v219
	v_rcp_f32_e32 v204, v204
	v_add_f32_e32 v220, 1.0, v220
	v_rcp_f32_e32 v205, v205
	v_add_f32_e32 v221, 1.0, v221
	v_mul_f32_e32 v198, v179, v198
	v_mul_f32_e32 v199, v179, v199
	v_mul_f32_e32 v200, v179, v200
	v_mul_f32_e32 v201, v179, v201
	v_mul_f32_e32 v202, v179, v202
	v_mul_f32_e32 v203, v179, v203
	v_mul_f32_e32 v204, v179, v204
	v_mul_f32_e32 v205, v179, v205
	v_exp_f32_e32 v120, v198
	v_exp_f32_e32 v121, v199
	v_exp_f32_e32 v122, v200
	v_exp_f32_e32 v123, v201
	v_exp_f32_e32 v124, v202
	v_exp_f32_e32 v125, v203
	v_exp_f32_e32 v126, v204
	v_exp_f32_e32 v127, v205
	v_fma_f32 v206, -v120, v120, 1.0
	v_fma_f32 v207, -v121, v121, 1.0
	v_fma_f32 v208, -v122, v122, 1.0
	v_fma_f32 v209, -v123, v123, 1.0
	v_fma_f32 v210, -v124, v124, 1.0
	v_fma_f32 v211, -v125, v125, 1.0
	v_fma_f32 v212, -v126, v126, 1.0
	v_fma_f32 v213, -v127, v127, 1.0
	v_max_f32_e32 v206, 0xda24260, v206
	v_max_f32_e32 v207, 0xda24260, v207
	v_max_f32_e32 v208, 0xda24260, v208
	v_max_f32_e32 v209, 0xda24260, v209
	v_max_f32_e32 v210, 0xda24260, v210
	v_max_f32_e32 v211, 0xda24260, v211
	v_max_f32_e32 v212, 0xda24260, v212
	v_max_f32_e32 v213, 0xda24260, v213
	v_mul_f32_e32 v198, v214, v206
	v_mul_f32_e32 v199, v215, v207
	v_mul_f32_e32 v200, v216, v208
	v_mul_f32_e32 v201, v217, v209
	v_mul_f32_e32 v202, v218, v210
	v_mul_f32_e32 v203, v219, v211
	v_mul_f32_e32 v204, v220, v212
	v_mul_f32_e32 v205, v221, v213
	v_mul_f32_e32 v214, v214, v198
	v_mul_f32_e32 v215, v215, v199
	v_mul_f32_e32 v216, v216, v200
	v_mul_f32_e32 v217, v217, v201
	v_mul_f32_e32 v218, v218, v202
	v_mul_f32_e32 v219, v219, v203
	v_mul_f32_e32 v220, v220, v204
	v_mul_f32_e32 v221, v221, v205
	v_rsq_f32_e32 v214, v214
	v_mul_f32_e32 v222, v108, v206
	v_rsq_f32_e32 v215, v215
	v_mul_f32_e32 v223, v109, v207
	v_rsq_f32_e32 v216, v216
	v_mul_f32_e32 v224, v110, v208
	v_rsq_f32_e32 v217, v217
	v_mul_f32_e32 v225, v111, v209
	v_rsq_f32_e32 v218, v218
	v_mul_f32_e32 v226, v142, v210
	v_rsq_f32_e32 v219, v219
	v_mul_f32_e32 v227, v143, v211
	v_rsq_f32_e32 v220, v220
	v_mul_f32_e32 v228, v144, v212
	v_rsq_f32_e32 v221, v221
	v_mul_f32_e32 v229, v145, v213
	v_mul_f32_e32 v170, v222, v214
	v_mul_f32_e32 v171, v223, v215
	v_mul_f32_e32 v172, v224, v216
	v_mul_f32_e32 v173, v225, v217
	v_mul_f32_e32 v174, v226, v218
	v_mul_f32_e32 v175, v227, v219
	v_mul_f32_e32 v176, v228, v220
	v_mul_f32_e32 v177, v229, v221
	v_mov_b32_e32 v198, v177
	v_mov_b32_e32 v199, v127
	v_fma_f32 v198, v126, v198, v176
	v_mul_f32_e32 v199, v199, v126
	v_fma_f32 v198, v125, v198, v175
	v_mul_f32_e32 v199, v199, v125
	v_fma_f32 v198, v124, v198, v174
	v_mul_f32_e32 v199, v199, v124
	v_fma_f32 v198, v123, v198, v173
	v_mul_f32_e32 v199, v199, v123
	v_fma_f32 v198, v122, v198, v172
	v_mul_f32_e32 v199, v199, v122
	v_fma_f32 v198, v121, v198, v171
	v_mul_f32_e32 v199, v199, v121
	v_fma_f32 v198, v120, v198, v170
	v_mul_f32_e32 v199, v199, v120
	ds_bpermute_b32 v164, v185, v199 offset:0
	ds_bpermute_b32 v246, v185, v198 offset:0
	ds_bpermute_b32 v165, v185, v199 offset:64
	ds_bpermute_b32 v247, v185, v198 offset:64
	ds_bpermute_b32 v166, v185, v199 offset:128
	ds_bpermute_b32 v248, v185, v198 offset:128
	ds_bpermute_b32 v167, v185, v199 offset:192
	ds_bpermute_b32 v249, v185, v198 offset:192
	s_waitcnt lgkmcnt(0)
	v_mov_b32_e32 v251, v249
	v_mov_b32_e32 v250, v167
	v_fma_f32 v251, v251, v166, v248
	v_mul_f32_e32 v250, v250, v166
	v_fma_f32 v251, v251, v165, v247
	v_mul_f32_e32 v250, v250, v165
	v_fma_f32 v251, v251, v164, v246
	v_mul_f32_e32 v250, v250, v164
	s_mov_b64 exec, s[10:11]
	ds_write_b64 v182, v[250:251] offset:1024
	s_mov_b64 exec, -1
	s_waitcnt lgkmcnt(0)
	s_barrier
	ds_read2_b64 v[4:7], v183 offset0:128 offset1:144
	s_add_i32 s52, s4, 1
	s_sub_i32 s52, 31, s52
	s_lshl_b32 s52, s52, 12
	v_add_u32_e32 v197, s52, v184
	s_waitcnt lgkmcnt(0)
	v_fma_f32 v198, v180, v6, v7
	v_cndmask_b32_e64 v199, v180, v198, s[24:25]
	v_fma_f32 v180, v198, v4, v5
	v_fma_f32 v200, v199, v167, v249
	v_cndmask_b32_e64 v199, v199, v200, s[16:17]
	v_fma_f32 v200, v199, v166, v248
	v_cndmask_b32_e64 v199, v199, v200, s[20:21]
	v_fma_f32 v200, v199, v165, v247
	v_cndmask_b32_e64 v199, v199, v200, s[22:23]
	v_fma_f32 v221, v127, v199, v177
	v_fma_f32 v220, v126, v221, v176
	v_fma_f32 v219, v125, v220, v175
	v_fma_f32 v218, v124, v219, v174
	v_fma_f32 v217, v123, v218, v173
	v_fma_f32 v216, v122, v217, v172
	v_fma_f32 v215, v121, v216, v171
	v_fma_f32 v214, v120, v215, v170
	ds_read_u16 v206, v197 offset:0
	ds_read_u16 v207, v197 offset:64
	ds_read_u16 v208, v197 offset:128
	ds_read_u16 v209, v197 offset:192
	ds_read_u16 v210, v197 offset:256
	ds_read_u16 v211, v197 offset:320
	ds_read_u16 v212, v197 offset:384
	ds_read_u16 v213, v197 offset:448
	s_waitcnt lgkmcnt(0)
	v_lshlrev_b32_e32 v206, 16, v206
	v_lshlrev_b32_e32 v207, 16, v207
	v_lshlrev_b32_e32 v208, 16, v208
	v_lshlrev_b32_e32 v209, 16, v209
	v_lshlrev_b32_e32 v210, 16, v210
	v_lshlrev_b32_e32 v211, 16, v211
	v_lshlrev_b32_e32 v212, 16, v212
	v_lshlrev_b32_e32 v213, 16, v213
	v_add_f32_e32 v214, v214, v206
	v_add_f32_e32 v215, v215, v207
	v_add_f32_e32 v216, v216, v208
	v_add_f32_e32 v217, v217, v209
	v_add_f32_e32 v218, v218, v210
	v_add_f32_e32 v219, v219, v211
	v_add_f32_e32 v220, v220, v212
	v_add_f32_e32 v221, v221, v213
	v_cvt_pk_bf16_f32 v206, v214, v215
	v_cvt_pk_bf16_f32 v208, v216, v217
	v_cvt_pk_bf16_f32 v210, v218, v219
	v_cvt_pk_bf16_f32 v212, v220, v221
	ds_write_b16 v197, v206 offset:0
	ds_write_b16_d16_hi v197, v206 offset:64
	ds_write_b16 v197, v208 offset:128
	ds_write_b16_d16_hi v197, v208 offset:192
	ds_write_b16 v197, v210 offset:256
	ds_write_b16_d16_hi v197, v210 offset:320
	ds_write_b16 v197, v212 offset:384
	ds_write_b16_d16_hi v197, v212 offset:448
	s_add_i32 s4, s4, 2
.Lrec2_loopB_d1:
	ds_read_b128 v[198:201], v130 offset:0
	ds_read_b128 v[214:217], v130 offset:576
	ds_read_b128 v[202:205], v131 offset:0
	ds_read_b128 v[218:221], v131 offset:576
	ds_read_b128 v[206:209], v130 offset:144
	ds_read_b128 v[222:225], v130 offset:720
	ds_read_b128 v[210:213], v131 offset:144
	s_waitcnt lgkmcnt(14)
	ds_read_b128 v[226:229], v131 offset:720
	s_waitcnt lgkmcnt(6)
	v_mfma_f32_16x16x32_bf16 v[100:103], v[198:201], v[20:23], v[12:15]
	v_mfma_f32_16x16x32_bf16 v[104:107], v[198:201], v[52:55], v[16:19]
	v_mfma_f32_16x16x32_bf16 v[108:111], v[198:201], v[84:87], v[242:245]
	v_mfma_f32_16x16x32_bf16 v[112:115], v[214:217], v[20:23], v[12:15]
	v_mfma_f32_16x16x32_bf16 v[138:141], v[214:217], v[52:55], v[16:19]
	v_mfma_f32_16x16x32_bf16 v[142:145], v[214:217], v[84:87], v[242:245]
	s_waitcnt lgkmcnt(4)
	v_mfma_f32_16x16x32_bf16 v[100:103], v[202:205], v[24:27], v[100:103]
	v_mfma_f32_16x16x32_bf16 v[104:107], v[202:205], v[56:59], v[104:107]
	v_mfma_f32_16x16x32_bf16 v[112:115], v[218:221], v[24:27], v[112:115]
	v_mfma_f32_16x16x32_bf16 v[138:141], v[218:221], v[56:59], v[138:141]
	ds_read_b128 v[198:201], v130 offset:288
	ds_read_b128 v[214:217], v130 offset:864
	ds_read_b128 v[202:205], v131 offset:288
	ds_read_b128 v[218:221], v131 offset:864
	s_waitcnt lgkmcnt(6)
	v_mfma_f32_16x16x32_bf16 v[100:103], v[206:209], v[28:31], v[100:103]
	v_mfma_f32_16x16x32_bf16 v[104:107], v[206:209], v[60:63], v[104:107]
	v_mfma_f32_16x16x32_bf16 v[108:111], v[206:209], v[88:91], v[108:111]
	v_mfma_f32_16x16x32_bf16 v[112:115], v[222:225], v[28:31], v[112:115]
	v_mfma_f32_16x16x32_bf16 v[138:141], v[222:225], v[60:63], v[138:141]
	v_mfma_f32_16x16x32_bf16 v[142:145], v[222:225], v[88:91], v[142:145]
	s_waitcnt lgkmcnt(4)
	v_mfma_f32_16x16x32_bf16 v[100:103], v[210:213], v[32:35], v[100:103]
	v_mfma_f32_16x16x32_bf16 v[104:107], v[210:213], v[64:67], v[104:107]
	v_mfma_f32_16x16x32_bf16 v[112:115], v[226:229], v[32:35], v[112:115]
	v_mfma_f32_16x16x32_bf16 v[138:141], v[226:229], v[64:67], v[138:141]
	ds_read_b128 v[206:209], v130 offset:432
	ds_read_b128 v[222:225], v130 offset:1008
	ds_read_b128 v[210:213], v131 offset:432
	ds_read_b128 v[226:229], v131 offset:1008
	s_waitcnt lgkmcnt(6)
	v_mfma_f32_16x16x32_bf16 v[100:103], v[198:201], v[36:39], v[100:103]
	v_mfma_f32_16x16x32_bf16 v[104:107], v[198:201], v[68:71], v[104:107]
	v_mfma_f32_16x16x32_bf16 v[108:111], v[198:201], v[92:95], v[108:111]
	v_mfma_f32_16x16x32_bf16 v[112:115], v[214:217], v[36:39], v[112:115]
	v_mfma_f32_16x16x32_bf16 v[138:141], v[214:217], v[68:71], v[138:141]
	v_mfma_f32_16x16x32_bf16 v[142:145], v[214:217], v[92:95], v[142:145]
	s_waitcnt lgkmcnt(4)
	v_mfma_f32_16x16x32_bf16 v[100:103], v[202:205], v[40:43], v[100:103]
	v_mfma_f32_16x16x32_bf16 v[104:107], v[202:205], v[72:75], v[104:107]
	v_mfma_f32_16x16x32_bf16 v[112:115], v[218:221], v[40:43], v[112:115]
	v_mfma_f32_16x16x32_bf16 v[138:141], v[218:221], v[72:75], v[138:141]
	s_waitcnt lgkmcnt(2)
	v_mfma_f32_16x16x32_bf16 v[100:103], v[206:209], v[44:47], v[100:103]
	v_mfma_f32_16x16x32_bf16 v[104:107], v[206:209], v[76:79], v[104:107]
	v_mfma_f32_16x16x32_bf16 v[108:111], v[206:209], v[96:99], v[108:111]
	v_mfma_f32_16x16x32_bf16 v[112:115], v[222:225], v[44:47], v[112:115]
	v_mfma_f32_16x16x32_bf16 v[138:141], v[222:225], v[76:79], v[138:141]
	v_mfma_f32_16x16x32_bf16 v[142:145], v[222:225], v[96:99], v[142:145]
	s_waitcnt lgkmcnt(0)
	v_mfma_f32_16x16x32_bf16 v[100:103], v[210:213], v[48:51], v[100:103]
	v_mfma_f32_16x16x32_bf16 v[104:107], v[210:213], v[80:83], v[104:107]
	v_mfma_f32_16x16x32_bf16 v[112:115], v[226:229], v[48:51], v[112:115]
	v_mfma_f32_16x16x32_bf16 v[138:141], v[226:229], v[80:83], v[138:141]
	s_waitcnt lgkmcnt(0)
	s_barrier
	s_waitcnt vmcnt(5)
	ds_write_b128 v134, v[146:149]
	ds_write_b128 v134, v[150:153] offset:4608
	ds_write_b128 v135, v[160:163]
	s_add_i32 s64, s4, -1
	s_sub_i32 s64, 31, s64
	s_mul_i32 s71, s64, 0x30000
	s_add_u32 s38, s60, s71
	s_addc_u32 s39, s61, 0
	s_lshl_b32 s64, s64, 12
	v_add_u32_e32 v136, s64, v195
	ds_read_b128 v[116:119], v136
	s_waitcnt vmcnt(3)
	s_waitcnt lgkmcnt(0)
	v_lshlrev_b32_e32 v136, 16, v116
	v_lshlrev_b32_e32 v137, 16, v8
	v_and_b32_e32 v168, 0xffff0000, v116
	v_and_b32_e32 v169, 0xffff0000, v8
	v_mul_f32_e32 v136, v136, v137
	v_mul_f32_e32 v168, v168, v169
	v_cvt_pk_bf16_f32 v116, v136, v168
	v_lshlrev_b32_e32 v136, 16, v117
	v_lshlrev_b32_e32 v137, 16, v9
	v_and_b32_e32 v168, 0xffff0000, v117
	v_and_b32_e32 v169, 0xffff0000, v9
	v_mul_f32_e32 v136, v136, v137
	v_mul_f32_e32 v168, v168, v169
	v_cvt_pk_bf16_f32 v117, v136, v168
	v_lshlrev_b32_e32 v136, 16, v118
	v_lshlrev_b32_e32 v137, 16, v10
	v_and_b32_e32 v168, 0xffff0000, v118
	v_and_b32_e32 v169, 0xffff0000, v10
	v_mul_f32_e32 v136, v136, v137
	v_mul_f32_e32 v168, v168, v169
	v_cvt_pk_bf16_f32 v118, v136, v168
	v_lshlrev_b32_e32 v136, 16, v119
	v_lshlrev_b32_e32 v137, 16, v11
	v_and_b32_e32 v168, 0xffff0000, v119
	v_and_b32_e32 v169, 0xffff0000, v11
	v_mul_f32_e32 v136, v136, v137
	v_mul_f32_e32 v168, v168, v169
	v_cvt_pk_bf16_f32 v119, v136, v168
	global_store_dwordx4 v255, v[116:119], s[38:39]
	s_add_i32 s64, s4, 0
	s_sub_i32 s64, 31, s64
	s_mul_i32 s71, s64, 0x30000
	s_add_u32 s38, s60, s71
	s_addc_u32 s39, s61, 0
	s_lshl_b32 s64, s64, 12
	global_load_dwordx4 v[8:11], v255, s[38:39]
	s_add_i32 s52, s4, 3
	s_min_u32 s52, s52, 31
	s_sub_i32 s52, 31, s52
	s_lshl_b32 s52, s52, 13
	s_add_u32 s26, s50, s52
	s_addc_u32 s27, s51, 0
	global_load_dwordx4 v[146:149], v154, s[26:27]
	global_load_dwordx4 v[150:153], v155, s[26:27]
	global_load_dwordx4 v[160:163], v159, s[26:27]
	v_exp_f32_e32 v198, v100
	v_exp_f32_e32 v199, v101
	v_exp_f32_e32 v200, v102
	v_exp_f32_e32 v201, v103
	v_exp_f32_e32 v202, v112
	v_exp_f32_e32 v203, v113
	v_exp_f32_e32 v204, v114
	v_exp_f32_e32 v205, v115
	v_exp_f32_e32 v214, v104
	v_add_f32_e32 v198, 1.0, v198
	v_exp_f32_e32 v215, v105
	v_add_f32_e32 v199, 1.0, v199
	v_exp_f32_e32 v216, v106
	v_add_f32_e32 v200, 1.0, v200
	v_exp_f32_e32 v217, v107
	v_add_f32_e32 v201, 1.0, v201
	v_exp_f32_e32 v218, v138
	v_add_f32_e32 v202, 1.0, v202
	v_exp_f32_e32 v219, v139
	v_add_f32_e32 v203, 1.0, v203
	v_exp_f32_e32 v220, v140
	v_add_f32_e32 v204, 1.0, v204
	v_exp_f32_e32 v221, v141
	v_add_f32_e32 v205, 1.0, v205
	v_rcp_f32_e32 v198, v198
	v_add_f32_e32 v214, 1.0, v214
	v_rcp_f32_e32 v199, v199
	v_add_f32_e32 v215, 1.0, v215
	v_rcp_f32_e32 v200, v200
	v_add_f32_e32 v216, 1.0, v216
	v_rcp_f32_e32 v201, v201
	v_add_f32_e32 v217, 1.0, v217
	v_rcp_f32_e32 v202, v202
	v_add_f32_e32 v218, 1.0, v218
	v_rcp_f32_e32 v203, v203
	v_add_f32_e32 v219, 1.0, v219
	v_rcp_f32_e32 v204, v204
	v_add_f32_e32 v220, 1.0, v220
	v_rcp_f32_e32 v205, v205
	v_add_f32_e32 v221, 1.0, v221
	v_mul_f32_e32 v198, v179, v198
	v_mul_f32_e32 v199, v179, v199
	v_mul_f32_e32 v200, v179, v200
	v_mul_f32_e32 v201, v179, v201
	v_mul_f32_e32 v202, v179, v202
	v_mul_f32_e32 v203, v179, v203
	v_mul_f32_e32 v204, v179, v204
	v_mul_f32_e32 v205, v179, v205
	v_exp_f32_e32 v120, v198
	v_exp_f32_e32 v121, v199
	v_exp_f32_e32 v122, v200
	v_exp_f32_e32 v123, v201
	v_exp_f32_e32 v124, v202
	v_exp_f32_e32 v125, v203
	v_exp_f32_e32 v126, v204
	v_exp_f32_e32 v127, v205
	v_fma_f32 v206, -v120, v120, 1.0
	v_fma_f32 v207, -v121, v121, 1.0
	v_fma_f32 v208, -v122, v122, 1.0
	v_fma_f32 v209, -v123, v123, 1.0
	v_fma_f32 v210, -v124, v124, 1.0
	v_fma_f32 v211, -v125, v125, 1.0
	v_fma_f32 v212, -v126, v126, 1.0
	v_fma_f32 v213, -v127, v127, 1.0
	v_max_f32_e32 v206, 0xda24260, v206
	v_max_f32_e32 v207, 0xda24260, v207
	v_max_f32_e32 v208, 0xda24260, v208
	v_max_f32_e32 v209, 0xda24260, v209
	v_max_f32_e32 v210, 0xda24260, v210
	v_max_f32_e32 v211, 0xda24260, v211
	v_max_f32_e32 v212, 0xda24260, v212
	v_max_f32_e32 v213, 0xda24260, v213
	v_mul_f32_e32 v198, v214, v206
	v_mul_f32_e32 v199, v215, v207
	v_mul_f32_e32 v200, v216, v208
	v_mul_f32_e32 v201, v217, v209
	v_mul_f32_e32 v202, v218, v210
	v_mul_f32_e32 v203, v219, v211
	v_mul_f32_e32 v204, v220, v212
	v_mul_f32_e32 v205, v221, v213
	v_mul_f32_e32 v214, v214, v198
	v_mul_f32_e32 v215, v215, v199
	v_mul_f32_e32 v216, v216, v200
	v_mul_f32_e32 v217, v217, v201
	v_mul_f32_e32 v218, v218, v202
	v_mul_f32_e32 v219, v219, v203
	v_mul_f32_e32 v220, v220, v204
	v_mul_f32_e32 v221, v221, v205
	v_rsq_f32_e32 v214, v214
	v_mul_f32_e32 v222, v108, v206
	v_rsq_f32_e32 v215, v215
	v_mul_f32_e32 v223, v109, v207
	v_rsq_f32_e32 v216, v216
	v_mul_f32_e32 v224, v110, v208
	v_rsq_f32_e32 v217, v217
	v_mul_f32_e32 v225, v111, v209
	v_rsq_f32_e32 v218, v218
	v_mul_f32_e32 v226, v142, v210
	v_rsq_f32_e32 v219, v219
	v_mul_f32_e32 v227, v143, v211
	v_rsq_f32_e32 v220, v220
	v_mul_f32_e32 v228, v144, v212
	v_rsq_f32_e32 v221, v221
	v_mul_f32_e32 v229, v145, v213
	v_mul_f32_e32 v170, v222, v214
	v_mul_f32_e32 v171, v223, v215
	v_mul_f32_e32 v172, v224, v216
	v_mul_f32_e32 v173, v225, v217
	v_mul_f32_e32 v174, v226, v218
	v_mul_f32_e32 v175, v227, v219
	v_mul_f32_e32 v176, v228, v220
	v_mul_f32_e32 v177, v229, v221
	v_mov_b32_e32 v198, v177
	v_mov_b32_e32 v199, v127
	v_fma_f32 v198, v126, v198, v176
	v_mul_f32_e32 v199, v199, v126
	v_fma_f32 v198, v125, v198, v175
	v_mul_f32_e32 v199, v199, v125
	v_fma_f32 v198, v124, v198, v174
	v_mul_f32_e32 v199, v199, v124
	v_fma_f32 v198, v123, v198, v173
	v_mul_f32_e32 v199, v199, v123
	v_fma_f32 v198, v122, v198, v172
	v_mul_f32_e32 v199, v199, v122
	v_fma_f32 v198, v121, v198, v171
	v_mul_f32_e32 v199, v199, v121
	v_fma_f32 v198, v120, v198, v170
	v_mul_f32_e32 v199, v199, v120
	ds_bpermute_b32 v164, v185, v199 offset:0
	ds_bpermute_b32 v246, v185, v198 offset:0
	ds_bpermute_b32 v165, v185, v199 offset:64
	ds_bpermute_b32 v247, v185, v198 offset:64
	ds_bpermute_b32 v166, v185, v199 offset:128
	ds_bpermute_b32 v248, v185, v198 offset:128
	ds_bpermute_b32 v167, v185, v199 offset:192
	ds_bpermute_b32 v249, v185, v198 offset:192
	s_waitcnt lgkmcnt(0)
	v_mov_b32_e32 v251, v249
	v_mov_b32_e32 v250, v167
	v_fma_f32 v251, v251, v166, v248
	v_mul_f32_e32 v250, v250, v166
	v_fma_f32 v251, v251, v165, v247
	v_mul_f32_e32 v250, v250, v165
	v_fma_f32 v251, v251, v164, v246
	v_mul_f32_e32 v250, v250, v164
	s_mov_b64 exec, s[10:11]
	ds_write_b64 v182, v[250:251] offset:0
	s_mov_b64 exec, -1
	s_waitcnt lgkmcnt(0)
	s_barrier
	ds_read2_b64 v[4:7], v183 offset0:0 offset1:16
	s_add_i32 s52, s4, 0
	s_sub_i32 s52, 31, s52
	s_lshl_b32 s52, s52, 12
	v_add_u32_e32 v197, s52, v184
	s_waitcnt lgkmcnt(0)
	v_fma_f32 v198, v180, v6, v7
	v_cndmask_b32_e64 v199, v180, v198, s[24:25]
	v_fma_f32 v180, v198, v4, v5
	v_fma_f32 v200, v199, v167, v249
	v_cndmask_b32_e64 v199, v199, v200, s[16:17]
	v_fma_f32 v200, v199, v166, v248
	v_cndmask_b32_e64 v199, v199, v200, s[20:21]
	v_fma_f32 v200, v199, v165, v247
	v_cndmask_b32_e64 v199, v199, v200, s[22:23]
	v_fma_f32 v221, v127, v199, v177
	v_fma_f32 v220, v126, v221, v176
	v_fma_f32 v219, v125, v220, v175
	v_fma_f32 v218, v124, v219, v174
	v_fma_f32 v217, v123, v218, v173
	v_fma_f32 v216, v122, v217, v172
	v_fma_f32 v215, v121, v216, v171
	v_fma_f32 v214, v120, v215, v170
	ds_read_u16 v206, v197 offset:0
	ds_read_u16 v207, v197 offset:64
	ds_read_u16 v208, v197 offset:128
	ds_read_u16 v209, v197 offset:192
	ds_read_u16 v210, v197 offset:256
	ds_read_u16 v211, v197 offset:320
	ds_read_u16 v212, v197 offset:384
	ds_read_u16 v213, v197 offset:448
	s_waitcnt lgkmcnt(0)
	v_lshlrev_b32_e32 v206, 16, v206
	v_lshlrev_b32_e32 v207, 16, v207
	v_lshlrev_b32_e32 v208, 16, v208
	v_lshlrev_b32_e32 v209, 16, v209
	v_lshlrev_b32_e32 v210, 16, v210
	v_lshlrev_b32_e32 v211, 16, v211
	v_lshlrev_b32_e32 v212, 16, v212
	v_lshlrev_b32_e32 v213, 16, v213
	v_add_f32_e32 v214, v214, v206
	v_add_f32_e32 v215, v215, v207
	v_add_f32_e32 v216, v216, v208
	v_add_f32_e32 v217, v217, v209
	v_add_f32_e32 v218, v218, v210
	v_add_f32_e32 v219, v219, v211
	v_add_f32_e32 v220, v220, v212
	v_add_f32_e32 v221, v221, v213
	v_cvt_pk_bf16_f32 v206, v214, v215
	v_cvt_pk_bf16_f32 v208, v216, v217
	v_cvt_pk_bf16_f32 v210, v218, v219
	v_cvt_pk_bf16_f32 v212, v220, v221
	ds_write_b16 v197, v206 offset:0
	ds_write_b16_d16_hi v197, v206 offset:64
	ds_write_b16 v197, v208 offset:128
	ds_write_b16_d16_hi v197, v208 offset:192
	ds_write_b16 v197, v210 offset:256
	ds_write_b16_d16_hi v197, v210 offset:320
	ds_write_b16 v197, v212 offset:384
	ds_write_b16_d16_hi v197, v212 offset:448
	ds_read_b128 v[198:201], v130 offset:0
	ds_read_b128 v[214:217], v130 offset:576
	ds_read_b128 v[202:205], v131 offset:0
	ds_read_b128 v[218:221], v131 offset:576
	ds_read_b128 v[206:209], v130 offset:144
	ds_read_b128 v[222:225], v130 offset:720
	ds_read_b128 v[210:213], v131 offset:144
	s_waitcnt lgkmcnt(14)
	ds_read_b128 v[226:229], v131 offset:720
	s_waitcnt lgkmcnt(6)
	v_mfma_f32_16x16x32_bf16 v[100:103], v[198:201], v[20:23], v[12:15]
	v_mfma_f32_16x16x32_bf16 v[104:107], v[198:201], v[52:55], v[16:19]
	v_mfma_f32_16x16x32_bf16 v[108:111], v[198:201], v[84:87], v[242:245]
	v_mfma_f32_16x16x32_bf16 v[112:115], v[214:217], v[20:23], v[12:15]
	v_mfma_f32_16x16x32_bf16 v[138:141], v[214:217], v[52:55], v[16:19]
	v_mfma_f32_16x16x32_bf16 v[142:145], v[214:217], v[84:87], v[242:245]
	s_waitcnt lgkmcnt(4)
	v_mfma_f32_16x16x32_bf16 v[100:103], v[202:205], v[24:27], v[100:103]
	v_mfma_f32_16x16x32_bf16 v[104:107], v[202:205], v[56:59], v[104:107]
	v_mfma_f32_16x16x32_bf16 v[112:115], v[218:221], v[24:27], v[112:115]
	v_mfma_f32_16x16x32_bf16 v[138:141], v[218:221], v[56:59], v[138:141]
	ds_read_b128 v[198:201], v130 offset:288
	ds_read_b128 v[214:217], v130 offset:864
	ds_read_b128 v[202:205], v131 offset:288
	ds_read_b128 v[218:221], v131 offset:864
	s_waitcnt lgkmcnt(6)
	v_mfma_f32_16x16x32_bf16 v[100:103], v[206:209], v[28:31], v[100:103]
	v_mfma_f32_16x16x32_bf16 v[104:107], v[206:209], v[60:63], v[104:107]
	v_mfma_f32_16x16x32_bf16 v[108:111], v[206:209], v[88:91], v[108:111]
	v_mfma_f32_16x16x32_bf16 v[112:115], v[222:225], v[28:31], v[112:115]
	v_mfma_f32_16x16x32_bf16 v[138:141], v[222:225], v[60:63], v[138:141]
	v_mfma_f32_16x16x32_bf16 v[142:145], v[222:225], v[88:91], v[142:145]
	s_waitcnt lgkmcnt(4)
	v_mfma_f32_16x16x32_bf16 v[100:103], v[210:213], v[32:35], v[100:103]
	v_mfma_f32_16x16x32_bf16 v[104:107], v[210:213], v[64:67], v[104:107]
	v_mfma_f32_16x16x32_bf16 v[112:115], v[226:229], v[32:35], v[112:115]
	v_mfma_f32_16x16x32_bf16 v[138:141], v[226:229], v[64:67], v[138:141]
	ds_read_b128 v[206:209], v130 offset:432
	ds_read_b128 v[222:225], v130 offset:1008
	ds_read_b128 v[210:213], v131 offset:432
	ds_read_b128 v[226:229], v131 offset:1008
	s_waitcnt lgkmcnt(6)
	v_mfma_f32_16x16x32_bf16 v[100:103], v[198:201], v[36:39], v[100:103]
	v_mfma_f32_16x16x32_bf16 v[104:107], v[198:201], v[68:71], v[104:107]
	v_mfma_f32_16x16x32_bf16 v[108:111], v[198:201], v[92:95], v[108:111]
	v_mfma_f32_16x16x32_bf16 v[112:115], v[214:217], v[36:39], v[112:115]
	v_mfma_f32_16x16x32_bf16 v[138:141], v[214:217], v[68:71], v[138:141]
	v_mfma_f32_16x16x32_bf16 v[142:145], v[214:217], v[92:95], v[142:145]
	s_waitcnt lgkmcnt(4)
	v_mfma_f32_16x16x32_bf16 v[100:103], v[202:205], v[40:43], v[100:103]
	v_mfma_f32_16x16x32_bf16 v[104:107], v[202:205], v[72:75], v[104:107]
	v_mfma_f32_16x16x32_bf16 v[112:115], v[218:221], v[40:43], v[112:115]
	v_mfma_f32_16x16x32_bf16 v[138:141], v[218:221], v[72:75], v[138:141]
	s_waitcnt lgkmcnt(2)
	v_mfma_f32_16x16x32_bf16 v[100:103], v[206:209], v[44:47], v[100:103]
	v_mfma_f32_16x16x32_bf16 v[104:107], v[206:209], v[76:79], v[104:107]
	v_mfma_f32_16x16x32_bf16 v[108:111], v[206:209], v[96:99], v[108:111]
	v_mfma_f32_16x16x32_bf16 v[112:115], v[222:225], v[44:47], v[112:115]
	v_mfma_f32_16x16x32_bf16 v[138:141], v[222:225], v[76:79], v[138:141]
	v_mfma_f32_16x16x32_bf16 v[142:145], v[222:225], v[96:99], v[142:145]
	s_waitcnt lgkmcnt(0)
	v_mfma_f32_16x16x32_bf16 v[100:103], v[210:213], v[48:51], v[100:103]
	v_mfma_f32_16x16x32_bf16 v[104:107], v[210:213], v[80:83], v[104:107]
	v_mfma_f32_16x16x32_bf16 v[112:115], v[226:229], v[48:51], v[112:115]
	v_mfma_f32_16x16x32_bf16 v[138:141], v[226:229], v[80:83], v[138:141]
	s_waitcnt lgkmcnt(0)
	s_barrier
	s_waitcnt vmcnt(5)
	ds_write_b128 v134, v[230:233]
	ds_write_b128 v134, v[234:237] offset:4608
	ds_write_b128 v135, v[238:241]
	s_add_i32 s64, s4, 0
	s_sub_i32 s64, 31, s64
	s_mul_i32 s71, s64, 0x30000
	s_add_u32 s38, s60, s71
	s_addc_u32 s39, s61, 0
	s_lshl_b32 s64, s64, 12
	v_add_u32_e32 v136, s64, v195
	ds_read_b128 v[116:119], v136
	s_waitcnt vmcnt(3)
	s_waitcnt lgkmcnt(0)
	v_lshlrev_b32_e32 v136, 16, v116
	v_lshlrev_b32_e32 v137, 16, v8
	v_and_b32_e32 v168, 0xffff0000, v116
	v_and_b32_e32 v169, 0xffff0000, v8
	v_mul_f32_e32 v136, v136, v137
	v_mul_f32_e32 v168, v168, v169
	v_cvt_pk_bf16_f32 v116, v136, v168
	v_lshlrev_b32_e32 v136, 16, v117
	v_lshlrev_b32_e32 v137, 16, v9
	v_and_b32_e32 v168, 0xffff0000, v117
	v_and_b32_e32 v169, 0xffff0000, v9
	v_mul_f32_e32 v136, v136, v137
	v_mul_f32_e32 v168, v168, v169
	v_cvt_pk_bf16_f32 v117, v136, v168
	v_lshlrev_b32_e32 v136, 16, v118
	v_lshlrev_b32_e32 v137, 16, v10
	v_and_b32_e32 v168, 0xffff0000, v118
	v_and_b32_e32 v169, 0xffff0000, v10
	v_mul_f32_e32 v136, v136, v137
	v_mul_f32_e32 v168, v168, v169
	v_cvt_pk_bf16_f32 v118, v136, v168
	v_lshlrev_b32_e32 v136, 16, v119
	v_lshlrev_b32_e32 v137, 16, v11
	v_and_b32_e32 v168, 0xffff0000, v119
	v_and_b32_e32 v169, 0xffff0000, v11
	v_mul_f32_e32 v136, v136, v137
	v_mul_f32_e32 v168, v168, v169
	v_cvt_pk_bf16_f32 v119, v136, v168
	global_store_dwordx4 v255, v[116:119], s[38:39]
	s_add_i32 s64, s4, 1
	s_sub_i32 s64, 31, s64
	s_mul_i32 s71, s64, 0x30000
	s_add_u32 s38, s60, s71
	s_addc_u32 s39, s61, 0
	s_lshl_b32 s64, s64, 12
	global_load_dwordx4 v[8:11], v255, s[38:39]
	s_add_i32 s52, s4, 4
	s_min_u32 s52, s52, 31
	s_sub_i32 s52, 31, s52
	s_lshl_b32 s52, s52, 13
	s_add_u32 s26, s50, s52
	s_addc_u32 s27, s51, 0
	global_load_dwordx4 v[230:233], v154, s[26:27]
	global_load_dwordx4 v[234:237], v155, s[26:27]
	global_load_dwordx4 v[238:241], v159, s[26:27]
	v_exp_f32_e32 v198, v100
	v_exp_f32_e32 v199, v101
	v_exp_f32_e32 v200, v102
	v_exp_f32_e32 v201, v103
	v_exp_f32_e32 v202, v112
	v_exp_f32_e32 v203, v113
	v_exp_f32_e32 v204, v114
	v_exp_f32_e32 v205, v115
	v_exp_f32_e32 v214, v104
	v_add_f32_e32 v198, 1.0, v198
	v_exp_f32_e32 v215, v105
	v_add_f32_e32 v199, 1.0, v199
	v_exp_f32_e32 v216, v106
	v_add_f32_e32 v200, 1.0, v200
	v_exp_f32_e32 v217, v107
	v_add_f32_e32 v201, 1.0, v201
	v_exp_f32_e32 v218, v138
	v_add_f32_e32 v202, 1.0, v202
	v_exp_f32_e32 v219, v139
	v_add_f32_e32 v203, 1.0, v203
	v_exp_f32_e32 v220, v140
	v_add_f32_e32 v204, 1.0, v204
	v_exp_f32_e32 v221, v141
	v_add_f32_e32 v205, 1.0, v205
	v_rcp_f32_e32 v198, v198
	v_add_f32_e32 v214, 1.0, v214
	v_rcp_f32_e32 v199, v199
	v_add_f32_e32 v215, 1.0, v215
	v_rcp_f32_e32 v200, v200
	v_add_f32_e32 v216, 1.0, v216
	v_rcp_f32_e32 v201, v201
	v_add_f32_e32 v217, 1.0, v217
	v_rcp_f32_e32 v202, v202
	v_add_f32_e32 v218, 1.0, v218
	v_rcp_f32_e32 v203, v203
	v_add_f32_e32 v219, 1.0, v219
	v_rcp_f32_e32 v204, v204
	v_add_f32_e32 v220, 1.0, v220
	v_rcp_f32_e32 v205, v205
	v_add_f32_e32 v221, 1.0, v221
	v_mul_f32_e32 v198, v179, v198
	v_mul_f32_e32 v199, v179, v199
	v_mul_f32_e32 v200, v179, v200
	v_mul_f32_e32 v201, v179, v201
	v_mul_f32_e32 v202, v179, v202
	v_mul_f32_e32 v203, v179, v203
	v_mul_f32_e32 v204, v179, v204
	v_mul_f32_e32 v205, v179, v205
	v_exp_f32_e32 v120, v198
	v_exp_f32_e32 v121, v199
	v_exp_f32_e32 v122, v200
	v_exp_f32_e32 v123, v201
	v_exp_f32_e32 v124, v202
	v_exp_f32_e32 v125, v203
	v_exp_f32_e32 v126, v204
	v_exp_f32_e32 v127, v205
	v_fma_f32 v206, -v120, v120, 1.0
	v_fma_f32 v207, -v121, v121, 1.0
	v_fma_f32 v208, -v122, v122, 1.0
	v_fma_f32 v209, -v123, v123, 1.0
	v_fma_f32 v210, -v124, v124, 1.0
	v_fma_f32 v211, -v125, v125, 1.0
	v_fma_f32 v212, -v126, v126, 1.0
	v_fma_f32 v213, -v127, v127, 1.0
	v_max_f32_e32 v206, 0xda24260, v206
	v_max_f32_e32 v207, 0xda24260, v207
	v_max_f32_e32 v208, 0xda24260, v208
	v_max_f32_e32 v209, 0xda24260, v209
	v_max_f32_e32 v210, 0xda24260, v210
	v_max_f32_e32 v211, 0xda24260, v211
	v_max_f32_e32 v212, 0xda24260, v212
	v_max_f32_e32 v213, 0xda24260, v213
	v_mul_f32_e32 v198, v214, v206
	v_mul_f32_e32 v199, v215, v207
	v_mul_f32_e32 v200, v216, v208
	v_mul_f32_e32 v201, v217, v209
	v_mul_f32_e32 v202, v218, v210
	v_mul_f32_e32 v203, v219, v211
	v_mul_f32_e32 v204, v220, v212
	v_mul_f32_e32 v205, v221, v213
	v_mul_f32_e32 v214, v214, v198
	v_mul_f32_e32 v215, v215, v199
	v_mul_f32_e32 v216, v216, v200
	v_mul_f32_e32 v217, v217, v201
	v_mul_f32_e32 v218, v218, v202
	v_mul_f32_e32 v219, v219, v203
	v_mul_f32_e32 v220, v220, v204
	v_mul_f32_e32 v221, v221, v205
	v_rsq_f32_e32 v214, v214
	v_mul_f32_e32 v222, v108, v206
	v_rsq_f32_e32 v215, v215
	v_mul_f32_e32 v223, v109, v207
	v_rsq_f32_e32 v216, v216
	v_mul_f32_e32 v224, v110, v208
	v_rsq_f32_e32 v217, v217
	v_mul_f32_e32 v225, v111, v209
	v_rsq_f32_e32 v218, v218
	v_mul_f32_e32 v226, v142, v210
	v_rsq_f32_e32 v219, v219
	v_mul_f32_e32 v227, v143, v211
	v_rsq_f32_e32 v220, v220
	v_mul_f32_e32 v228, v144, v212
	v_rsq_f32_e32 v221, v221
	v_mul_f32_e32 v229, v145, v213
	v_mul_f32_e32 v170, v222, v214
	v_mul_f32_e32 v171, v223, v215
	v_mul_f32_e32 v172, v224, v216
	v_mul_f32_e32 v173, v225, v217
	v_mul_f32_e32 v174, v226, v218
	v_mul_f32_e32 v175, v227, v219
	v_mul_f32_e32 v176, v228, v220
	v_mul_f32_e32 v177, v229, v221
	v_mov_b32_e32 v198, v177
	v_mov_b32_e32 v199, v127
	v_fma_f32 v198, v126, v198, v176
	v_mul_f32_e32 v199, v199, v126
	v_fma_f32 v198, v125, v198, v175
	v_mul_f32_e32 v199, v199, v125
	v_fma_f32 v198, v124, v198, v174
	v_mul_f32_e32 v199, v199, v124
	v_fma_f32 v198, v123, v198, v173
	v_mul_f32_e32 v199, v199, v123
	v_fma_f32 v198, v122, v198, v172
	v_mul_f32_e32 v199, v199, v122
	v_fma_f32 v198, v121, v198, v171
	v_mul_f32_e32 v199, v199, v121
	v_fma_f32 v198, v120, v198, v170
	v_mul_f32_e32 v199, v199, v120
	ds_bpermute_b32 v164, v185, v199 offset:0
	ds_bpermute_b32 v246, v185, v198 offset:0
	ds_bpermute_b32 v165, v185, v199 offset:64
	ds_bpermute_b32 v247, v185, v198 offset:64
	ds_bpermute_b32 v166, v185, v199 offset:128
	ds_bpermute_b32 v248, v185, v198 offset:128
	ds_bpermute_b32 v167, v185, v199 offset:192
	ds_bpermute_b32 v249, v185, v198 offset:192
	s_waitcnt lgkmcnt(0)
	v_mov_b32_e32 v251, v249
	v_mov_b32_e32 v250, v167
	v_fma_f32 v251, v251, v166, v248
	v_mul_f32_e32 v250, v250, v166
	v_fma_f32 v251, v251, v165, v247
	v_mul_f32_e32 v250, v250, v165
	v_fma_f32 v251, v251, v164, v246
	v_mul_f32_e32 v250, v250, v164
	s_mov_b64 exec, s[10:11]
	ds_write_b64 v182, v[250:251] offset:1024
	s_mov_b64 exec, -1
	s_waitcnt lgkmcnt(0)
	s_barrier
	ds_read2_b64 v[4:7], v183 offset0:128 offset1:144
	s_add_i32 s52, s4, 1
	s_sub_i32 s52, 31, s52
	s_lshl_b32 s52, s52, 12
	v_add_u32_e32 v197, s52, v184
	s_waitcnt lgkmcnt(0)
	v_fma_f32 v198, v180, v6, v7
	v_cndmask_b32_e64 v199, v180, v198, s[24:25]
	v_fma_f32 v180, v198, v4, v5
	v_fma_f32 v200, v199, v167, v249
	v_cndmask_b32_e64 v199, v199, v200, s[16:17]
	v_fma_f32 v200, v199, v166, v248
	v_cndmask_b32_e64 v199, v199, v200, s[20:21]
	v_fma_f32 v200, v199, v165, v247
	v_cndmask_b32_e64 v199, v199, v200, s[22:23]
	v_fma_f32 v221, v127, v199, v177
	v_fma_f32 v220, v126, v221, v176
	v_fma_f32 v219, v125, v220, v175
	v_fma_f32 v218, v124, v219, v174
	v_fma_f32 v217, v123, v218, v173
	v_fma_f32 v216, v122, v217, v172
	v_fma_f32 v215, v121, v216, v171
	v_fma_f32 v214, v120, v215, v170
	ds_read_u16 v206, v197 offset:0
	ds_read_u16 v207, v197 offset:64
	ds_read_u16 v208, v197 offset:128
	ds_read_u16 v209, v197 offset:192
	ds_read_u16 v210, v197 offset:256
	ds_read_u16 v211, v197 offset:320
	ds_read_u16 v212, v197 offset:384
	ds_read_u16 v213, v197 offset:448
	s_waitcnt lgkmcnt(0)
	v_lshlrev_b32_e32 v206, 16, v206
	v_lshlrev_b32_e32 v207, 16, v207
	v_lshlrev_b32_e32 v208, 16, v208
	v_lshlrev_b32_e32 v209, 16, v209
	v_lshlrev_b32_e32 v210, 16, v210
	v_lshlrev_b32_e32 v211, 16, v211
	v_lshlrev_b32_e32 v212, 16, v212
	v_lshlrev_b32_e32 v213, 16, v213
	v_add_f32_e32 v214, v214, v206
	v_add_f32_e32 v215, v215, v207
	v_add_f32_e32 v216, v216, v208
	v_add_f32_e32 v217, v217, v209
	v_add_f32_e32 v218, v218, v210
	v_add_f32_e32 v219, v219, v211
	v_add_f32_e32 v220, v220, v212
	v_add_f32_e32 v221, v221, v213
	v_cvt_pk_bf16_f32 v206, v214, v215
	v_cvt_pk_bf16_f32 v208, v216, v217
	v_cvt_pk_bf16_f32 v210, v218, v219
	v_cvt_pk_bf16_f32 v212, v220, v221
	ds_write_b16 v197, v206 offset:0
	ds_write_b16_d16_hi v197, v206 offset:64
	ds_write_b16 v197, v208 offset:128
	ds_write_b16_d16_hi v197, v208 offset:192
	ds_write_b16 v197, v210 offset:256
	ds_write_b16_d16_hi v197, v210 offset:320
	ds_write_b16 v197, v212 offset:384
	ds_write_b16_d16_hi v197, v212 offset:448
	s_add_i32 s4, s4, 2
	s_cmp_lt_u32 s4, 32
	s_cbranch_scc1 .Lrec2_loopB_d1
	s_waitcnt lgkmcnt(0)
	s_barrier
	s_add_i32 s64, s4, -1
	s_sub_i32 s64, 31, s64
	s_mul_i32 s71, s64, 0x30000
	s_add_u32 s38, s60, s71
	s_addc_u32 s39, s61, 0
	s_lshl_b32 s64, s64, 12
	v_add_u32_e32 v136, s64, v195
	ds_read_b128 v[116:119], v136
	s_waitcnt vmcnt(3)
	s_waitcnt lgkmcnt(0)
	v_lshlrev_b32_e32 v136, 16, v116
	v_lshlrev_b32_e32 v137, 16, v8
	v_and_b32_e32 v168, 0xffff0000, v116
	v_and_b32_e32 v169, 0xffff0000, v8
	v_mul_f32_e32 v136, v136, v137
	v_mul_f32_e32 v168, v168, v169
	v_cvt_pk_bf16_f32 v116, v136, v168
	v_lshlrev_b32_e32 v136, 16, v117
	v_lshlrev_b32_e32 v137, 16, v9
	v_and_b32_e32 v168, 0xffff0000, v117
	v_and_b32_e32 v169, 0xffff0000, v9
	v_mul_f32_e32 v136, v136, v137
	v_mul_f32_e32 v168, v168, v169
	v_cvt_pk_bf16_f32 v117, v136, v168
	v_lshlrev_b32_e32 v136, 16, v118
	v_lshlrev_b32_e32 v137, 16, v10
	v_and_b32_e32 v168, 0xffff0000, v118
	v_and_b32_e32 v169, 0xffff0000, v10
	v_mul_f32_e32 v136, v136, v137
	v_mul_f32_e32 v168, v168, v169
	v_cvt_pk_bf16_f32 v118, v136, v168
	v_lshlrev_b32_e32 v136, 16, v119
	v_lshlrev_b32_e32 v137, 16, v11
	v_and_b32_e32 v168, 0xffff0000, v119
	v_and_b32_e32 v169, 0xffff0000, v11
	v_mul_f32_e32 v136, v136, v137
	v_mul_f32_e32 v168, v168, v169
	v_cvt_pk_bf16_f32 v119, v136, v168
	global_store_dwordx4 v255, v[116:119], s[38:39]
.Lrec2_done:
	s_waitcnt lgkmcnt(0)
	s_barrier
	s_add_i32 s84, s84, s33
	s_cmpk_gt_i32 s84, 0xff
	s_cbranch_scc0 .LBB0_598
